# write-through (sc1) dwordx4 stores in GEMM epilogues, weight conversion and conv so the grid barrier has less dirty L2 to write back
# speedup vs baseline: 1.0136x; 1.0003x over previous
; __device__ __forceinline__ unsigned cvt_pk_bf16(float lo, float hi) { unsigned r; asm volatile("v_cvt_pk_bf16_f32 %0, %1, %2" : "=v"(r) : "v"(lo), "v"(hi)); return r; }
;     __device__ __forceinline__ void operator()(const f32x4 (&acc)[2][2][4][2], const Unit& u, int wr, int wc, int fr, int fq) const {
;     ...
;             for (int m = 0; m < 4; ++m) { const size_t row = (size_t)(row0 + ai * HALF + m * 16); float ss = 0.f;
; #pragma unroll
;                 for (int bj = 0; bj < 2; ++bj) { const int col = col0 + bj * HALF;
;                     const f32x4 v0 = acc[ai][bj][m][0], v1 = acc[ai][bj][m][1];
;                     ss += (v0[0] * v0[0] + v0[1] * v0[1]) + (v0[2] * v0[2] + v0[3] * v0[3]) + (v1[0] * v1[0] + v1[1] * v1[1]) + (v1[2] * v1[2] + v1[3] * v1[3]);
;                     u32x4 w; w.x = cvt_pk_bf16(v0[0], v0[1]); w.y = cvt_pk_bf16(v0[2], v0[3]); w.z = cvt_pk_bf16(v1[0], v1[1]); w.w = cvt_pk_bf16(v1[2], v1[3]);
;                     *(u32x4*)(O + row * 2048 + col) = w; }
;                 ss += __shfl_xor(ss, 16); ss += __shfl_xor(ss, 32);
;                 if (fq == 0) rowss[row * 32 + u.pn * 4 + wc] = ss; }
.LBB0_41:
	v_mul_f32_e32 v144, v127, v127
	v_mul_f32_e32 v145, v129, v129
	v_fmac_f32_e32 v144, v126, v126
	v_fmac_f32_e32 v145, v128, v128
	v_add_f32_e32 v144, v144, v145
	v_mul_f32_e32 v145, v123, v123
	v_fmac_f32_e32 v145, v122, v122
	v_cvt_pk_bf16_f32 v126, v126, v127
	v_cvt_pk_bf16_f32 v127, v128, v129
	v_cvt_pk_bf16_f32 v128, v122, v123
	v_mul_f32_e32 v122, v119, v119
	v_mul_f32_e32 v123, v121, v121
	v_fmac_f32_e32 v122, v118, v118
	v_fmac_f32_e32 v123, v120, v120
	v_add_f32_e32 v122, v122, v123
	v_mul_f32_e32 v123, v115, v115
	v_fmac_f32_e32 v123, v114, v114
	v_add_f32_e32 v144, v144, v145
	v_mul_f32_e32 v145, v125, v125
	v_add_f32_e32 v122, v122, v123
	v_mul_f32_e32 v123, v117, v117
	v_fmac_f32_e32 v145, v124, v124
	v_fmac_f32_e32 v123, v116, v116
	v_add_f32_e32 v144, v145, v144
	v_add_f32_e32 v122, v123, v122
	v_cmp_lt_i32_e32 vcc, v178, v173
	v_add_f32_e32 v123, v144, v122
	v_lshl_add_u32 v154, s78, 8, v138
	v_cndmask_b32_e32 v122, v172, v178, vcc
	v_lshlrev_b32_e32 v122, 2, v122
	v_ashrrev_i32_e32 v155, 31, v154
	ds_bpermute_b32 v144, v122, v123
	v_lshl_or_b32 v152, s77, 8, v157
	v_lshlrev_b64 v[142:143], 12, v[154:155]
	v_cvt_pk_bf16_f32 v129, v124, v125
	v_lshl_add_u64 v[124:125], s[42:43], 0, v[142:143]
	v_ashrrev_i32_e32 v153, 31, v152
	v_lshl_add_u64 v[142:143], v[152:153], 1, v[124:125]
	v_cmp_lt_i32_e32 vcc, v179, v173
	flat_store_dwordx4 v[142:143], v[126:129] sc1
	v_cvt_pk_bf16_f32 v124, v118, v119
	s_waitcnt lgkmcnt(0)
	v_add_f32_e32 v119, v123, v144
	v_cndmask_b32_e32 v118, v172, v179, vcc
	v_lshlrev_b32_e32 v118, 2, v118
	ds_bpermute_b32 v123, v118, v119
	s_lshl_b32 s60, s77, 2
	s_ashr_i32 s61, s60, 31
	v_cvt_pk_bf16_f32 v125, v120, v121
	v_cvt_pk_bf16_f32 v126, v114, v115
	v_cvt_pk_bf16_f32 v127, v116, v117
	flat_store_dwordx4 v[142:143], v[124:127] offset:256 sc1
	s_and_saveexec_b64 s[2:3], s[38:39]
	s_mov_b32 s65, s95
	s_cbranch_execz .LBB0_43
	v_lshlrev_b64 v[114:115], 7, v[154:155]
	v_lshl_add_u64 v[114:115], s[44:45], 0, v[114:115]
	v_lshl_add_u64 v[114:115], s[60:61], 2, v[114:115]
	s_lshl_b32 s64, s73, 2
	s_waitcnt lgkmcnt(0)
	v_add_f32_e32 v116, v119, v123
	v_lshl_add_u64 v[114:115], v[114:115], 0, s[64:65]
	flat_store_dword v[114:115], v116
.LBB0_43:
	s_or_b64 exec, exec, s[2:3]
	v_mul_f32_e32 v119, v111, v111
	v_mul_f32_e32 v120, v113, v113
	v_fmac_f32_e32 v119, v110, v110
	v_fmac_f32_e32 v120, v112, v112
	v_add_f32_e32 v119, v119, v120
	v_mul_f32_e32 v120, v107, v107
	v_fmac_f32_e32 v120, v106, v106
	v_cvt_pk_bf16_f32 v110, v110, v111
	v_cvt_pk_bf16_f32 v111, v112, v113
	v_cvt_pk_bf16_f32 v112, v106, v107
	v_mul_f32_e32 v106, v103, v103
	v_mul_f32_e32 v107, v105, v105
	v_fmac_f32_e32 v106, v102, v102
	v_fmac_f32_e32 v107, v104, v104
	v_add_f32_e32 v106, v106, v107
	v_mul_f32_e32 v107, v99, v99
	v_fmac_f32_e32 v107, v98, v98
	v_add_f32_e32 v119, v119, v120
	v_mul_f32_e32 v120, v109, v109
	v_add_f32_e32 v106, v106, v107
	v_mul_f32_e32 v107, v101, v101
	v_fmac_f32_e32 v120, v108, v108
	v_fmac_f32_e32 v107, v100, v100
	v_add_f32_e32 v119, v120, v119
	v_add_f32_e32 v106, v107, v106
	v_cvt_pk_bf16_f32 v113, v108, v109
	v_add_f32_e32 v108, v119, v106
	v_or_b32_e32 v114, 16, v154
	ds_bpermute_b32 v109, v122, v108
	v_ashrrev_i32_e32 v115, 31, v114
	v_lshlrev_b64 v[116:117], 12, v[114:115]
	v_lshl_add_u64 v[106:107], s[42:43], 0, v[116:117]
	v_lshl_add_u64 v[116:117], v[152:153], 1, v[106:107]
	flat_store_dwordx4 v[116:117], v[110:113] sc1
	v_cvt_pk_bf16_f32 v106, v102, v103
	s_waitcnt lgkmcnt(0)
	v_add_f32_e32 v102, v108, v109
	ds_bpermute_b32 v103, v118, v102
	v_cvt_pk_bf16_f32 v107, v104, v105
	v_cvt_pk_bf16_f32 v108, v98, v99
	v_cvt_pk_bf16_f32 v109, v100, v101
	flat_store_dwordx4 v[116:117], v[106:109] offset:256 sc1
	s_and_saveexec_b64 s[2:3], s[38:39]
	s_cbranch_execz .LBB0_45
	v_lshlrev_b64 v[98:99], 7, v[114:115]
	v_lshl_add_u64 v[98:99], s[44:45], 0, v[98:99]
	v_lshl_add_u64 v[98:99], s[60:61], 2, v[98:99]
	s_lshl_b32 s64, s73, 2
	s_waitcnt lgkmcnt(0)
	v_add_f32_e32 v100, v102, v103
	v_lshl_add_u64 v[98:99], v[98:99], 0, s[64:65]
	flat_store_dword v[98:99], v100
.LBB0_45:
	s_or_b64 exec, exec, s[2:3]
	v_mul_f32_e32 v102, v95, v95
	s_waitcnt lgkmcnt(0)
	v_mul_f32_e32 v103, v97, v97
	v_fmac_f32_e32 v102, v94, v94
	v_fmac_f32_e32 v103, v96, v96
	v_add_f32_e32 v102, v102, v103
	v_mul_f32_e32 v103, v91, v91
	v_fmac_f32_e32 v103, v90, v90
	v_cvt_pk_bf16_f32 v94, v94, v95
	v_cvt_pk_bf16_f32 v95, v96, v97
	v_cvt_pk_bf16_f32 v96, v90, v91
	v_mul_f32_e32 v90, v87, v87
	v_mul_f32_e32 v91, v89, v89
	v_fmac_f32_e32 v90, v86, v86
	v_fmac_f32_e32 v91, v88, v88
	v_add_f32_e32 v90, v90, v91
	v_mul_f32_e32 v91, v83, v83
	v_fmac_f32_e32 v91, v82, v82
	v_add_f32_e32 v102, v102, v103
	v_mul_f32_e32 v103, v93, v93
	v_add_f32_e32 v90, v90, v91
	v_mul_f32_e32 v91, v85, v85
	v_fmac_f32_e32 v103, v92, v92
	v_fmac_f32_e32 v91, v84, v84
	v_add_f32_e32 v102, v103, v102
	v_add_f32_e32 v90, v91, v90
	v_cvt_pk_bf16_f32 v97, v92, v93
	v_add_f32_e32 v92, v102, v90
	v_or_b32_e32 v98, 32, v154
	ds_bpermute_b32 v93, v122, v92
	v_ashrrev_i32_e32 v99, 31, v98
	v_lshlrev_b64 v[100:101], 12, v[98:99]
	v_lshl_add_u64 v[90:91], s[42:43], 0, v[100:101]
	v_lshl_add_u64 v[100:101], v[152:153], 1, v[90:91]
	flat_store_dwordx4 v[100:101], v[94:97] sc1
	v_cvt_pk_bf16_f32 v90, v86, v87
	s_waitcnt lgkmcnt(0)
	v_add_f32_e32 v86, v92, v93
	ds_bpermute_b32 v87, v118, v86
	v_cvt_pk_bf16_f32 v91, v88, v89
	v_cvt_pk_bf16_f32 v92, v82, v83
	v_cvt_pk_bf16_f32 v93, v84, v85
	flat_store_dwordx4 v[100:101], v[90:93] offset:256 sc1
	s_and_saveexec_b64 s[2:3], s[38:39]
	v_readlane_b32 s88, v253, 46
	s_cbranch_execz .LBB0_47
	v_lshlrev_b64 v[82:83], 7, v[98:99]
	v_lshl_add_u64 v[82:83], s[44:45], 0, v[82:83]
	v_lshl_add_u64 v[82:83], s[60:61], 2, v[82:83]
	s_lshl_b32 s64, s73, 2
	s_waitcnt lgkmcnt(0)
	v_add_f32_e32 v84, v86, v87
	v_lshl_add_u64 v[82:83], v[82:83], 0, s[64:65]
	flat_store_dword v[82:83], v84
; __device__ __forceinline__ unsigned cvt_pk_bf16(float lo, float hi) { unsigned r; asm volatile("v_cvt_pk_bf16_f32 %0, %1, %2" : "=v"(r) : "v"(lo), "v"(hi)); return r; }
;     __device__ __forceinline__ void operator()(const f32x4 (&acc)[2][2][4][2], const Unit& u, int wr, int wc, int fr, int fq) const {
;     ...
;             for (int m = 0; m < 4; ++m) { const size_t row = (size_t)(row0 + ai * HALF + m * 16); float ss = 0.f;
; #pragma unroll
;                 for (int bj = 0; bj < 2; ++bj) { const int col = col0 + bj * HALF;
;                     const f32x4 v0 = acc[ai][bj][m][0], v1 = acc[ai][bj][m][1];
;                     ss += (v0[0] * v0[0] + v0[1] * v0[1]) + (v0[2] * v0[2] + v0[3] * v0[3]) + (v1[0] * v1[0] + v1[1] * v1[1]) + (v1[2] * v1[2] + v1[3] * v1[3]);
;                     u32x4 w; w.x = cvt_pk_bf16(v0[0], v0[1]); w.y = cvt_pk_bf16(v0[2], v0[3]); w.z = cvt_pk_bf16(v1[0], v1[1]); w.w = cvt_pk_bf16(v1[2], v1[3]);
;                     *(u32x4*)(O + row * 2048 + col) = w; }
;                 ss += __shfl_xor(ss, 16); ss += __shfl_xor(ss, 32);
;                 if (fq == 0) rowss[row * 32 + u.pn * 4 + wc] = ss; }
.LBB0_47:
	s_or_b64 exec, exec, s[2:3]
	v_mul_f32_e32 v86, v79, v79
	s_waitcnt lgkmcnt(0)
	v_mul_f32_e32 v87, v81, v81
	v_fmac_f32_e32 v86, v78, v78
	v_fmac_f32_e32 v87, v80, v80
	v_add_f32_e32 v86, v86, v87
	v_mul_f32_e32 v87, v75, v75
	v_fmac_f32_e32 v87, v74, v74
	v_cvt_pk_bf16_f32 v78, v78, v79
	v_cvt_pk_bf16_f32 v79, v80, v81
	v_cvt_pk_bf16_f32 v80, v74, v75
	v_mul_f32_e32 v74, v71, v71
	v_mul_f32_e32 v75, v73, v73
	v_fmac_f32_e32 v74, v70, v70
	v_fmac_f32_e32 v75, v72, v72
	v_add_f32_e32 v74, v74, v75
	v_mul_f32_e32 v75, v67, v67
	v_fmac_f32_e32 v75, v66, v66
	v_add_f32_e32 v86, v86, v87
	v_mul_f32_e32 v87, v77, v77
	v_add_f32_e32 v74, v74, v75
	v_mul_f32_e32 v75, v69, v69
	v_fmac_f32_e32 v87, v76, v76
	v_fmac_f32_e32 v75, v68, v68
	v_add_f32_e32 v86, v87, v86
	v_add_f32_e32 v74, v75, v74
	v_cvt_pk_bf16_f32 v81, v76, v77
	v_add_f32_e32 v76, v86, v74
	v_or_b32_e32 v82, 48, v154
	ds_bpermute_b32 v77, v122, v76
	v_ashrrev_i32_e32 v83, 31, v82
	v_lshlrev_b64 v[84:85], 12, v[82:83]
	v_lshl_add_u64 v[74:75], s[42:43], 0, v[84:85]
	v_lshl_add_u64 v[84:85], v[152:153], 1, v[74:75]
	flat_store_dwordx4 v[84:85], v[78:81] sc1
	v_cvt_pk_bf16_f32 v74, v70, v71
	s_waitcnt lgkmcnt(0)
	v_add_f32_e32 v70, v76, v77
	ds_bpermute_b32 v71, v118, v70
	v_cvt_pk_bf16_f32 v75, v72, v73
	v_cvt_pk_bf16_f32 v76, v66, v67
	v_cvt_pk_bf16_f32 v77, v68, v69
	flat_store_dwordx4 v[84:85], v[74:77] offset:256 sc1
	s_and_saveexec_b64 s[2:3], s[38:39]
	s_cbranch_execz .LBB0_49
	v_lshlrev_b64 v[66:67], 7, v[82:83]
	v_lshl_add_u64 v[66:67], s[44:45], 0, v[66:67]
	v_lshl_add_u64 v[66:67], s[60:61], 2, v[66:67]
	s_lshl_b32 s64, s73, 2
	s_waitcnt lgkmcnt(0)
	v_add_f32_e32 v68, v70, v71
	v_lshl_add_u64 v[66:67], v[66:67], 0, s[64:65]
	flat_store_dword v[66:67], v68
.LBB0_49:
	s_or_b64 exec, exec, s[2:3]
	v_mul_f32_e32 v70, v63, v63
	s_waitcnt lgkmcnt(0)
	v_mul_f32_e32 v71, v65, v65
	v_fmac_f32_e32 v70, v62, v62
	v_fmac_f32_e32 v71, v64, v64
	v_add_f32_e32 v70, v70, v71
	v_mul_f32_e32 v71, v59, v59
	v_fmac_f32_e32 v71, v58, v58
	v_cvt_pk_bf16_f32 v62, v62, v63
	v_cvt_pk_bf16_f32 v63, v64, v65
	v_cvt_pk_bf16_f32 v64, v58, v59
	v_mul_f32_e32 v58, v55, v55
	v_mul_f32_e32 v59, v57, v57
	v_fmac_f32_e32 v58, v54, v54
	v_fmac_f32_e32 v59, v56, v56
	v_add_f32_e32 v58, v58, v59
	v_mul_f32_e32 v59, v51, v51
	v_fmac_f32_e32 v59, v50, v50
	v_add_f32_e32 v70, v70, v71
	v_mul_f32_e32 v71, v61, v61
	v_add_f32_e32 v58, v58, v59
	v_mul_f32_e32 v59, v53, v53
	v_fmac_f32_e32 v71, v60, v60
	v_fmac_f32_e32 v59, v52, v52
	v_add_f32_e32 v70, v71, v70
	v_add_f32_e32 v58, v59, v58
	v_cvt_pk_bf16_f32 v65, v60, v61
	v_add_f32_e32 v60, v70, v58
	v_add_u32_e32 v66, 0x80, v154
	ds_bpermute_b32 v61, v122, v60
	v_ashrrev_i32_e32 v67, 31, v66
	v_lshlrev_b64 v[68:69], 12, v[66:67]
	v_lshl_add_u64 v[58:59], s[42:43], 0, v[68:69]
	v_lshl_add_u64 v[68:69], v[152:153], 1, v[58:59]
	flat_store_dwordx4 v[68:69], v[62:65] sc1
	v_cvt_pk_bf16_f32 v58, v54, v55
	s_waitcnt lgkmcnt(0)
	v_add_f32_e32 v54, v60, v61
	ds_bpermute_b32 v55, v118, v54
	v_cvt_pk_bf16_f32 v59, v56, v57
	v_cvt_pk_bf16_f32 v60, v50, v51
	v_cvt_pk_bf16_f32 v61, v52, v53
	flat_store_dwordx4 v[68:69], v[58:61] offset:256 sc1
	s_and_saveexec_b64 s[2:3], s[38:39]
	s_cbranch_execz .LBB0_51
	v_lshlrev_b64 v[50:51], 7, v[66:67]
	v_lshl_add_u64 v[50:51], s[44:45], 0, v[50:51]
	v_lshl_add_u64 v[50:51], s[60:61], 2, v[50:51]
	s_lshl_b32 s64, s73, 2
	s_waitcnt lgkmcnt(0)
	v_add_f32_e32 v52, v54, v55
	v_lshl_add_u64 v[50:51], v[50:51], 0, s[64:65]
	flat_store_dword v[50:51], v52
; __device__ __forceinline__ unsigned cvt_pk_bf16(float lo, float hi) { unsigned r; asm volatile("v_cvt_pk_bf16_f32 %0, %1, %2" : "=v"(r) : "v"(lo), "v"(hi)); return r; }
;     __device__ __forceinline__ void operator()(const f32x4 (&acc)[2][2][4][2], const Unit& u, int wr, int wc, int fr, int fq) const {
;     ...
;             for (int m = 0; m < 4; ++m) { const size_t row = (size_t)(row0 + ai * HALF + m * 16); float ss = 0.f;
; #pragma unroll
;                 for (int bj = 0; bj < 2; ++bj) { const int col = col0 + bj * HALF;
;                     const f32x4 v0 = acc[ai][bj][m][0], v1 = acc[ai][bj][m][1];
;                     ss += (v0[0] * v0[0] + v0[1] * v0[1]) + (v0[2] * v0[2] + v0[3] * v0[3]) + (v1[0] * v1[0] + v1[1] * v1[1]) + (v1[2] * v1[2] + v1[3] * v1[3]);
;                     u32x4 w; w.x = cvt_pk_bf16(v0[0], v0[1]); w.y = cvt_pk_bf16(v0[2], v0[3]); w.z = cvt_pk_bf16(v1[0], v1[1]); w.w = cvt_pk_bf16(v1[2], v1[3]);
;                     *(u32x4*)(O + row * 2048 + col) = w; }
;                 ss += __shfl_xor(ss, 16); ss += __shfl_xor(ss, 32);
;                 if (fq == 0) rowss[row * 32 + u.pn * 4 + wc] = ss; }
.LBB0_51:
	s_or_b64 exec, exec, s[2:3]
	v_mul_f32_e32 v54, v47, v47
	s_waitcnt lgkmcnt(0)
	v_mul_f32_e32 v55, v49, v49
	v_fmac_f32_e32 v54, v46, v46
	v_fmac_f32_e32 v55, v48, v48
	v_add_f32_e32 v54, v54, v55
	v_mul_f32_e32 v55, v43, v43
	v_fmac_f32_e32 v55, v42, v42
	v_cvt_pk_bf16_f32 v46, v46, v47
	v_cvt_pk_bf16_f32 v47, v48, v49
	v_cvt_pk_bf16_f32 v48, v42, v43
	v_mul_f32_e32 v42, v39, v39
	v_mul_f32_e32 v43, v41, v41
	v_fmac_f32_e32 v42, v38, v38
	v_fmac_f32_e32 v43, v40, v40
	v_add_f32_e32 v42, v42, v43
	v_mul_f32_e32 v43, v35, v35
	v_fmac_f32_e32 v43, v34, v34
	v_add_f32_e32 v54, v54, v55
	v_mul_f32_e32 v55, v45, v45
	v_add_f32_e32 v42, v42, v43
	v_mul_f32_e32 v43, v37, v37
	v_fmac_f32_e32 v55, v44, v44
	v_fmac_f32_e32 v43, v36, v36
	v_add_f32_e32 v54, v55, v54
	v_add_f32_e32 v42, v43, v42
	v_cvt_pk_bf16_f32 v49, v44, v45
	v_add_f32_e32 v44, v54, v42
	v_add_u32_e32 v50, 0x90, v154
	ds_bpermute_b32 v45, v122, v44
	v_ashrrev_i32_e32 v51, 31, v50
	v_lshlrev_b64 v[52:53], 12, v[50:51]
	v_lshl_add_u64 v[42:43], s[42:43], 0, v[52:53]
	v_lshl_add_u64 v[52:53], v[152:153], 1, v[42:43]
	flat_store_dwordx4 v[52:53], v[46:49] sc1
	v_cvt_pk_bf16_f32 v42, v38, v39
	s_waitcnt lgkmcnt(0)
	v_add_f32_e32 v38, v44, v45
	ds_bpermute_b32 v39, v118, v38
	v_cvt_pk_bf16_f32 v43, v40, v41
	v_cvt_pk_bf16_f32 v44, v34, v35
	v_cvt_pk_bf16_f32 v45, v36, v37
	flat_store_dwordx4 v[52:53], v[42:45] offset:256 sc1
	s_and_saveexec_b64 s[2:3], s[38:39]
	s_cbranch_execz .LBB0_53
	v_lshlrev_b64 v[34:35], 7, v[50:51]
	v_lshl_add_u64 v[34:35], s[44:45], 0, v[34:35]
	v_lshl_add_u64 v[34:35], s[60:61], 2, v[34:35]
	s_lshl_b32 s64, s73, 2
	s_waitcnt lgkmcnt(0)
	v_add_f32_e32 v36, v38, v39
	v_lshl_add_u64 v[34:35], v[34:35], 0, s[64:65]
	flat_store_dword v[34:35], v36
.LBB0_53:
	s_or_b64 exec, exec, s[2:3]
	v_mul_f32_e32 v38, v31, v31
	s_waitcnt lgkmcnt(0)
	v_mul_f32_e32 v39, v33, v33
	v_fmac_f32_e32 v38, v30, v30
	v_fmac_f32_e32 v39, v32, v32
	v_add_f32_e32 v38, v38, v39
	v_mul_f32_e32 v39, v27, v27
	v_fmac_f32_e32 v39, v26, v26
	v_cvt_pk_bf16_f32 v30, v30, v31
	v_cvt_pk_bf16_f32 v31, v32, v33
	v_cvt_pk_bf16_f32 v32, v26, v27
	v_mul_f32_e32 v26, v23, v23
	v_mul_f32_e32 v27, v25, v25
	v_fmac_f32_e32 v26, v22, v22
	v_fmac_f32_e32 v27, v24, v24
	v_add_f32_e32 v26, v26, v27
	v_mul_f32_e32 v27, v19, v19
	v_fmac_f32_e32 v27, v18, v18
	v_add_f32_e32 v38, v38, v39
	v_mul_f32_e32 v39, v29, v29
	v_add_f32_e32 v26, v26, v27
	v_mul_f32_e32 v27, v21, v21
	v_fmac_f32_e32 v39, v28, v28
	v_fmac_f32_e32 v27, v20, v20
	v_add_f32_e32 v38, v39, v38
	v_add_f32_e32 v26, v27, v26
	v_cvt_pk_bf16_f32 v33, v28, v29
	v_add_f32_e32 v28, v38, v26
	v_add_u32_e32 v34, 0xa0, v154
	ds_bpermute_b32 v29, v122, v28
	v_ashrrev_i32_e32 v35, 31, v34
	v_lshlrev_b64 v[36:37], 12, v[34:35]
	v_lshl_add_u64 v[26:27], s[42:43], 0, v[36:37]
	v_lshl_add_u64 v[36:37], v[152:153], 1, v[26:27]
	flat_store_dwordx4 v[36:37], v[30:33] sc1
	v_cvt_pk_bf16_f32 v26, v22, v23
	s_waitcnt lgkmcnt(0)
	v_add_f32_e32 v22, v28, v29
	ds_bpermute_b32 v23, v118, v22
	v_cvt_pk_bf16_f32 v27, v24, v25
	v_cvt_pk_bf16_f32 v28, v18, v19
	v_cvt_pk_bf16_f32 v29, v20, v21
	flat_store_dwordx4 v[36:37], v[26:29] offset:256 sc1
	s_and_saveexec_b64 s[2:3], s[38:39]
	s_cbranch_execz .LBB0_55
	v_lshlrev_b64 v[18:19], 7, v[34:35]
	v_lshl_add_u64 v[18:19], s[44:45], 0, v[18:19]
	v_lshl_add_u64 v[18:19], s[60:61], 2, v[18:19]
	s_lshl_b32 s64, s73, 2
	s_waitcnt lgkmcnt(0)
	v_add_f32_e32 v20, v22, v23
	v_lshl_add_u64 v[18:19], v[18:19], 0, s[64:65]
	flat_store_dword v[18:19], v20
.LBB0_55:
	s_or_b64 exec, exec, s[2:3]
	v_mul_f32_e32 v22, v15, v15
	s_waitcnt lgkmcnt(0)
	v_mul_f32_e32 v23, v17, v17
	v_fmac_f32_e32 v22, v14, v14
	v_fmac_f32_e32 v23, v16, v16
	v_add_f32_e32 v22, v22, v23
	v_mul_f32_e32 v23, v11, v11
	v_fmac_f32_e32 v23, v10, v10
	v_cvt_pk_bf16_f32 v14, v14, v15
	v_cvt_pk_bf16_f32 v15, v16, v17
	v_cvt_pk_bf16_f32 v16, v10, v11
	v_mul_f32_e32 v10, v7, v7
	v_mul_f32_e32 v11, v9, v9
	v_fmac_f32_e32 v10, v6, v6
	v_fmac_f32_e32 v11, v8, v8
	v_add_f32_e32 v10, v10, v11
	v_mul_f32_e32 v11, v3, v3
	v_fmac_f32_e32 v11, v2, v2
	v_add_f32_e32 v22, v22, v23
	v_mul_f32_e32 v23, v13, v13
	v_add_f32_e32 v10, v10, v11
	v_mul_f32_e32 v11, v5, v5
	v_fmac_f32_e32 v23, v12, v12
	v_fmac_f32_e32 v11, v4, v4
	v_add_f32_e32 v22, v23, v22
	v_add_f32_e32 v10, v11, v10
	v_cvt_pk_bf16_f32 v17, v12, v13
	v_add_f32_e32 v12, v22, v10
	v_add_u32_e32 v18, 0xb0, v154
	ds_bpermute_b32 v13, v122, v12
	v_ashrrev_i32_e32 v19, 31, v18
	v_lshlrev_b64 v[20:21], 12, v[18:19]
	v_lshl_add_u64 v[10:11], s[42:43], 0, v[20:21]
	v_lshl_add_u64 v[20:21], v[152:153], 1, v[10:11]
	flat_store_dwordx4 v[20:21], v[14:17] sc1
	v_cvt_pk_bf16_f32 v10, v6, v7
	s_waitcnt lgkmcnt(0)
	v_add_f32_e32 v6, v12, v13
	ds_bpermute_b32 v7, v118, v6
	v_cvt_pk_bf16_f32 v11, v8, v9
	v_cvt_pk_bf16_f32 v12, v2, v3
	v_cvt_pk_bf16_f32 v13, v4, v5
	flat_store_dwordx4 v[20:21], v[10:13] offset:256 sc1
	s_and_saveexec_b64 s[2:3], s[38:39]
	s_cbranch_execz .LBB0_57
	v_lshlrev_b64 v[2:3], 7, v[18:19]
	v_lshl_add_u64 v[2:3], s[44:45], 0, v[2:3]
	v_lshl_add_u64 v[2:3], s[60:61], 2, v[2:3]
	s_lshl_b32 s64, s73, 2
	s_waitcnt lgkmcnt(0)
	v_add_f32_e32 v4, v6, v7
	v_lshl_add_u64 v[2:3], v[2:3], 0, s[64:65]
	flat_store_dword v[2:3], v4

; __device__ __forceinline__ unsigned cvt_pk_bf16(float lo, float hi) { unsigned r; asm volatile("v_cvt_pk_bf16_f32 %0, %1, %2" : "=v"(r) : "v"(lo), "v"(hi)); return r; }
; __device__ __forceinline__ float bflo(unsigned w) { return __uint_as_float(w << 16); }
; __device__ __forceinline__ float bfhi(unsigned w) { return __uint_as_float(w & 0xffff0000u); }
;     __device__ __forceinline__ void operator()(const f32x4 (&acc)[2][2][4][2], const Unit& u, int wr, int wc, int fr, int fq) const {
;     ...
;             for (int m = 0; m < 4; ++m) { const size_t row = (size_t)(row0 + ai * HALF + m * 16);
; #pragma unroll
;                 for (int bj = 0; bj < 2; ++bj) { const int col = col0 + bj * HALF;
;                     const u32x4 g = *(const u32x4*)(P + row * LDP + PC_GB + col);
;                     f32x4 v0 = acc[ai][bj][m][0], v1 = acc[ai][bj][m][1];
;                     v0[0] *= bflo(g.x); v0[1] *= bfhi(g.x); v0[2] *= bflo(g.y); v0[3] *= bfhi(g.y);
;                     v1[0] *= bflo(g.z); v1[1] *= bfhi(g.z); v1[2] *= bflo(g.w); v1[3] *= bfhi(g.w);
;                     u32x4 w; w.x = cvt_pk_bf16(v0[0], v0[1]); w.y = cvt_pk_bf16(v0[2], v0[3]); w.z = cvt_pk_bf16(v1[0], v1[1]); w.w = cvt_pk_bf16(v1[2], v1[3]);
;                     *(u32x4*)(O + row * 2048 + col) = w; }
.LBB0_82:
	v_mul_u32_u24_e32 v161, 0x6200, v160
	v_lshlrev_b32_e32 v163, 12, v160
	v_lshl_add_u32 v161, v162, 1, v161
	v_lshl_add_u32 v163, v162, 1, v163
	s_add_u32 s2, s40, 0x5200
	s_addc_u32 s3, s41, 0
	global_load_dwordx4 v[130:133], v161, s[2:3]
	s_add_u32 s2, s40, 0x5300
	s_addc_u32 s3, s41, 0
	global_load_dwordx4 v[134:137], v161, s[2:3]
	s_add_u32 s2, s40, 0x67200
	s_addc_u32 s3, s41, 0
	global_load_dwordx4 v[186:189], v161, s[2:3]
	s_add_u32 s2, s40, 0x67300
	s_addc_u32 s3, s41, 0
	global_load_dwordx4 v[190:193], v161, s[2:3]
	s_add_u32 s2, s40, 0xc9200
	s_addc_u32 s3, s41, 0
	global_load_dwordx4 v[194:197], v161, s[2:3]
	s_add_u32 s2, s40, 0xc9300
	s_addc_u32 s3, s41, 0
	global_load_dwordx4 v[198:201], v161, s[2:3]
	s_add_u32 s2, s40, 0x12b200
	s_addc_u32 s3, s41, 0
	global_load_dwordx4 v[202:205], v161, s[2:3]
	s_add_u32 s2, s40, 0x12b300
	s_addc_u32 s3, s41, 0
	global_load_dwordx4 v[206:209], v161, s[2:3]
	s_add_u32 s2, s40, 0x315200
	s_addc_u32 s3, s41, 0
	global_load_dwordx4 v[214:217], v161, s[2:3]
	s_add_u32 s2, s40, 0x315300
	s_addc_u32 s3, s41, 0
	global_load_dwordx4 v[218:221], v161, s[2:3]
	s_add_u32 s2, s40, 0x377200
	s_addc_u32 s3, s41, 0
	global_load_dwordx4 v[222:225], v161, s[2:3]
	s_add_u32 s2, s40, 0x377300
	s_addc_u32 s3, s41, 0
	global_load_dwordx4 v[226:229], v161, s[2:3]
	s_add_u32 s2, s40, 0x3d9200
	s_addc_u32 s3, s41, 0
	global_load_dwordx4 v[230:233], v161, s[2:3]
	s_add_u32 s2, s40, 0x3d9300
	s_addc_u32 s3, s41, 0
	global_load_dwordx4 v[234:237], v161, s[2:3]
	s_add_u32 s2, s40, 0x43b200
	s_addc_u32 s3, s41, 0
	global_load_dwordx4 v[238:241], v161, s[2:3]
	s_add_u32 s2, s40, 0x43b300
	s_addc_u32 s3, s41, 0
	global_load_dwordx4 v[242:245], v161, s[2:3]
	s_waitcnt vmcnt(15)
	v_lshlrev_b32_e32 v142, 16, v130
	v_and_b32_e32 v130, 0xffff0000, v130
	v_lshlrev_b32_e32 v143, 16, v131
	v_and_b32_e32 v131, 0xffff0000, v131
	v_lshlrev_b32_e32 v144, 16, v132
	v_and_b32_e32 v132, 0xffff0000, v132
	v_lshlrev_b32_e32 v145, 16, v133
	v_and_b32_e32 v133, 0xffff0000, v133
	v_mul_f32_e32 v126, v126, v142
	v_mul_f32_e32 v127, v127, v130
	v_mul_f32_e32 v128, v128, v143
	v_mul_f32_e32 v129, v129, v131
	v_mul_f32_e32 v122, v122, v144
	v_mul_f32_e32 v123, v123, v132
	v_mul_f32_e32 v124, v124, v145
	v_mul_f32_e32 v125, v125, v133
	v_cvt_pk_bf16_f32 v130, v126, v127
	v_cvt_pk_bf16_f32 v131, v128, v129
	v_cvt_pk_bf16_f32 v132, v122, v123
	v_cvt_pk_bf16_f32 v133, v124, v125
	s_waitcnt vmcnt(14)
	v_lshlrev_b32_e32 v142, 16, v134
	v_and_b32_e32 v134, 0xffff0000, v134
	v_lshlrev_b32_e32 v143, 16, v135
	v_and_b32_e32 v135, 0xffff0000, v135
	v_lshlrev_b32_e32 v144, 16, v136
	v_and_b32_e32 v136, 0xffff0000, v136
	v_lshlrev_b32_e32 v145, 16, v137
	v_and_b32_e32 v137, 0xffff0000, v137
	v_mul_f32_e32 v118, v118, v142
	v_mul_f32_e32 v119, v119, v134
	v_mul_f32_e32 v120, v120, v143
	v_mul_f32_e32 v121, v121, v135
	v_mul_f32_e32 v114, v114, v144
	v_mul_f32_e32 v115, v115, v136
	v_mul_f32_e32 v116, v116, v145
	v_mul_f32_e32 v117, v117, v137
	v_cvt_pk_bf16_f32 v134, v118, v119
	v_cvt_pk_bf16_f32 v135, v120, v121
	v_cvt_pk_bf16_f32 v136, v114, v115
	v_cvt_pk_bf16_f32 v137, v116, v117
	s_waitcnt vmcnt(13)
	v_lshlrev_b32_e32 v142, 16, v186
	v_and_b32_e32 v186, 0xffff0000, v186
	v_lshlrev_b32_e32 v143, 16, v187
	v_and_b32_e32 v187, 0xffff0000, v187
	v_lshlrev_b32_e32 v144, 16, v188
	v_and_b32_e32 v188, 0xffff0000, v188
	v_lshlrev_b32_e32 v145, 16, v189
	v_and_b32_e32 v189, 0xffff0000, v189
	v_mul_f32_e32 v110, v110, v142
	v_mul_f32_e32 v111, v111, v186
	v_mul_f32_e32 v112, v112, v143
	v_mul_f32_e32 v113, v113, v187
	v_mul_f32_e32 v106, v106, v144
	v_mul_f32_e32 v107, v107, v188
	v_mul_f32_e32 v108, v108, v145
	v_mul_f32_e32 v109, v109, v189
	v_cvt_pk_bf16_f32 v186, v110, v111
	v_cvt_pk_bf16_f32 v187, v112, v113
	v_cvt_pk_bf16_f32 v188, v106, v107
	v_cvt_pk_bf16_f32 v189, v108, v109
	s_waitcnt vmcnt(12)
	v_lshlrev_b32_e32 v142, 16, v190
	v_and_b32_e32 v190, 0xffff0000, v190
	v_lshlrev_b32_e32 v143, 16, v191
	v_and_b32_e32 v191, 0xffff0000, v191
	v_lshlrev_b32_e32 v144, 16, v192
	v_and_b32_e32 v192, 0xffff0000, v192
	v_lshlrev_b32_e32 v145, 16, v193
	v_and_b32_e32 v193, 0xffff0000, v193
	v_mul_f32_e32 v102, v102, v142
	v_mul_f32_e32 v103, v103, v190
	v_mul_f32_e32 v104, v104, v143
	v_mul_f32_e32 v105, v105, v191
	v_mul_f32_e32 v98, v98, v144
	v_mul_f32_e32 v99, v99, v192
	v_mul_f32_e32 v100, v100, v145
	v_mul_f32_e32 v101, v101, v193
	v_cvt_pk_bf16_f32 v190, v102, v103
	v_cvt_pk_bf16_f32 v191, v104, v105
	v_cvt_pk_bf16_f32 v192, v98, v99
	v_cvt_pk_bf16_f32 v193, v100, v101
	s_waitcnt vmcnt(11)
	v_lshlrev_b32_e32 v142, 16, v194
	v_and_b32_e32 v194, 0xffff0000, v194
	v_lshlrev_b32_e32 v143, 16, v195
	v_and_b32_e32 v195, 0xffff0000, v195
	v_lshlrev_b32_e32 v144, 16, v196
	v_and_b32_e32 v196, 0xffff0000, v196
	v_lshlrev_b32_e32 v145, 16, v197
	v_and_b32_e32 v197, 0xffff0000, v197
	v_mul_f32_e32 v94, v94, v142
	v_mul_f32_e32 v95, v95, v194
	v_mul_f32_e32 v96, v96, v143
	v_mul_f32_e32 v97, v97, v195
	v_mul_f32_e32 v90, v90, v144
	v_mul_f32_e32 v91, v91, v196
	v_mul_f32_e32 v92, v92, v145
	v_mul_f32_e32 v93, v93, v197
	v_cvt_pk_bf16_f32 v194, v94, v95
	v_cvt_pk_bf16_f32 v195, v96, v97
	v_cvt_pk_bf16_f32 v196, v90, v91
	v_cvt_pk_bf16_f32 v197, v92, v93
	s_waitcnt vmcnt(10)
	v_lshlrev_b32_e32 v142, 16, v198
	v_and_b32_e32 v198, 0xffff0000, v198
	v_lshlrev_b32_e32 v143, 16, v199
	v_and_b32_e32 v199, 0xffff0000, v199
	v_lshlrev_b32_e32 v144, 16, v200
	v_and_b32_e32 v200, 0xffff0000, v200
	v_lshlrev_b32_e32 v145, 16, v201
	v_and_b32_e32 v201, 0xffff0000, v201
	v_mul_f32_e32 v86, v86, v142
	v_mul_f32_e32 v87, v87, v198
	v_mul_f32_e32 v88, v88, v143
	v_mul_f32_e32 v89, v89, v199
	v_mul_f32_e32 v82, v82, v144
	v_mul_f32_e32 v83, v83, v200
	v_mul_f32_e32 v84, v84, v145
	v_mul_f32_e32 v85, v85, v201
	v_cvt_pk_bf16_f32 v198, v86, v87
	v_cvt_pk_bf16_f32 v199, v88, v89
	v_cvt_pk_bf16_f32 v200, v82, v83
	v_cvt_pk_bf16_f32 v201, v84, v85
	s_waitcnt vmcnt(9)
; __device__ __forceinline__ unsigned cvt_pk_bf16(float lo, float hi) { unsigned r; asm volatile("v_cvt_pk_bf16_f32 %0, %1, %2" : "=v"(r) : "v"(lo), "v"(hi)); return r; }
; __device__ __forceinline__ float bflo(unsigned w) { return __uint_as_float(w << 16); }
; __device__ __forceinline__ float bfhi(unsigned w) { return __uint_as_float(w & 0xffff0000u); }
;     __device__ __forceinline__ void operator()(const f32x4 (&acc)[2][2][4][2], const Unit& u, int wr, int wc, int fr, int fq) const {
;     ...
;             for (int m = 0; m < 4; ++m) { const size_t row = (size_t)(row0 + ai * HALF + m * 16);
; #pragma unroll
;                 for (int bj = 0; bj < 2; ++bj) { const int col = col0 + bj * HALF;
;                     const u32x4 g = *(const u32x4*)(P + row * LDP + PC_GB + col);
;                     f32x4 v0 = acc[ai][bj][m][0], v1 = acc[ai][bj][m][1];
;                     v0[0] *= bflo(g.x); v0[1] *= bfhi(g.x); v0[2] *= bflo(g.y); v0[3] *= bfhi(g.y);
;                     v1[0] *= bflo(g.z); v1[1] *= bfhi(g.z); v1[2] *= bflo(g.w); v1[3] *= bfhi(g.w);
;                     u32x4 w; w.x = cvt_pk_bf16(v0[0], v0[1]); w.y = cvt_pk_bf16(v0[2], v0[3]); w.z = cvt_pk_bf16(v1[0], v1[1]); w.w = cvt_pk_bf16(v1[2], v1[3]);
;                     *(u32x4*)(O + row * 2048 + col) = w; }
	v_lshlrev_b32_e32 v142, 16, v202
	v_and_b32_e32 v202, 0xffff0000, v202
	v_lshlrev_b32_e32 v143, 16, v203
	v_and_b32_e32 v203, 0xffff0000, v203
	v_lshlrev_b32_e32 v144, 16, v204
	v_and_b32_e32 v204, 0xffff0000, v204
	v_lshlrev_b32_e32 v145, 16, v205
	v_and_b32_e32 v205, 0xffff0000, v205
	v_mul_f32_e32 v78, v78, v142
	v_mul_f32_e32 v79, v79, v202
	v_mul_f32_e32 v80, v80, v143
	v_mul_f32_e32 v81, v81, v203
	v_mul_f32_e32 v74, v74, v144
	v_mul_f32_e32 v75, v75, v204
	v_mul_f32_e32 v76, v76, v145
	v_mul_f32_e32 v77, v77, v205
	v_cvt_pk_bf16_f32 v202, v78, v79
	v_cvt_pk_bf16_f32 v203, v80, v81
	v_cvt_pk_bf16_f32 v204, v74, v75
	v_cvt_pk_bf16_f32 v205, v76, v77
	s_waitcnt vmcnt(8)
	v_lshlrev_b32_e32 v142, 16, v206
	v_and_b32_e32 v206, 0xffff0000, v206
	v_lshlrev_b32_e32 v143, 16, v207
	v_and_b32_e32 v207, 0xffff0000, v207
	v_lshlrev_b32_e32 v144, 16, v208
	v_and_b32_e32 v208, 0xffff0000, v208
	v_lshlrev_b32_e32 v145, 16, v209
	v_and_b32_e32 v209, 0xffff0000, v209
	v_mul_f32_e32 v70, v70, v142
	v_mul_f32_e32 v71, v71, v206
	v_mul_f32_e32 v72, v72, v143
	v_mul_f32_e32 v73, v73, v207
	v_mul_f32_e32 v66, v66, v144
	v_mul_f32_e32 v67, v67, v208
	v_mul_f32_e32 v68, v68, v145
	v_mul_f32_e32 v69, v69, v209
	v_cvt_pk_bf16_f32 v206, v70, v71
	v_cvt_pk_bf16_f32 v207, v72, v73
	v_cvt_pk_bf16_f32 v208, v66, v67
	v_cvt_pk_bf16_f32 v209, v68, v69
	s_waitcnt vmcnt(7)
	v_lshlrev_b32_e32 v142, 16, v214
	v_and_b32_e32 v214, 0xffff0000, v214
	v_lshlrev_b32_e32 v143, 16, v215
	v_and_b32_e32 v215, 0xffff0000, v215
	v_lshlrev_b32_e32 v144, 16, v216
	v_and_b32_e32 v216, 0xffff0000, v216
	v_lshlrev_b32_e32 v145, 16, v217
	v_and_b32_e32 v217, 0xffff0000, v217
	v_mul_f32_e32 v62, v62, v142
	v_mul_f32_e32 v63, v63, v214
	v_mul_f32_e32 v64, v64, v143
	v_mul_f32_e32 v65, v65, v215
	v_mul_f32_e32 v58, v58, v144
	v_mul_f32_e32 v59, v59, v216
	v_mul_f32_e32 v60, v60, v145
	v_mul_f32_e32 v61, v61, v217
	v_cvt_pk_bf16_f32 v214, v62, v63
	v_cvt_pk_bf16_f32 v215, v64, v65
	v_cvt_pk_bf16_f32 v216, v58, v59
	v_cvt_pk_bf16_f32 v217, v60, v61
	s_waitcnt vmcnt(6)
	v_lshlrev_b32_e32 v142, 16, v218
	v_and_b32_e32 v218, 0xffff0000, v218
	v_lshlrev_b32_e32 v143, 16, v219
	v_and_b32_e32 v219, 0xffff0000, v219
	v_lshlrev_b32_e32 v144, 16, v220
	v_and_b32_e32 v220, 0xffff0000, v220
	v_lshlrev_b32_e32 v145, 16, v221
	v_and_b32_e32 v221, 0xffff0000, v221
	v_mul_f32_e32 v54, v54, v142
	v_mul_f32_e32 v55, v55, v218
	v_mul_f32_e32 v56, v56, v143
	v_mul_f32_e32 v57, v57, v219
	v_mul_f32_e32 v50, v50, v144
	v_mul_f32_e32 v51, v51, v220
	v_mul_f32_e32 v52, v52, v145
	v_mul_f32_e32 v53, v53, v221
	v_cvt_pk_bf16_f32 v218, v54, v55
	v_cvt_pk_bf16_f32 v219, v56, v57
	v_cvt_pk_bf16_f32 v220, v50, v51
	v_cvt_pk_bf16_f32 v221, v52, v53
	s_waitcnt vmcnt(5)
	v_lshlrev_b32_e32 v142, 16, v222
	v_and_b32_e32 v222, 0xffff0000, v222
	v_lshlrev_b32_e32 v143, 16, v223
	v_and_b32_e32 v223, 0xffff0000, v223
	v_lshlrev_b32_e32 v144, 16, v224
	v_and_b32_e32 v224, 0xffff0000, v224
	v_lshlrev_b32_e32 v145, 16, v225
	v_and_b32_e32 v225, 0xffff0000, v225
	v_mul_f32_e32 v46, v46, v142
	v_mul_f32_e32 v47, v47, v222
	v_mul_f32_e32 v48, v48, v143
	v_mul_f32_e32 v49, v49, v223
	v_mul_f32_e32 v42, v42, v144
	v_mul_f32_e32 v43, v43, v224
	v_mul_f32_e32 v44, v44, v145
	v_mul_f32_e32 v45, v45, v225
	v_cvt_pk_bf16_f32 v222, v46, v47
	v_cvt_pk_bf16_f32 v223, v48, v49
	v_cvt_pk_bf16_f32 v224, v42, v43
	v_cvt_pk_bf16_f32 v225, v44, v45
	s_waitcnt vmcnt(4)
	v_lshlrev_b32_e32 v142, 16, v226
	v_and_b32_e32 v226, 0xffff0000, v226
	v_lshlrev_b32_e32 v143, 16, v227
	v_and_b32_e32 v227, 0xffff0000, v227
	v_lshlrev_b32_e32 v144, 16, v228
	v_and_b32_e32 v228, 0xffff0000, v228
	v_lshlrev_b32_e32 v145, 16, v229
	v_and_b32_e32 v229, 0xffff0000, v229
	v_mul_f32_e32 v38, v38, v142
	v_mul_f32_e32 v39, v39, v226
	v_mul_f32_e32 v40, v40, v143
	v_mul_f32_e32 v41, v41, v227
	v_mul_f32_e32 v34, v34, v144
	v_mul_f32_e32 v35, v35, v228
	v_mul_f32_e32 v36, v36, v145
	v_mul_f32_e32 v37, v37, v229
	v_cvt_pk_bf16_f32 v226, v38, v39
	v_cvt_pk_bf16_f32 v227, v40, v41
	v_cvt_pk_bf16_f32 v228, v34, v35
	v_cvt_pk_bf16_f32 v229, v36, v37
	s_waitcnt vmcnt(3)
; __device__ __forceinline__ unsigned cvt_pk_bf16(float lo, float hi) { unsigned r; asm volatile("v_cvt_pk_bf16_f32 %0, %1, %2" : "=v"(r) : "v"(lo), "v"(hi)); return r; }
; __device__ __forceinline__ float bflo(unsigned w) { return __uint_as_float(w << 16); }
; __device__ __forceinline__ float bfhi(unsigned w) { return __uint_as_float(w & 0xffff0000u); }
; #define PG8_BAR __builtin_amdgcn_s_barrier()
;     __device__ __forceinline__ void operator()(const f32x4 (&acc)[2][2][4][2], const Unit& u, int wr, int wc, int fr, int fq) const {
;     ...
;             for (int m = 0; m < 4; ++m) { const size_t row = (size_t)(row0 + ai * HALF + m * 16);
; #pragma unroll
;                 for (int bj = 0; bj < 2; ++bj) { const int col = col0 + bj * HALF;
;                     const u32x4 g = *(const u32x4*)(P + row * LDP + PC_GB + col);
;                     f32x4 v0 = acc[ai][bj][m][0], v1 = acc[ai][bj][m][1];
;                     v0[0] *= bflo(g.x); v0[1] *= bfhi(g.x); v0[2] *= bflo(g.y); v0[3] *= bfhi(g.y);
;                     v1[0] *= bflo(g.z); v1[1] *= bfhi(g.z); v1[2] *= bflo(g.w); v1[3] *= bfhi(g.w);
;                     u32x4 w; w.x = cvt_pk_bf16(v0[0], v0[1]); w.y = cvt_pk_bf16(v0[2], v0[3]); w.z = cvt_pk_bf16(v1[0], v1[1]); w.w = cvt_pk_bf16(v1[2], v1[3]);
;                     *(u32x4*)(O + row * 2048 + col) = w; }
; template <class Epi, class Sched, bool ALIGN_EPI = false, bool SP2 = false>
; __device__ __forceinline__ void gemm_phase(PG8_LAS unsigned char* lds, const Gemm g, const Sched& S, const Epi& E) {
;     ...
;         if (!has_next) break;
; #pragma unroll
;         for (int a = 0; a < 2; ++a)
; #pragma unroll
;             for (int b = 0; b < 2; ++b)
; #pragma unroll
;                 for (int m = 0; m < 4; ++m)
; #pragma unroll
;                     for (int n = 0; n < 2; ++n) acc[a][b][m][n] = (f32x4){0.f, 0.f, 0.f, 0.f};
;         cur = nxt; cA = nA; cB = nB; ++ui;
;         if constexpr (ALIGN_EPI) { if (wr == 1) PG8_BAR; }
	v_lshlrev_b32_e32 v142, 16, v230
	v_and_b32_e32 v230, 0xffff0000, v230
	v_lshlrev_b32_e32 v143, 16, v231
	v_and_b32_e32 v231, 0xffff0000, v231
	v_lshlrev_b32_e32 v144, 16, v232
	v_and_b32_e32 v232, 0xffff0000, v232
	v_lshlrev_b32_e32 v145, 16, v233
	v_and_b32_e32 v233, 0xffff0000, v233
	v_mul_f32_e32 v30, v30, v142
	v_mul_f32_e32 v31, v31, v230
	v_mul_f32_e32 v32, v32, v143
	v_mul_f32_e32 v33, v33, v231
	v_mul_f32_e32 v26, v26, v144
	v_mul_f32_e32 v27, v27, v232
	v_mul_f32_e32 v28, v28, v145
	v_mul_f32_e32 v29, v29, v233
	v_cvt_pk_bf16_f32 v230, v30, v31
	v_cvt_pk_bf16_f32 v231, v32, v33
	v_cvt_pk_bf16_f32 v232, v26, v27
	v_cvt_pk_bf16_f32 v233, v28, v29
	s_waitcnt vmcnt(2)
	v_lshlrev_b32_e32 v142, 16, v234
	v_and_b32_e32 v234, 0xffff0000, v234
	v_lshlrev_b32_e32 v143, 16, v235
	v_and_b32_e32 v235, 0xffff0000, v235
	v_lshlrev_b32_e32 v144, 16, v236
	v_and_b32_e32 v236, 0xffff0000, v236
	v_lshlrev_b32_e32 v145, 16, v237
	v_and_b32_e32 v237, 0xffff0000, v237
	v_mul_f32_e32 v22, v22, v142
	v_mul_f32_e32 v23, v23, v234
	v_mul_f32_e32 v24, v24, v143
	v_mul_f32_e32 v25, v25, v235
	v_mul_f32_e32 v18, v18, v144
	v_mul_f32_e32 v19, v19, v236
	v_mul_f32_e32 v20, v20, v145
	v_mul_f32_e32 v21, v21, v237
	v_cvt_pk_bf16_f32 v234, v22, v23
	v_cvt_pk_bf16_f32 v235, v24, v25
	v_cvt_pk_bf16_f32 v236, v18, v19
	v_cvt_pk_bf16_f32 v237, v20, v21
	s_waitcnt vmcnt(1)
	v_lshlrev_b32_e32 v142, 16, v238
	v_and_b32_e32 v238, 0xffff0000, v238
	v_lshlrev_b32_e32 v143, 16, v239
	v_and_b32_e32 v239, 0xffff0000, v239
	v_lshlrev_b32_e32 v144, 16, v240
	v_and_b32_e32 v240, 0xffff0000, v240
	v_lshlrev_b32_e32 v145, 16, v241
	v_and_b32_e32 v241, 0xffff0000, v241
	v_mul_f32_e32 v14, v14, v142
	v_mul_f32_e32 v15, v15, v238
	v_mul_f32_e32 v16, v16, v143
	v_mul_f32_e32 v17, v17, v239
	v_mul_f32_e32 v10, v10, v144
	v_mul_f32_e32 v11, v11, v240
	v_mul_f32_e32 v12, v12, v145
	v_mul_f32_e32 v13, v13, v241
	v_cvt_pk_bf16_f32 v238, v14, v15
	v_cvt_pk_bf16_f32 v239, v16, v17
	v_cvt_pk_bf16_f32 v240, v10, v11
	v_cvt_pk_bf16_f32 v241, v12, v13
	s_waitcnt vmcnt(0)
	v_lshlrev_b32_e32 v142, 16, v242
	v_and_b32_e32 v242, 0xffff0000, v242
	v_lshlrev_b32_e32 v143, 16, v243
	v_and_b32_e32 v243, 0xffff0000, v243
	v_lshlrev_b32_e32 v144, 16, v244
	v_and_b32_e32 v244, 0xffff0000, v244
	v_lshlrev_b32_e32 v145, 16, v245
	v_and_b32_e32 v245, 0xffff0000, v245
	v_mul_f32_e32 v6, v6, v142
	v_mul_f32_e32 v7, v7, v242
	v_mul_f32_e32 v8, v8, v143
	v_mul_f32_e32 v9, v9, v243
	v_mul_f32_e32 v2, v2, v144
	v_mul_f32_e32 v3, v3, v244
	v_mul_f32_e32 v4, v4, v145
	v_mul_f32_e32 v5, v5, v245
	v_cvt_pk_bf16_f32 v242, v6, v7
	v_cvt_pk_bf16_f32 v243, v8, v9
	v_cvt_pk_bf16_f32 v244, v2, v3
	v_cvt_pk_bf16_f32 v245, v4, v5
	global_store_dwordx4 v163, v[130:133], s[42:43] sc1
	s_add_u32 s2, s42, 0x100
	s_addc_u32 s3, s43, 0
	global_store_dwordx4 v163, v[134:137], s[2:3] sc1
	s_add_u32 s2, s42, 0x10000
	s_addc_u32 s3, s43, 0
	global_store_dwordx4 v163, v[186:189], s[2:3] sc1
	s_add_u32 s2, s42, 0x10100
	s_addc_u32 s3, s43, 0
	global_store_dwordx4 v163, v[190:193], s[2:3] sc1
	s_add_u32 s2, s42, 0x20000
	s_addc_u32 s3, s43, 0
	global_store_dwordx4 v163, v[194:197], s[2:3] sc1
	s_add_u32 s2, s42, 0x20100
	s_addc_u32 s3, s43, 0
	global_store_dwordx4 v163, v[198:201], s[2:3] sc1
	s_add_u32 s2, s42, 0x30000
	s_addc_u32 s3, s43, 0
	global_store_dwordx4 v163, v[202:205], s[2:3] sc1
	s_add_u32 s2, s42, 0x30100
	s_addc_u32 s3, s43, 0
	global_store_dwordx4 v163, v[206:209], s[2:3] sc1
	s_add_u32 s2, s42, 0x80000
	s_addc_u32 s3, s43, 0
	global_store_dwordx4 v163, v[214:217], s[2:3] sc1
	s_add_u32 s2, s42, 0x80100
	s_addc_u32 s3, s43, 0
	global_store_dwordx4 v163, v[218:221], s[2:3] sc1
	s_add_u32 s2, s42, 0x90000
	s_addc_u32 s3, s43, 0
	global_store_dwordx4 v163, v[222:225], s[2:3] sc1
	s_add_u32 s2, s42, 0x90100
	s_addc_u32 s3, s43, 0
	global_store_dwordx4 v163, v[226:229], s[2:3] sc1
	s_add_u32 s2, s42, 0xa0000
	s_addc_u32 s3, s43, 0
	global_store_dwordx4 v163, v[230:233], s[2:3] sc1
	s_add_u32 s2, s42, 0xa0100
	s_addc_u32 s3, s43, 0
	global_store_dwordx4 v163, v[234:237], s[2:3] sc1
	s_add_u32 s2, s42, 0xb0000
	s_addc_u32 s3, s43, 0
	global_store_dwordx4 v163, v[238:241], s[2:3] sc1
	s_add_u32 s2, s42, 0xb0100
	s_addc_u32 s3, s43, 0
	global_store_dwordx4 v163, v[242:245], s[2:3] sc1
	s_mov_b64 s[2:3], -1
	s_andn2_b64 vcc, exec, s[38:39]
	s_cbranch_vccnz .LBB0_69
	s_andn2_b64 vcc, exec, s[0:1]
	s_cbranch_vccnz .LBB0_68
	s_barrier
	s_branch .LBB0_68

; __device__ __forceinline__ void phase_conv(const Args& a, int l) {
;     ...
;     for (int idx0 = blockIdx.x * NTHR + tid; idx0 < M * (DB / 8); idx0 += 2 * stride) {
;         u32x4 bg[2], zb[2], c0[2], h0[2], c1[2], h1[2], c2[2], h2[2]; float s1[2], s2[2];
; #pragma unroll
;         for (int u = 0; u < 2; ++u) { const int idx = idx0 + u * stride < M * (DB / 8) ? idx0 + u * stride : idx0;
;             const int m = idx >> 7, c = (idx & 127) * 8, t = m % SEQ;
;             const bf16* q = P + (size_t)m * LDP; const bf16* q1 = t >= 1 ? q - LDP : q; const bf16* q2 = t >= 2 ? q - 2 * LDP : q;
;             s1[u] = t >= 1 ? 1.f : 0.f; s2[u] = t >= 2 ? 1.f : 0.f;
;             bg[u] = *(const u32x4*)(q + PC_BG + c); zb[u] = *(const u32x4*)(q + PC_ZB + c); c0[u] = *(const u32x4*)(q + PC_CG + c); h0[u] = *(const u32x4*)(q + PC_HB + c);
;             c1[u] = *(const u32x4*)(q1 + PC_CG + c); h1[u] = *(const u32x4*)(q1 + PC_HB + c); c2[u] = *(const u32x4*)(q2 + PC_CG + c); h2[u] = *(const u32x4*)(q2 + PC_HB + c); }
; #pragma unroll
;         for (int u = 0; u < 2; ++u) { const int idx = idx0 + u * stride; if (idx < M * (DB / 8)) {
;             const int m = idx >> 7, c = (idx & 127) * 8;
;             float w0[8], w1[8], w2[8];
;             *(f32x4*)w0 = *(const f32x4*)(cwp + c) * s2[u]; *(f32x4*)(w0 + 4) = *(const f32x4*)(cwp + c + 4) * s2[u];
;             *(f32x4*)w1 = *(const f32x4*)(cwp + DB + c) * s1[u]; *(f32x4*)(w1 + 4) = *(const f32x4*)(cwp + DB + c + 4) * s1[u];
;             *(f32x4*)w2 = *(const f32x4*)(cwp + 2 * DB + c); *(f32x4*)(w2 + 4) = *(const f32x4*)(cwp + 2 * DB + c + 4);
.LBB0_94:
	v_add_u32_e32 v98, s88, v96
	s_mov_b32 s0, 0x200000
	v_cmp_gt_i32_e64 s[38:39], s0, v98
	s_waitcnt vmcnt(0)
	v_mov_b64_e32 v[34:35], s[4:5]
	s_movk_i32 s2, 0x2000
	v_cndmask_b32_e64 v0, v96, v98, s[38:39]
	v_ashrrev_i32_e32 v3, 31, v0
	v_ashrrev_i32_e32 v2, 7, v0
	v_lshrrev_b32_e32 v3, 20, v3
	v_add_u32_e32 v3, v2, v3
	v_and_b32_e32 v3, 0xfffff000, v3
	v_sub_u32_e32 v6, v2, v3
	v_cmp_lt_i32_e32 vcc, 0, v6
	v_mad_i64_i32 v[2:3], s[0:1], v2, s7, v[34:35]
	s_nop 0
	v_cndmask_b32_e64 v5, 0, -1, vcc
	v_cndmask_b32_e32 v4, 0, v180, vcc
	v_cmp_lt_i32_e64 s[40:41], 1, v6
	v_lshlrev_b32_e32 v0, 4, v0
	v_lshl_add_u64 v[18:19], v[2:3], 0, v[4:5]
	v_cndmask_b32_e64 v5, 0, -1, s[40:41]
	v_cndmask_b32_e64 v4, 0, v181, s[40:41]
	v_and_b32_e32 v0, 0x7f0, v0
	v_lshl_add_u64 v[20:21], v[2:3], 0, v[4:5]
	v_lshl_add_u64 v[2:3], v[2:3], 0, v[0:1]
	v_add_co_u32_e64 v10, s[0:1], s2, v2
	s_movk_i32 s3, 0x3000
	s_nop 0
	v_addc_co_u32_e64 v11, s[0:1], 0, v3, s[0:1]
	v_add_co_u32_e64 v12, s[0:1], s3, v2
	v_lshl_add_u64 v[18:19], v[18:19], 0, v[0:1]
	s_nop 0
	v_addc_co_u32_e64 v13, s[0:1], 0, v3, s[0:1]
	v_add_co_u32_e64 v22, s[0:1], s2, v18
	s_waitcnt lgkmcnt(0)
	global_load_dwordx4 v[6:9], v[10:11], off offset:512
	v_addc_co_u32_e64 v23, s[0:1], 0, v19, s[0:1]
	v_add_co_u32_e64 v18, s[0:1], s3, v18
	global_load_dwordx4 v[2:5], v[12:13], off offset:2560
	global_load_dwordx4 v[14:17], v[10:11], off offset:2560
	s_nop 0
	global_load_dwordx4 v[10:13], v[12:13], off offset:512
	v_addc_co_u32_e64 v19, s[0:1], 0, v19, s[0:1]
	global_load_dwordx4 v[26:29], v[22:23], off offset:2560
	global_load_dwordx4 v[30:33], v[18:19], off offset:512
	v_lshl_add_u64 v[18:19], v[20:21], 0, v[0:1]
	v_add_co_u32_e64 v20, s[0:1], s2, v18
	v_and_b32_e32 v36, 0x3f8, v97
	s_nop 0
	v_addc_co_u32_e64 v21, s[0:1], 0, v19, s[0:1]
	v_add_co_u32_e64 v18, s[0:1], s3, v18
	v_lshlrev_b32_e32 v0, 1, v36
	s_nop 0
	v_addc_co_u32_e64 v19, s[0:1], 0, v19, s[0:1]
	v_readlane_b32 s0, v251, 31
	v_readlane_b32 s1, v251, 32
	v_ashrrev_i32_e32 v78, 7, v96
	v_lshlrev_b32_e32 v76, 2, v36
	v_lshl_add_u64 v[74:75], s[0:1], 0, v[0:1]
	v_mad_i64_i32 v[38:39], s[0:1], v78, s7, v[34:35]
	v_ashrrev_i32_e32 v34, 31, v96
	v_lshrrev_b32_e32 v34, 20, v34
	v_add_u32_e32 v34, v78, v34
	v_and_b32_e32 v34, 0xfffff000, v34
	v_sub_u32_e32 v46, v78, v34
	v_cmp_lt_i32_e64 s[0:1], 1, v46
	global_load_dwordx4 v[22:25], v[20:21], off offset:2560
	v_ashrrev_i32_e32 v79, 31, v78
	v_cndmask_b32_e64 v35, 0, -1, s[0:1]
	v_cndmask_b32_e64 v34, 0, v181, s[0:1]
	v_lshl_add_u64 v[34:35], v[38:39], 0, v[34:35]
	v_lshl_add_u64 v[40:41], v[34:35], 0, v[0:1]
	v_add_co_u32_e64 v34, s[42:43], s3, v40
	s_nop 1
	v_addc_co_u32_e64 v35, s[42:43], 0, v41, s[42:43]
	v_add_co_u32_e64 v40, s[42:43], s2, v40
	global_load_dwordx4 v[34:37], v[34:35], off offset:512
	s_nop 0
	v_addc_co_u32_e64 v41, s[42:43], 0, v41, s[42:43]
	v_cmp_lt_i32_e64 s[42:43], 0, v46
	global_load_dwordx4 v[42:45], v[40:41], off offset:2560
	s_waitcnt vmcnt(0)
	v_lshlrev_b32_e32 v103, 16, v34
	v_cndmask_b32_e64 v41, 0, -1, s[42:43]
	v_cndmask_b32_e64 v40, 0, v180, s[42:43]
	v_lshl_add_u64 v[40:41], v[38:39], 0, v[40:41]
	v_lshl_add_u64 v[40:41], v[40:41], 0, v[0:1]
	v_add_co_u32_e64 v46, s[44:45], s3, v40
	v_lshl_add_u64 v[38:39], v[38:39], 0, v[0:1]
	s_nop 0
	v_addc_co_u32_e64 v47, s[44:45], 0, v41, s[44:45]
	v_add_co_u32_e64 v40, s[44:45], s2, v40
	global_load_dwordx4 v[58:61], v[46:47], off offset:512
	s_nop 0
	v_addc_co_u32_e64 v41, s[44:45], 0, v41, s[44:45]
	global_load_dwordx4 v[62:65], v[40:41], off offset:2560
	v_add_co_u32_e64 v40, s[44:45], s3, v38
	v_cndmask_b32_e64 v0, 0, 1.0, s[0:1]
	s_nop 0
	v_addc_co_u32_e64 v41, s[44:45], 0, v39, s[44:45]
	v_add_co_u32_e64 v50, s[44:45], s2, v38
	global_load_dwordx4 v[46:49], v[40:41], off offset:512
	s_nop 0
	v_addc_co_u32_e64 v51, s[44:45], 0, v39, s[44:45]
	global_load_dwordx4 v[18:21], v[18:19], off offset:512
	s_nop 0
	global_load_dwordx4 v[54:57], v[50:51], off offset:2560
	s_nop 0
	global_load_dwordx4 v[38:41], v[40:41], off offset:2560
	s_nop 0
	global_load_dwordx4 v[50:53], v[50:51], off offset:512
	s_nop 0
	global_load_dwordx4 v[66:69], v76, s[52:53] offset:16
	global_load_dwordx4 v[70:73], v76, s[52:53]
	v_cndmask_b32_e64 v86, 0, 1.0, s[42:43]
	v_lshlrev_b32_e32 v101, 16, v42
	s_waitcnt vmcnt(7)
	v_lshlrev_b32_e32 v77, 16, v62
	v_and_b32_e32 v62, 0xffff0000, v62
	s_waitcnt vmcnt(6)
	v_lshlrev_b32_e32 v102, 16, v46
	s_waitcnt vmcnt(4)
	v_lshlrev_b32_e32 v100, 16, v54
	v_pk_mul_f32 v[100:101], v[102:103], v[100:101]
	s_waitcnt vmcnt(1)
	v_pk_mul_f32 v[80:81], v[0:1], v[68:69] op_sel_hi:[0,1]
	s_waitcnt vmcnt(0)
	v_pk_mul_f32 v[88:89], v[0:1], v[72:73] op_sel_hi:[0,1]
	v_pk_mul_f32 v[92:93], v[0:1], v[70:71] op_sel_hi:[0,1]
	v_pk_mul_f32 v[84:85], v[0:1], v[66:67] op_sel_hi:[0,1]
	global_load_dwordx4 v[66:69], v76, s[54:55] offset:16
	global_load_dwordx4 v[70:73], v76, s[54:55]
	v_lshlrev_b32_e32 v0, 16, v58
	v_mov_b32_e32 v103, v92
	v_mul_f32_e32 v0, v77, v0
	v_and_b32_e32 v58, 0xffff0000, v58
	v_mul_f32_e32 v58, v62, v58
	v_lshlrev_b32_e32 v62, 16, v47
	s_waitcnt vmcnt(1)
	v_pk_mul_f32 v[82:83], v[86:87], v[68:69] op_sel_hi:[0,1]
	s_waitcnt vmcnt(0)
	v_pk_mul_f32 v[90:91], v[86:87], v[72:73] op_sel_hi:[0,1]
	v_pk_mul_f32 v[94:95], v[86:87], v[70:71] op_sel_hi:[0,1]
	v_pk_mul_f32 v[86:87], v[86:87], v[66:67] op_sel_hi:[0,1]
	global_load_dwordx4 v[66:69], v76, s[56:57] offset:16
	global_load_dwordx4 v[70:73], v76, s[56:57]
	s_waitcnt vmcnt(0)
; __device__ __forceinline__ unsigned cvt_pk_bf16(float lo, float hi) { unsigned r; asm volatile("v_cvt_pk_bf16_f32 %0, %1, %2" : "=v"(r) : "v"(lo), "v"(hi)); return r; }
; __device__ __forceinline__ float fsig(float x) { return __builtin_amdgcn_rcpf(1.0f + __expf(-x)); }
; __device__ __forceinline__ float bflo(unsigned w) { return __uint_as_float(w << 16); }
; __device__ __forceinline__ float bfhi(unsigned w) { return __uint_as_float(w & 0xffff0000u); }
; __device__ __forceinline__ void phase_conv(const Args& a, int l) {
;     ...
;         for (int u = 0; u < 2; ++u) { const int idx = idx0 + u * stride; if (idx < M * (DB / 8)) {
;             const int m = idx >> 7, c = (idx & 127) * 8;
;             float w0[8], w1[8], w2[8];
;             *(f32x4*)w0 = *(const f32x4*)(cwp + c) * s2[u]; *(f32x4*)(w0 + 4) = *(const f32x4*)(cwp + c + 4) * s2[u];
;             *(f32x4*)w1 = *(const f32x4*)(cwp + DB + c) * s1[u]; *(f32x4*)(w1 + 4) = *(const f32x4*)(cwp + DB + c + 4) * s1[u];
;             *(f32x4*)w2 = *(const f32x4*)(cwp + 2 * DB + c); *(f32x4*)(w2 + 4) = *(const f32x4*)(cwp + 2 * DB + c + 4);
;             float o[8];
; #pragma unroll
;             for (int k = 0; k < 4; ++k) {
;                 const float u0l = bflo(c0[u][k]) * bflo(h0[u][k]), u0h = bfhi(c0[u][k]) * bfhi(h0[u][k]);
;                 const float u1l = bflo(c1[u][k]) * bflo(h1[u][k]), u1h = bfhi(c1[u][k]) * bfhi(h1[u][k]);
;                 const float u2l = bflo(c2[u][k]) * bflo(h2[u][k]), u2h = bfhi(c2[u][k]) * bfhi(h2[u][k]);
;                 const float zl = bflo(zb[u][k]), zh = bfhi(zb[u][k]);
;                 o[2 * k] = bflo(bg[u][k]) * (w0[2 * k] * u2l + w1[2 * k] * u1l + w2[2 * k] * u0l) * (zl * fsig(zl));
;                 o[2 * k + 1] = bfhi(bg[u][k]) * (w0[2 * k + 1] * u2h + w1[2 * k + 1] * u1h + w2[2 * k + 1] * u0h) * (zh * fsig(zh));
;             }
;             u32x4 w; w.x = cvt_pk_bf16(o[0], o[1]); w.y = cvt_pk_bf16(o[2], o[3]); w.z = cvt_pk_bf16(o[4], o[5]); w.w = cvt_pk_bf16(o[6], o[7]);
;             *(u32x4*)(YB + (size_t)m * D + c) = w; } }
	v_mov_b32_e32 v102, v70
	v_pk_mul_f32 v[100:101], v[100:101], v[102:103]
	v_lshlrev_b32_e32 v102, 16, v38
	v_fma_f32 v0, v0, v94, v101
	v_add_f32_e32 v101, v100, v0
	v_mul_f32_e32 v0, 0xbfb8aa3b, v102
	v_exp_f32_e32 v0, v0
	v_lshlrev_b32_e32 v103, 16, v50
	v_mov_b32_e32 v92, v71
	v_add_f32_e32 v0, 1.0, v0
	v_rcp_f32_e32 v100, v0
	s_nop 0
	v_pk_mul_f32 v[100:101], v[100:101], v[102:103]
	s_nop 0
	v_mul_f32_e32 v0, v100, v101
	v_and_b32_e32 v101, 0xffff0000, v42
	v_and_b32_e32 v100, 0xffff0000, v54
	v_and_b32_e32 v103, 0xffff0000, v34
	v_and_b32_e32 v102, 0xffff0000, v46
	v_pk_mul_f32 v[100:101], v[102:103], v[100:101]
	v_and_b32_e32 v42, 0xffff0000, v59
	v_pk_mul_f32 v[70:71], v[100:101], v[92:93]
	v_and_b32_e32 v92, 0xffff0000, v38
	v_fma_f32 v34, v58, v95, v71
	v_add_f32_e32 v71, v70, v34
	v_mul_f32_e32 v34, 0xbfb8aa3b, v92
	v_exp_f32_e32 v34, v34
	v_lshlrev_b32_e32 v38, 16, v63
	v_lshlrev_b32_e32 v58, 16, v55
	v_and_b32_e32 v93, 0xffff0000, v50
	v_add_f32_e32 v34, 1.0, v34
	v_rcp_f32_e32 v70, v34
	v_lshlrev_b32_e32 v34, 16, v59
	v_mul_f32_e32 v34, v38, v34
	v_and_b32_e32 v38, 0xffff0000, v63
	v_lshlrev_b32_e32 v59, 16, v43
	v_lshlrev_b32_e32 v63, 16, v35
	v_pk_mul_f32 v[58:59], v[62:63], v[58:59]
	v_mov_b32_e32 v62, v72
	v_mov_b32_e32 v63, v88
	v_pk_mul_f32 v[58:59], v[58:59], v[62:63]
	v_lshlrev_b32_e32 v62, 16, v39
	v_fma_f32 v34, v34, v90, v59
	v_add_f32_e32 v59, v58, v34
	v_mul_f32_e32 v34, 0xbfb8aa3b, v62
	v_exp_f32_e32 v34, v34
	v_mul_f32_e32 v38, v38, v42
	v_and_b32_e32 v43, 0xffff0000, v43
	v_and_b32_e32 v42, 0xffff0000, v55
	v_add_f32_e32 v34, 1.0, v34
	v_rcp_f32_e32 v58, v34
	v_and_b32_e32 v35, 0xffff0000, v35
	v_and_b32_e32 v34, 0xffff0000, v47
	v_pk_mul_f32 v[34:35], v[34:35], v[42:43]
	v_mov_b32_e32 v88, v73
	v_pk_mul_f32 v[34:35], v[34:35], v[88:89]
	v_and_b32_e32 v42, 0xffff0000, v39
	v_fma_f32 v35, v38, v91, v35
	v_add_f32_e32 v35, v34, v35
	v_mul_f32_e32 v34, 0xbfb8aa3b, v42
	v_exp_f32_e32 v34, v34
	v_and_b32_e32 v43, 0xffff0000, v51
	v_lshlrev_b32_e32 v39, 16, v36
	v_lshlrev_b32_e32 v38, 16, v48
	v_add_f32_e32 v34, 1.0, v34
	v_rcp_f32_e32 v34, v34
	v_lshlrev_b32_e32 v63, 16, v51
	v_pk_mul_f32 v[70:71], v[70:71], v[92:93]
	v_pk_mul_f32 v[58:59], v[58:59], v[62:63]
	v_pk_mul_f32 v[34:35], v[34:35], v[42:43]
	v_mul_f32_e32 v46, v70, v71
	v_mul_f32_e32 v42, v34, v35
	v_lshlrev_b32_e32 v34, 16, v60
	v_lshlrev_b32_e32 v35, 16, v64
	v_mul_f32_e32 v43, v35, v34
	v_and_b32_e32 v34, 0xffff0000, v64
	v_and_b32_e32 v35, 0xffff0000, v60
	v_mul_f32_e32 v47, v34, v35
	v_lshlrev_b32_e32 v35, 16, v44
	v_lshlrev_b32_e32 v34, 16, v56
	v_pk_mul_f32 v[34:35], v[38:39], v[34:35]
	v_mov_b32_e32 v38, v66
	v_mov_b32_e32 v39, v84
	v_pk_mul_f32 v[34:35], v[34:35], v[38:39]
	v_lshlrev_b32_e32 v38, 16, v40
	v_fma_f32 v35, v43, v86, v35
	v_add_f32_e32 v35, v34, v35
	v_mul_f32_e32 v34, 0xbfb8aa3b, v38
	v_exp_f32_e32 v34, v34
	v_lshlrev_b32_e32 v39, 16, v52
	v_mov_b32_e32 v84, v67
	v_mul_f32_e32 v50, v58, v59
	v_add_f32_e32 v34, 1.0, v34
	v_rcp_f32_e32 v34, v34
	s_nop 0
	v_pk_mul_f32 v[34:35], v[34:35], v[38:39]
	s_nop 0
	v_mul_f32_e32 v43, v34, v35
	v_and_b32_e32 v35, 0xffff0000, v44
	v_and_b32_e32 v34, 0xffff0000, v56
	v_and_b32_e32 v39, 0xffff0000, v36
	v_and_b32_e32 v38, 0xffff0000, v48
	v_pk_mul_f32 v[34:35], v[38:39], v[34:35]
	v_and_b32_e32 v38, 0xffff0000, v40
	v_pk_mul_f32 v[34:35], v[34:35], v[84:85]
	v_and_b32_e32 v39, 0xffff0000, v52
	v_fma_f32 v35, v47, v87, v35
	v_add_f32_e32 v35, v34, v35
	v_mul_f32_e32 v34, 0xbfb8aa3b, v38
	v_exp_f32_e32 v34, v34
	s_nop 0
	v_add_f32_e32 v34, 1.0, v34
	v_rcp_f32_e32 v34, v34
	s_nop 0
	v_pk_mul_f32 v[34:35], v[34:35], v[38:39]
	s_nop 0
	v_mul_f32_e32 v40, v34, v35
	v_lshlrev_b32_e32 v34, 16, v61
	v_lshlrev_b32_e32 v35, 16, v65
	v_mul_f32_e32 v36, v35, v34
	v_and_b32_e32 v34, 0xffff0000, v65
	v_and_b32_e32 v35, 0xffff0000, v61
	v_mul_f32_e32 v44, v34, v35
	v_lshlrev_b32_e32 v35, 16, v45
	v_lshlrev_b32_e32 v34, 16, v57
	v_lshlrev_b32_e32 v39, 16, v37
	v_lshlrev_b32_e32 v38, 16, v49
	v_pk_mul_f32 v[34:35], v[38:39], v[34:35]
	v_mov_b32_e32 v38, v68
	v_mov_b32_e32 v39, v80
	v_pk_mul_f32 v[34:35], v[34:35], v[38:39]
	v_lshlrev_b32_e32 v38, 16, v41
	v_fma_f32 v35, v36, v82, v35
	v_add_f32_e32 v35, v34, v35
	v_mul_f32_e32 v34, 0xbfb8aa3b, v38
	v_exp_f32_e32 v34, v34
	v_lshlrev_b32_e32 v39, 16, v53
	v_and_b32_e32 v37, 0xffff0000, v37
	v_and_b32_e32 v36, 0xffff0000, v49
	v_add_f32_e32 v34, 1.0, v34
	v_rcp_f32_e32 v34, v34
	v_mov_b32_e32 v80, v69
	v_pk_mul_f32 v[34:35], v[34:35], v[38:39]
	s_nop 0
	v_mul_f32_e32 v38, v34, v35
	v_and_b32_e32 v35, 0xffff0000, v45
	v_and_b32_e32 v34, 0xffff0000, v57
	v_pk_mul_f32 v[34:35], v[36:37], v[34:35]
	v_and_b32_e32 v36, 0xffff0000, v41
	v_pk_mul_f32 v[34:35], v[34:35], v[80:81]
	v_and_b32_e32 v37, 0xffff0000, v53
	v_fma_f32 v35, v44, v83, v35
	v_add_f32_e32 v35, v34, v35
	v_mul_f32_e32 v34, 0xbfb8aa3b, v36
	v_exp_f32_e32 v34, v34
	s_nop 0
	v_add_f32_e32 v34, 1.0, v34
	v_rcp_f32_e32 v34, v34
	s_nop 0
	v_pk_mul_f32 v[34:35], v[34:35], v[36:37]
	s_nop 0
	v_mul_f32_e32 v37, v34, v35
	v_cvt_pk_bf16_f32 v34, v0, v46
	v_cvt_pk_bf16_f32 v35, v50, v42
	v_cvt_pk_bf16_f32 v36, v43, v40
	v_cvt_pk_bf16_f32 v37, v38, v37
	v_lshlrev_b64 v[38:39], 12, v[78:79]
	v_lshl_add_u64 v[38:39], v[74:75], 0, v[38:39]
	global_store_dwordx4 v[38:39], v[34:37], off sc1
	s_and_saveexec_b64 s[0:1], s[38:39]
	s_cbranch_execz .LBB0_93
; __device__ __forceinline__ unsigned cvt_pk_bf16(float lo, float hi) { unsigned r; asm volatile("v_cvt_pk_bf16_f32 %0, %1, %2" : "=v"(r) : "v"(lo), "v"(hi)); return r; }
; __device__ __forceinline__ float fsig(float x) { return __builtin_amdgcn_rcpf(1.0f + __expf(-x)); }
; __device__ __forceinline__ float bflo(unsigned w) { return __uint_as_float(w << 16); }
; __device__ __forceinline__ float bfhi(unsigned w) { return __uint_as_float(w & 0xffff0000u); }
; __device__ __forceinline__ void phase_conv(const Args& a, int l) {
;     ...
;         for (int u = 0; u < 2; ++u) { const int idx = idx0 + u * stride; if (idx < M * (DB / 8)) {
;             const int m = idx >> 7, c = (idx & 127) * 8;
;             float w0[8], w1[8], w2[8];
;             *(f32x4*)w0 = *(const f32x4*)(cwp + c) * s2[u]; *(f32x4*)(w0 + 4) = *(const f32x4*)(cwp + c + 4) * s2[u];
;             *(f32x4*)w1 = *(const f32x4*)(cwp + DB + c) * s1[u]; *(f32x4*)(w1 + 4) = *(const f32x4*)(cwp + DB + c + 4) * s1[u];
;             *(f32x4*)w2 = *(const f32x4*)(cwp + 2 * DB + c); *(f32x4*)(w2 + 4) = *(const f32x4*)(cwp + 2 * DB + c + 4);
;             float o[8];
; #pragma unroll
;             for (int k = 0; k < 4; ++k) {
;                 const float u0l = bflo(c0[u][k]) * bflo(h0[u][k]), u0h = bfhi(c0[u][k]) * bfhi(h0[u][k]);
;                 const float u1l = bflo(c1[u][k]) * bflo(h1[u][k]), u1h = bfhi(c1[u][k]) * bfhi(h1[u][k]);
;                 const float u2l = bflo(c2[u][k]) * bflo(h2[u][k]), u2h = bfhi(c2[u][k]) * bfhi(h2[u][k]);
;                 const float zl = bflo(zb[u][k]), zh = bfhi(zb[u][k]);
;                 o[2 * k] = bflo(bg[u][k]) * (w0[2 * k] * u2l + w1[2 * k] * u1l + w2[2 * k] * u0l) * (zl * fsig(zl));
;                 o[2 * k + 1] = bfhi(bg[u][k]) * (w0[2 * k + 1] * u2h + w1[2 * k + 1] * u1h + w2[2 * k + 1] * u0h) * (zh * fsig(zh));
;             }
;             u32x4 w; w.x = cvt_pk_bf16(o[0], o[1]); w.y = cvt_pk_bf16(o[2], o[3]); w.z = cvt_pk_bf16(o[4], o[5]); w.w = cvt_pk_bf16(o[6], o[7]);
;             *(u32x4*)(YB + (size_t)m * D + c) = w; } }
	v_mov_b32_e32 v77, v1
	v_lshl_add_u64 v[38:39], s[52:53], 0, v[76:77]
	global_load_dwordx4 v[34:37], v[38:39], off offset:16
	s_nop 0
	global_load_dwordx4 v[38:41], v[38:39], off
	v_lshl_add_u64 v[44:45], s[54:55], 0, v[76:77]
	v_cndmask_b32_e64 v0, 0, 1.0, s[40:41]
	v_lshl_add_u64 v[54:55], s[56:57], 0, v[76:77]
	v_cndmask_b32_e64 v48, 0, 1.0, vcc
	v_lshlrev_b32_e32 v61, 16, v18
	v_lshlrev_b32_e32 v60, 16, v10
	s_waitcnt vmcnt(1)
	v_pk_mul_f32 v[42:43], v[0:1], v[36:37] op_sel_hi:[0,1]
	s_waitcnt vmcnt(0)
	v_pk_mul_f32 v[50:51], v[0:1], v[40:41] op_sel_hi:[0,1]
	v_pk_mul_f32 v[56:57], v[0:1], v[38:39] op_sel_hi:[0,1]
	v_pk_mul_f32 v[46:47], v[0:1], v[34:35] op_sel_hi:[0,1]
	global_load_dwordx4 v[34:37], v[44:45], off offset:16
	global_load_dwordx4 v[38:41], v[44:45], off
	v_lshlrev_b32_e32 v0, 16, v26
	v_and_b32_e32 v26, 0xffff0000, v26
	s_waitcnt vmcnt(1)
	v_pk_mul_f32 v[44:45], v[48:49], v[36:37] op_sel_hi:[0,1]
	s_waitcnt vmcnt(0)
	v_pk_mul_f32 v[52:53], v[48:49], v[40:41] op_sel_hi:[0,1]
	v_pk_mul_f32 v[58:59], v[48:49], v[38:39] op_sel_hi:[0,1]
	v_pk_mul_f32 v[48:49], v[48:49], v[34:35] op_sel_hi:[0,1]
	global_load_dwordx4 v[34:37], v[54:55], off offset:16
	global_load_dwordx4 v[38:41], v[54:55], off
	v_lshlrev_b32_e32 v54, 16, v30
	v_mul_f32_e32 v0, v54, v0
	v_lshlrev_b32_e32 v55, 16, v22
	v_lshlrev_b32_e32 v54, 16, v14
	v_pk_mul_f32 v[54:55], v[54:55], v[60:61]
	v_mov_b32_e32 v61, v56
	v_and_b32_e32 v30, 0xffff0000, v30
	v_mul_f32_e32 v26, v30, v26
	v_lshlrev_b32_e32 v30, 16, v11
	s_waitcnt vmcnt(0)
	v_mov_b32_e32 v60, v38
	v_pk_mul_f32 v[54:55], v[54:55], v[60:61]
	v_lshlrev_b32_e32 v60, 16, v2
	v_fma_f32 v0, v0, v58, v55
	v_add_f32_e32 v55, v54, v0
	v_mul_f32_e32 v0, 0xbfb8aa3b, v60
	v_exp_f32_e32 v0, v0
	v_lshlrev_b32_e32 v61, 16, v6
	v_mov_b32_e32 v56, v39
	v_add_f32_e32 v0, 1.0, v0
	v_rcp_f32_e32 v54, v0
	s_nop 0
	v_pk_mul_f32 v[54:55], v[54:55], v[60:61]
	s_nop 0
	v_mul_f32_e32 v0, v54, v55
	v_and_b32_e32 v55, 0xffff0000, v22
	v_and_b32_e32 v54, 0xffff0000, v14
	v_and_b32_e32 v61, 0xffff0000, v18
	v_and_b32_e32 v60, 0xffff0000, v10
	v_pk_mul_f32 v[54:55], v[54:55], v[60:61]
	v_and_b32_e32 v14, 0xffff0000, v27
	v_pk_mul_f32 v[38:39], v[54:55], v[56:57]
	v_and_b32_e32 v55, 0xffff0000, v6
	v_fma_f32 v10, v26, v59, v39
	v_add_f32_e32 v39, v38, v10
	v_lshlrev_b32_e32 v6, 16, v27
	v_lshlrev_b32_e32 v10, 16, v31
	v_mul_f32_e32 v6, v10, v6
	v_and_b32_e32 v10, 0xffff0000, v31
	v_mul_f32_e32 v18, v10, v14
	v_lshlrev_b32_e32 v27, 16, v23
	v_lshlrev_b32_e32 v26, 16, v15
	v_lshlrev_b32_e32 v31, 16, v19
	v_and_b32_e32 v23, 0xffff0000, v23
	v_and_b32_e32 v22, 0xffff0000, v15
	v_and_b32_e32 v15, 0xffff0000, v19
	v_and_b32_e32 v14, 0xffff0000, v11
	v_pk_mul_f32 v[26:27], v[26:27], v[30:31]
	v_mov_b32_e32 v30, v40
	v_mov_b32_e32 v31, v50
	v_pk_mul_f32 v[10:11], v[22:23], v[14:15]
	v_and_b32_e32 v14, 0xffff0000, v3
	v_pk_mul_f32 v[26:27], v[26:27], v[30:31]
	v_lshlrev_b32_e32 v30, 16, v3
	v_mul_f32_e32 v3, 0xbfb8aa3b, v14
	v_exp_f32_e32 v3, v3
	v_mov_b32_e32 v50, v41
	v_pk_mul_f32 v[10:11], v[10:11], v[50:51]
	v_and_b32_e32 v15, 0xffff0000, v7
	v_fma_f32 v11, v18, v53, v11
	v_add_f32_e32 v3, 1.0, v3
	v_add_f32_e32 v11, v10, v11
	v_rcp_f32_e32 v10, v3
	v_lshlrev_b32_e32 v31, 16, v7
	v_lshlrev_b32_e32 v7, 16, v28
	v_and_b32_e32 v54, 0xffff0000, v2
	v_pk_mul_f32 v[10:11], v[10:11], v[14:15]
	v_lshlrev_b32_e32 v15, 16, v20
	v_mul_f32_e32 v3, v10, v11
	v_lshlrev_b32_e32 v10, 16, v32
	v_mul_f32_e32 v7, v10, v7
	v_and_b32_e32 v10, 0xffff0000, v32
	v_and_b32_e32 v11, 0xffff0000, v28
	v_mul_f32_e32 v18, v10, v11
	v_lshlrev_b32_e32 v11, 16, v24
	v_lshlrev_b32_e32 v10, 16, v16
	v_lshlrev_b32_e32 v14, 16, v12
	v_pk_mul_f32 v[10:11], v[10:11], v[14:15]
	v_mov_b32_e32 v14, v34
	v_mov_b32_e32 v15, v46
	v_pk_mul_f32 v[10:11], v[10:11], v[14:15]
	v_lshlrev_b32_e32 v14, 16, v4
	v_fma_f32 v7, v7, v48, v11
	v_add_f32_e32 v11, v10, v7
	v_mul_f32_e32 v7, 0xbfb8aa3b, v14
	v_exp_f32_e32 v7, v7
	v_lshlrev_b32_e32 v15, 16, v8
	v_mov_b32_e32 v46, v35
	v_fma_f32 v6, v6, v52, v27
	v_add_f32_e32 v7, 1.0, v7
	v_rcp_f32_e32 v10, v7
	v_mul_f32_e32 v2, 0xbfb8aa3b, v54
	v_add_f32_e32 v27, v26, v6
	v_mul_f32_e32 v6, 0xbfb8aa3b, v30
	v_pk_mul_f32 v[10:11], v[10:11], v[14:15]
	v_and_b32_e32 v15, 0xffff0000, v20
	v_mul_f32_e32 v7, v10, v11
	v_and_b32_e32 v11, 0xffff0000, v24
	v_and_b32_e32 v10, 0xffff0000, v16
	v_and_b32_e32 v14, 0xffff0000, v12
	v_pk_mul_f32 v[10:11], v[10:11], v[14:15]
	v_and_b32_e32 v14, 0xffff0000, v4
	v_mul_f32_e32 v4, 0xbfb8aa3b, v14
	v_exp_f32_e32 v4, v4
	v_pk_mul_f32 v[10:11], v[10:11], v[46:47]
	v_and_b32_e32 v15, 0xffff0000, v8
	v_fma_f32 v11, v18, v49, v11
	v_add_f32_e32 v4, 1.0, v4
	v_add_f32_e32 v11, v10, v11
	v_rcp_f32_e32 v10, v4
	v_lshlrev_b32_e32 v4, 16, v29
	v_lshlrev_b32_e32 v8, 16, v33
	v_mul_f32_e32 v4, v8, v4
	v_pk_mul_f32 v[10:11], v[10:11], v[14:15]
	v_and_b32_e32 v8, 0xffff0000, v33
	v_mul_f32_e32 v12, v10, v11
	v_and_b32_e32 v10, 0xffff0000, v29
	v_mul_f32_e32 v8, v8, v10
	v_lshlrev_b32_e32 v11, 16, v25
	v_lshlrev_b32_e32 v10, 16, v17
	v_lshlrev_b32_e32 v15, 16, v21
	v_lshlrev_b32_e32 v14, 16, v13
	v_pk_mul_f32 v[10:11], v[10:11], v[14:15]
	v_mov_b32_e32 v14, v36
	v_mov_b32_e32 v15, v42
	v_pk_mul_f32 v[10:11], v[10:11], v[14:15]
	v_lshlrev_b32_e32 v14, 16, v5
	v_fma_f32 v4, v4, v44, v11
	v_add_f32_e32 v11, v10, v4
	v_mul_f32_e32 v4, 0xbfb8aa3b, v14
	v_exp_f32_e32 v4, v4
	v_lshlrev_b32_e32 v15, 16, v9
	v_mov_b32_e32 v42, v37
	v_exp_f32_e32 v2, v2
	v_add_f32_e32 v4, 1.0, v4
	v_rcp_f32_e32 v10, v4
	v_exp_f32_e32 v6, v6
	v_add_f32_e32 v2, 1.0, v2
	v_rcp_f32_e32 v38, v2
	v_pk_mul_f32 v[10:11], v[10:11], v[14:15]
	v_and_b32_e32 v15, 0xffff0000, v21
	v_mul_f32_e32 v16, v10, v11
	v_and_b32_e32 v11, 0xffff0000, v25
	v_and_b32_e32 v10, 0xffff0000, v17
	v_and_b32_e32 v14, 0xffff0000, v13
	v_pk_mul_f32 v[10:11], v[10:11], v[14:15]
	v_add_f32_e32 v6, 1.0, v6
	v_pk_mul_f32 v[10:11], v[10:11], v[42:43]
	v_rcp_f32_e32 v26, v6
	v_fma_f32 v4, v8, v45, v11
	v_and_b32_e32 v8, 0xffff0000, v5
	v_add_f32_e32 v11, v10, v4
	v_mul_f32_e32 v4, 0xbfb8aa3b, v8
	v_exp_f32_e32 v4, v4
	v_and_b32_e32 v9, 0xffff0000, v9
	v_pk_mul_f32 v[38:39], v[38:39], v[54:55]
	v_pk_mul_f32 v[26:27], v[26:27], v[30:31]
	v_add_f32_e32 v4, 1.0, v4
	v_rcp_f32_e32 v10, v4
	v_mul_f32_e32 v2, v38, v39
	v_mul_f32_e32 v6, v26, v27
	v_cvt_pk_bf16_f32 v2, v0, v2
	v_pk_mul_f32 v[4:5], v[10:11], v[8:9]
	v_ashrrev_i32_e32 v8, 7, v98
	v_ashrrev_i32_e32 v9, 31, v8
	v_mul_f32_e32 v5, v4, v5
	v_cvt_pk_bf16_f32 v3, v6, v3
	v_cvt_pk_bf16_f32 v4, v7, v12
	v_lshlrev_b64 v[6:7], 12, v[8:9]
	v_lshl_add_u64 v[6:7], v[74:75], 0, v[6:7]
	v_cvt_pk_bf16_f32 v5, v16, v5
	global_store_dwordx4 v[6:7], v[2:5], off sc1
	s_branch .LBB0_93

; __device__ __forceinline__ unsigned cvt_pk_bf16(float lo, float hi) { unsigned r; asm volatile("v_cvt_pk_bf16_f32 %0, %1, %2" : "=v"(r) : "v"(lo), "v"(hi)); return r; }
; __device__ __forceinline__ float fsig(float x) { return __builtin_amdgcn_rcpf(1.0f + __expf(-x)); }
;     __device__ __forceinline__ void operator()(const f32x4 (&acc)[2][2][4][2], const Unit& u, int wr, int wc, int fr, int fq) const {
;     ...
;             for (int m = 0; m < 4; ++m) { bf16_t* rowp = O + (size_t)(row0 + ai * HALF + m * 16) * LDP + col0;
; #pragma unroll
;                 for (int bj = 0; bj < 2; ++bj) { f32x4 v0 = acc[ai][bj][m][0], v1 = acc[ai][bj][m][1];
;                     if (act == 1) {
; #pragma unroll
;                         for (int j = 0; j < 4; ++j) { v0[j] = v0[j] * fsig(v0[j]); v1[j] = v1[j] * fsig(v1[j]); } }
;                     else if (act == 2) {
; #pragma unroll
;                         for (int j = 0; j < 4; ++j) { v0[j] = fsig(v0[j]); v1[j] = fsig(v1[j]); } }
;                     u32x4 w; w.x = cvt_pk_bf16(v0[0], v0[1]); w.y = cvt_pk_bf16(v0[2], v0[3]); w.z = cvt_pk_bf16(v1[0], v1[1]); w.w = cvt_pk_bf16(v1[2], v1[3]);
;                     *(u32x4*)(rowp + bj * HALF) = w; } }
.LBB0_423:
	v_lshl_add_u32 v159, s71, 8, v138
	v_lshl_or_b32 v152, s70, 8, v157
	v_mov_b64_e32 v[154:155], s[42:43]
	v_ashrrev_i32_e32 v153, 31, v152
	v_mad_i64_i32 v[154:155], s[2:3], v159, s7, v[154:155]
	v_cvt_pk_bf16_f32 v126, v126, v127
	v_cvt_pk_bf16_f32 v127, v128, v129
	v_cvt_pk_bf16_f32 v128, v122, v123
	v_cndmask_b32_e64 v122, 0, 1, s[56:57]
	v_lshl_add_u64 v[154:155], v[152:153], 1, v[154:155]
	v_cmp_ne_u32_e64 s[40:41], 1, v122
	s_andn2_b64 vcc, exec, s[56:57]
	v_cvt_pk_bf16_f32 v129, v124, v125
	flat_store_dwordx4 v[154:155], v[126:129] sc1
	s_cbranch_vccnz .LBB0_425
	v_mul_f32_e32 v118, 0xbfb8aa3b, v118
	v_mul_f32_e32 v114, 0xbfb8aa3b, v114
	v_mul_f32_e32 v119, 0xbfb8aa3b, v119
	v_mul_f32_e32 v115, 0xbfb8aa3b, v115
	v_mul_f32_e32 v120, 0xbfb8aa3b, v120
	v_mul_f32_e32 v116, 0xbfb8aa3b, v116
	v_mul_f32_e32 v121, 0xbfb8aa3b, v121
	v_mul_f32_e32 v117, 0xbfb8aa3b, v117
	v_exp_f32_e32 v118, v118
	v_exp_f32_e32 v114, v114
	v_exp_f32_e32 v119, v119
	v_exp_f32_e32 v115, v115
	v_exp_f32_e32 v120, v120
	v_exp_f32_e32 v116, v116
	v_exp_f32_e32 v121, v121
	v_exp_f32_e32 v117, v117
	v_add_f32_e32 v118, 1.0, v118
	v_add_f32_e32 v114, 1.0, v114
	v_add_f32_e32 v119, 1.0, v119
	v_add_f32_e32 v115, 1.0, v115
	v_add_f32_e32 v120, 1.0, v120
	v_add_f32_e32 v116, 1.0, v116
	v_add_f32_e32 v121, 1.0, v121
	v_add_f32_e32 v117, 1.0, v117
	v_rcp_f32_e32 v118, v118
	v_rcp_f32_e32 v114, v114
	v_rcp_f32_e32 v119, v119
	v_rcp_f32_e32 v115, v115
	v_rcp_f32_e32 v120, v120
	v_rcp_f32_e32 v116, v116
	v_rcp_f32_e32 v121, v121
	v_rcp_f32_e32 v117, v117
.LBB0_425:
	v_readlane_b32 s78, v253, 49
	s_and_b64 vcc, exec, s[40:41]
	s_mov_b32 s75, 0x800000
	s_mov_b32 s76, 0x1ffff
	v_readlane_b32 s79, v253, 50
	v_cvt_pk_bf16_f32 v118, v118, v119
	v_cvt_pk_bf16_f32 v119, v120, v121
	v_cvt_pk_bf16_f32 v120, v114, v115
	v_cvt_pk_bf16_f32 v121, v116, v117
	flat_store_dwordx4 v[154:155], v[118:121] offset:256 sc1
	s_cbranch_vccnz .LBB0_427
	v_mul_f32_e32 v110, 0xbfb8aa3b, v110
	v_mul_f32_e32 v106, 0xbfb8aa3b, v106
	v_mul_f32_e32 v111, 0xbfb8aa3b, v111
	v_mul_f32_e32 v107, 0xbfb8aa3b, v107
	v_mul_f32_e32 v112, 0xbfb8aa3b, v112
	v_mul_f32_e32 v108, 0xbfb8aa3b, v108
	v_mul_f32_e32 v113, 0xbfb8aa3b, v113
	v_mul_f32_e32 v109, 0xbfb8aa3b, v109
	v_exp_f32_e32 v110, v110
	v_exp_f32_e32 v106, v106
	v_exp_f32_e32 v111, v111
	v_exp_f32_e32 v107, v107
	v_exp_f32_e32 v112, v112
	v_exp_f32_e32 v108, v108
	v_exp_f32_e32 v113, v113
	v_exp_f32_e32 v109, v109
	v_add_f32_e32 v110, 1.0, v110
	v_add_f32_e32 v106, 1.0, v106
	v_add_f32_e32 v111, 1.0, v111
	v_add_f32_e32 v107, 1.0, v107
	v_add_f32_e32 v112, 1.0, v112
	v_add_f32_e32 v108, 1.0, v108
	v_add_f32_e32 v113, 1.0, v113
	v_add_f32_e32 v109, 1.0, v109
	v_rcp_f32_e32 v110, v110
	v_rcp_f32_e32 v106, v106
	v_rcp_f32_e32 v111, v111
	v_rcp_f32_e32 v107, v107
	v_rcp_f32_e32 v112, v112
	v_rcp_f32_e32 v108, v108
	v_rcp_f32_e32 v113, v113
	v_rcp_f32_e32 v109, v109
.LBB0_427:
	v_or_b32_e32 v116, 16, v159
	v_mov_b64_e32 v[114:115], s[42:43]
	v_mad_i64_i32 v[114:115], s[2:3], v116, s7, v[114:115]
	v_lshl_add_u64 v[114:115], v[152:153], 1, v[114:115]
	s_and_b64 vcc, exec, s[40:41]
	v_cvt_pk_bf16_f32 v110, v110, v111
	v_cvt_pk_bf16_f32 v111, v112, v113
	v_cvt_pk_bf16_f32 v112, v106, v107
	v_cvt_pk_bf16_f32 v113, v108, v109
	flat_store_dwordx4 v[114:115], v[110:113] sc1
	s_cbranch_vccnz .LBB0_429
	v_mul_f32_e32 v102, 0xbfb8aa3b, v102
	v_mul_f32_e32 v98, 0xbfb8aa3b, v98
	v_mul_f32_e32 v103, 0xbfb8aa3b, v103
	v_mul_f32_e32 v99, 0xbfb8aa3b, v99
	v_mul_f32_e32 v104, 0xbfb8aa3b, v104
	v_mul_f32_e32 v100, 0xbfb8aa3b, v100
	v_mul_f32_e32 v105, 0xbfb8aa3b, v105
	v_mul_f32_e32 v101, 0xbfb8aa3b, v101
	v_exp_f32_e32 v102, v102
	v_exp_f32_e32 v98, v98
	v_exp_f32_e32 v103, v103
	v_exp_f32_e32 v99, v99
	v_exp_f32_e32 v104, v104
	v_exp_f32_e32 v100, v100
	v_exp_f32_e32 v105, v105
	v_exp_f32_e32 v101, v101
	v_add_f32_e32 v102, 1.0, v102
	v_add_f32_e32 v98, 1.0, v98
	v_add_f32_e32 v103, 1.0, v103
	v_add_f32_e32 v99, 1.0, v99
	v_add_f32_e32 v104, 1.0, v104
	v_add_f32_e32 v100, 1.0, v100
	v_add_f32_e32 v105, 1.0, v105
	v_add_f32_e32 v101, 1.0, v101
	v_rcp_f32_e32 v102, v102
	v_rcp_f32_e32 v98, v98
	v_rcp_f32_e32 v103, v103
	v_rcp_f32_e32 v99, v99
	v_rcp_f32_e32 v104, v104
	v_rcp_f32_e32 v100, v100
	v_rcp_f32_e32 v105, v105
	v_rcp_f32_e32 v101, v101
.LBB0_429:
	s_and_b64 vcc, exec, s[40:41]
	v_cvt_pk_bf16_f32 v102, v102, v103
	v_cvt_pk_bf16_f32 v103, v104, v105
	v_cvt_pk_bf16_f32 v104, v98, v99
	v_cvt_pk_bf16_f32 v105, v100, v101
	flat_store_dwordx4 v[114:115], v[102:105] offset:256 sc1
	s_cbranch_vccnz .LBB0_431
	v_mul_f32_e32 v94, 0xbfb8aa3b, v94
	v_mul_f32_e32 v90, 0xbfb8aa3b, v90
	v_mul_f32_e32 v95, 0xbfb8aa3b, v95
	v_mul_f32_e32 v91, 0xbfb8aa3b, v91
	v_mul_f32_e32 v96, 0xbfb8aa3b, v96
	v_mul_f32_e32 v92, 0xbfb8aa3b, v92
	v_mul_f32_e32 v97, 0xbfb8aa3b, v97
	v_mul_f32_e32 v93, 0xbfb8aa3b, v93
	v_exp_f32_e32 v94, v94
	v_exp_f32_e32 v90, v90
	v_exp_f32_e32 v95, v95
	v_exp_f32_e32 v91, v91
	v_exp_f32_e32 v96, v96
	v_exp_f32_e32 v92, v92
	v_exp_f32_e32 v97, v97
	v_exp_f32_e32 v93, v93
	v_add_f32_e32 v94, 1.0, v94
	v_add_f32_e32 v90, 1.0, v90
	v_add_f32_e32 v95, 1.0, v95
	v_add_f32_e32 v91, 1.0, v91
	v_add_f32_e32 v96, 1.0, v96
	v_add_f32_e32 v92, 1.0, v92
	v_add_f32_e32 v97, 1.0, v97
	v_add_f32_e32 v93, 1.0, v93
	v_rcp_f32_e32 v94, v94
	v_rcp_f32_e32 v90, v90
	v_rcp_f32_e32 v95, v95
	v_rcp_f32_e32 v91, v91
	v_rcp_f32_e32 v96, v96
	v_rcp_f32_e32 v92, v92
	v_rcp_f32_e32 v97, v97
	v_rcp_f32_e32 v93, v93
; __device__ __forceinline__ unsigned cvt_pk_bf16(float lo, float hi) { unsigned r; asm volatile("v_cvt_pk_bf16_f32 %0, %1, %2" : "=v"(r) : "v"(lo), "v"(hi)); return r; }
; __device__ __forceinline__ float fsig(float x) { return __builtin_amdgcn_rcpf(1.0f + __expf(-x)); }
;     __device__ __forceinline__ void operator()(const f32x4 (&acc)[2][2][4][2], const Unit& u, int wr, int wc, int fr, int fq) const {
;     ...
;             for (int m = 0; m < 4; ++m) { bf16_t* rowp = O + (size_t)(row0 + ai * HALF + m * 16) * LDP + col0;
; #pragma unroll
;                 for (int bj = 0; bj < 2; ++bj) { f32x4 v0 = acc[ai][bj][m][0], v1 = acc[ai][bj][m][1];
;                     if (act == 1) {
; #pragma unroll
;                         for (int j = 0; j < 4; ++j) { v0[j] = v0[j] * fsig(v0[j]); v1[j] = v1[j] * fsig(v1[j]); } }
;                     else if (act == 2) {
; #pragma unroll
;                         for (int j = 0; j < 4; ++j) { v0[j] = fsig(v0[j]); v1[j] = fsig(v1[j]); } }
;                     u32x4 w; w.x = cvt_pk_bf16(v0[0], v0[1]); w.y = cvt_pk_bf16(v0[2], v0[3]); w.z = cvt_pk_bf16(v1[0], v1[1]); w.w = cvt_pk_bf16(v1[2], v1[3]);
;                     *(u32x4*)(rowp + bj * HALF) = w; } }
.LBB0_431:
	v_or_b32_e32 v100, 32, v159
	v_mov_b64_e32 v[98:99], s[42:43]
	v_mad_i64_i32 v[98:99], s[2:3], v100, s7, v[98:99]
	v_lshl_add_u64 v[98:99], v[152:153], 1, v[98:99]
	s_and_b64 vcc, exec, s[40:41]
	v_cvt_pk_bf16_f32 v94, v94, v95
	v_cvt_pk_bf16_f32 v95, v96, v97
	v_cvt_pk_bf16_f32 v96, v90, v91
	v_cvt_pk_bf16_f32 v97, v92, v93
	flat_store_dwordx4 v[98:99], v[94:97] sc1
	s_cbranch_vccnz .LBB0_433
	v_mul_f32_e32 v86, 0xbfb8aa3b, v86
	v_mul_f32_e32 v82, 0xbfb8aa3b, v82
	v_mul_f32_e32 v87, 0xbfb8aa3b, v87
	v_mul_f32_e32 v83, 0xbfb8aa3b, v83
	v_mul_f32_e32 v88, 0xbfb8aa3b, v88
	v_mul_f32_e32 v84, 0xbfb8aa3b, v84
	v_mul_f32_e32 v89, 0xbfb8aa3b, v89
	v_mul_f32_e32 v85, 0xbfb8aa3b, v85
	v_exp_f32_e32 v86, v86
	v_exp_f32_e32 v82, v82
	v_exp_f32_e32 v87, v87
	v_exp_f32_e32 v83, v83
	v_exp_f32_e32 v88, v88
	v_exp_f32_e32 v84, v84
	v_exp_f32_e32 v89, v89
	v_exp_f32_e32 v85, v85
	v_add_f32_e32 v86, 1.0, v86
	v_add_f32_e32 v82, 1.0, v82
	v_add_f32_e32 v87, 1.0, v87
	v_add_f32_e32 v83, 1.0, v83
	v_add_f32_e32 v88, 1.0, v88
	v_add_f32_e32 v84, 1.0, v84
	v_add_f32_e32 v89, 1.0, v89
	v_add_f32_e32 v85, 1.0, v85
	v_rcp_f32_e32 v86, v86
	v_rcp_f32_e32 v82, v82
	v_rcp_f32_e32 v87, v87
	v_rcp_f32_e32 v83, v83
	v_rcp_f32_e32 v88, v88
	v_rcp_f32_e32 v84, v84
	v_rcp_f32_e32 v89, v89
	v_rcp_f32_e32 v85, v85
.LBB0_433:
	s_and_b64 vcc, exec, s[40:41]
	v_cvt_pk_bf16_f32 v86, v86, v87
	v_cvt_pk_bf16_f32 v87, v88, v89
	v_cvt_pk_bf16_f32 v88, v82, v83
	v_cvt_pk_bf16_f32 v89, v84, v85
	flat_store_dwordx4 v[98:99], v[86:89] offset:256 sc1
	s_cbranch_vccnz .LBB0_435
	v_mul_f32_e32 v78, 0xbfb8aa3b, v78
	v_mul_f32_e32 v74, 0xbfb8aa3b, v74
	v_mul_f32_e32 v79, 0xbfb8aa3b, v79
	v_mul_f32_e32 v75, 0xbfb8aa3b, v75
	v_mul_f32_e32 v80, 0xbfb8aa3b, v80
	v_mul_f32_e32 v76, 0xbfb8aa3b, v76
	v_mul_f32_e32 v81, 0xbfb8aa3b, v81
	v_mul_f32_e32 v77, 0xbfb8aa3b, v77
	v_exp_f32_e32 v78, v78
	v_exp_f32_e32 v74, v74
	v_exp_f32_e32 v79, v79
	v_exp_f32_e32 v75, v75
	v_exp_f32_e32 v80, v80
	v_exp_f32_e32 v76, v76
	v_exp_f32_e32 v81, v81
	v_exp_f32_e32 v77, v77
	v_add_f32_e32 v78, 1.0, v78
	v_add_f32_e32 v74, 1.0, v74
	v_add_f32_e32 v79, 1.0, v79
	v_add_f32_e32 v75, 1.0, v75
	v_add_f32_e32 v80, 1.0, v80
	v_add_f32_e32 v76, 1.0, v76
	v_add_f32_e32 v81, 1.0, v81
	v_add_f32_e32 v77, 1.0, v77
	v_rcp_f32_e32 v78, v78
	v_rcp_f32_e32 v74, v74
	v_rcp_f32_e32 v79, v79
	v_rcp_f32_e32 v75, v75
	v_rcp_f32_e32 v80, v80
	v_rcp_f32_e32 v76, v76
	v_rcp_f32_e32 v81, v81
	v_rcp_f32_e32 v77, v77
.LBB0_435:
	v_or_b32_e32 v84, 48, v159
	v_mov_b64_e32 v[82:83], s[42:43]
	v_mad_i64_i32 v[82:83], s[2:3], v84, s7, v[82:83]
	v_lshl_add_u64 v[82:83], v[152:153], 1, v[82:83]
	s_and_b64 vcc, exec, s[40:41]
	v_cvt_pk_bf16_f32 v78, v78, v79
	v_cvt_pk_bf16_f32 v79, v80, v81
	v_cvt_pk_bf16_f32 v80, v74, v75
	v_cvt_pk_bf16_f32 v81, v76, v77
	flat_store_dwordx4 v[82:83], v[78:81] sc1
	s_cbranch_vccnz .LBB0_437
	v_mul_f32_e32 v70, 0xbfb8aa3b, v70
	v_mul_f32_e32 v66, 0xbfb8aa3b, v66
	v_mul_f32_e32 v71, 0xbfb8aa3b, v71
	v_mul_f32_e32 v67, 0xbfb8aa3b, v67
	v_mul_f32_e32 v72, 0xbfb8aa3b, v72
	v_mul_f32_e32 v68, 0xbfb8aa3b, v68
	v_mul_f32_e32 v73, 0xbfb8aa3b, v73
	v_mul_f32_e32 v69, 0xbfb8aa3b, v69
	v_exp_f32_e32 v70, v70
	v_exp_f32_e32 v66, v66
	v_exp_f32_e32 v71, v71
	v_exp_f32_e32 v67, v67
	v_exp_f32_e32 v72, v72
	v_exp_f32_e32 v68, v68
	v_exp_f32_e32 v73, v73
	v_exp_f32_e32 v69, v69
	v_add_f32_e32 v70, 1.0, v70
	v_add_f32_e32 v66, 1.0, v66
	v_add_f32_e32 v71, 1.0, v71
	v_add_f32_e32 v67, 1.0, v67
	v_add_f32_e32 v72, 1.0, v72
	v_add_f32_e32 v68, 1.0, v68
	v_add_f32_e32 v73, 1.0, v73
	v_add_f32_e32 v69, 1.0, v69
	v_rcp_f32_e32 v70, v70
	v_rcp_f32_e32 v66, v66
	v_rcp_f32_e32 v71, v71
	v_rcp_f32_e32 v67, v67
	v_rcp_f32_e32 v72, v72
	v_rcp_f32_e32 v68, v68
	v_rcp_f32_e32 v73, v73
	v_rcp_f32_e32 v69, v69
.LBB0_437:
	s_and_b64 vcc, exec, s[40:41]
	v_cvt_pk_bf16_f32 v70, v70, v71
	v_cvt_pk_bf16_f32 v71, v72, v73
	v_cvt_pk_bf16_f32 v72, v66, v67
	v_cvt_pk_bf16_f32 v73, v68, v69
	flat_store_dwordx4 v[82:83], v[70:73] offset:256 sc1
	s_cbranch_vccnz .LBB0_439
	v_mul_f32_e32 v62, 0xbfb8aa3b, v62
	v_mul_f32_e32 v58, 0xbfb8aa3b, v58
	v_mul_f32_e32 v63, 0xbfb8aa3b, v63
	v_mul_f32_e32 v59, 0xbfb8aa3b, v59
	v_mul_f32_e32 v64, 0xbfb8aa3b, v64
	v_mul_f32_e32 v60, 0xbfb8aa3b, v60
	v_mul_f32_e32 v65, 0xbfb8aa3b, v65
	v_mul_f32_e32 v61, 0xbfb8aa3b, v61
	v_exp_f32_e32 v62, v62
	v_exp_f32_e32 v58, v58
	v_exp_f32_e32 v63, v63
	v_exp_f32_e32 v59, v59
	v_exp_f32_e32 v64, v64
	v_exp_f32_e32 v60, v60
	v_exp_f32_e32 v65, v65
	v_exp_f32_e32 v61, v61
	v_add_f32_e32 v62, 1.0, v62
	v_add_f32_e32 v58, 1.0, v58
	v_add_f32_e32 v63, 1.0, v63
	v_add_f32_e32 v59, 1.0, v59
	v_add_f32_e32 v64, 1.0, v64
	v_add_f32_e32 v60, 1.0, v60
	v_add_f32_e32 v65, 1.0, v65
	v_add_f32_e32 v61, 1.0, v61
	v_rcp_f32_e32 v62, v62
	v_rcp_f32_e32 v58, v58
	v_rcp_f32_e32 v63, v63
	v_rcp_f32_e32 v59, v59
	v_rcp_f32_e32 v64, v64
	v_rcp_f32_e32 v60, v60
	v_rcp_f32_e32 v65, v65
	v_rcp_f32_e32 v61, v61
.LBB0_439:
	v_add_u32_e32 v68, 0x80, v159
	v_mov_b64_e32 v[66:67], s[42:43]
	v_mad_i64_i32 v[66:67], s[2:3], v68, s7, v[66:67]
	v_lshl_add_u64 v[66:67], v[152:153], 1, v[66:67]
	s_and_b64 vcc, exec, s[40:41]
	v_cvt_pk_bf16_f32 v62, v62, v63
	v_cvt_pk_bf16_f32 v63, v64, v65
	v_cvt_pk_bf16_f32 v64, v58, v59
	v_cvt_pk_bf16_f32 v65, v60, v61
	flat_store_dwordx4 v[66:67], v[62:65] sc1
	s_cbranch_vccnz .LBB0_441
	v_mul_f32_e32 v54, 0xbfb8aa3b, v54
	v_mul_f32_e32 v50, 0xbfb8aa3b, v50
	v_mul_f32_e32 v55, 0xbfb8aa3b, v55
	v_mul_f32_e32 v51, 0xbfb8aa3b, v51
	v_mul_f32_e32 v56, 0xbfb8aa3b, v56
	v_mul_f32_e32 v52, 0xbfb8aa3b, v52
	v_mul_f32_e32 v57, 0xbfb8aa3b, v57
	v_mul_f32_e32 v53, 0xbfb8aa3b, v53
	v_exp_f32_e32 v54, v54
	v_exp_f32_e32 v50, v50
	v_exp_f32_e32 v55, v55
	v_exp_f32_e32 v51, v51
	v_exp_f32_e32 v56, v56
	v_exp_f32_e32 v52, v52
	v_exp_f32_e32 v57, v57
	v_exp_f32_e32 v53, v53
	v_add_f32_e32 v54, 1.0, v54
	v_add_f32_e32 v50, 1.0, v50
	v_add_f32_e32 v55, 1.0, v55
	v_add_f32_e32 v51, 1.0, v51
	v_add_f32_e32 v56, 1.0, v56
	v_add_f32_e32 v52, 1.0, v52
	v_add_f32_e32 v57, 1.0, v57
	v_add_f32_e32 v53, 1.0, v53
	v_rcp_f32_e32 v54, v54
	v_rcp_f32_e32 v50, v50
	v_rcp_f32_e32 v55, v55
	v_rcp_f32_e32 v51, v51
	v_rcp_f32_e32 v56, v56
	v_rcp_f32_e32 v52, v52
	v_rcp_f32_e32 v57, v57
	v_rcp_f32_e32 v53, v53
; __device__ __forceinline__ unsigned cvt_pk_bf16(float lo, float hi) { unsigned r; asm volatile("v_cvt_pk_bf16_f32 %0, %1, %2" : "=v"(r) : "v"(lo), "v"(hi)); return r; }
; __device__ __forceinline__ float fsig(float x) { return __builtin_amdgcn_rcpf(1.0f + __expf(-x)); }
;     __device__ __forceinline__ void operator()(const f32x4 (&acc)[2][2][4][2], const Unit& u, int wr, int wc, int fr, int fq) const {
;     ...
;             for (int m = 0; m < 4; ++m) { bf16_t* rowp = O + (size_t)(row0 + ai * HALF + m * 16) * LDP + col0;
; #pragma unroll
;                 for (int bj = 0; bj < 2; ++bj) { f32x4 v0 = acc[ai][bj][m][0], v1 = acc[ai][bj][m][1];
;                     if (act == 1) {
; #pragma unroll
;                         for (int j = 0; j < 4; ++j) { v0[j] = v0[j] * fsig(v0[j]); v1[j] = v1[j] * fsig(v1[j]); } }
;                     else if (act == 2) {
; #pragma unroll
;                         for (int j = 0; j < 4; ++j) { v0[j] = fsig(v0[j]); v1[j] = fsig(v1[j]); } }
;                     u32x4 w; w.x = cvt_pk_bf16(v0[0], v0[1]); w.y = cvt_pk_bf16(v0[2], v0[3]); w.z = cvt_pk_bf16(v1[0], v1[1]); w.w = cvt_pk_bf16(v1[2], v1[3]);
;                     *(u32x4*)(rowp + bj * HALF) = w; } }
.LBB0_441:
	s_and_b64 vcc, exec, s[40:41]
	v_cvt_pk_bf16_f32 v54, v54, v55
	v_cvt_pk_bf16_f32 v55, v56, v57
	v_cvt_pk_bf16_f32 v56, v50, v51
	v_cvt_pk_bf16_f32 v57, v52, v53
	flat_store_dwordx4 v[66:67], v[54:57] offset:256 sc1
	s_cbranch_vccnz .LBB0_443
	v_mul_f32_e32 v46, 0xbfb8aa3b, v46
	v_mul_f32_e32 v42, 0xbfb8aa3b, v42
	v_mul_f32_e32 v47, 0xbfb8aa3b, v47
	v_mul_f32_e32 v43, 0xbfb8aa3b, v43
	v_mul_f32_e32 v48, 0xbfb8aa3b, v48
	v_mul_f32_e32 v44, 0xbfb8aa3b, v44
	v_mul_f32_e32 v49, 0xbfb8aa3b, v49
	v_mul_f32_e32 v45, 0xbfb8aa3b, v45
	v_exp_f32_e32 v46, v46
	v_exp_f32_e32 v42, v42
	v_exp_f32_e32 v47, v47
	v_exp_f32_e32 v43, v43
	v_exp_f32_e32 v48, v48
	v_exp_f32_e32 v44, v44
	v_exp_f32_e32 v49, v49
	v_exp_f32_e32 v45, v45
	v_add_f32_e32 v46, 1.0, v46
	v_add_f32_e32 v42, 1.0, v42
	v_add_f32_e32 v47, 1.0, v47
	v_add_f32_e32 v43, 1.0, v43
	v_add_f32_e32 v48, 1.0, v48
	v_add_f32_e32 v44, 1.0, v44
	v_add_f32_e32 v49, 1.0, v49
	v_add_f32_e32 v45, 1.0, v45
	v_rcp_f32_e32 v46, v46
	v_rcp_f32_e32 v42, v42
	v_rcp_f32_e32 v47, v47
	v_rcp_f32_e32 v43, v43
	v_rcp_f32_e32 v48, v48
	v_rcp_f32_e32 v44, v44
	v_rcp_f32_e32 v49, v49
	v_rcp_f32_e32 v45, v45
.LBB0_443:
	v_add_u32_e32 v52, 0x90, v159
	v_mov_b64_e32 v[50:51], s[42:43]
	v_mad_i64_i32 v[50:51], s[2:3], v52, s7, v[50:51]
	v_lshl_add_u64 v[50:51], v[152:153], 1, v[50:51]
	s_and_b64 vcc, exec, s[40:41]
	v_cvt_pk_bf16_f32 v46, v46, v47
	v_cvt_pk_bf16_f32 v47, v48, v49
	v_cvt_pk_bf16_f32 v48, v42, v43
	v_cvt_pk_bf16_f32 v49, v44, v45
	flat_store_dwordx4 v[50:51], v[46:49] sc1
	s_cbranch_vccnz .LBB0_445
	v_mul_f32_e32 v38, 0xbfb8aa3b, v38
	v_mul_f32_e32 v34, 0xbfb8aa3b, v34
	v_mul_f32_e32 v39, 0xbfb8aa3b, v39
	v_mul_f32_e32 v35, 0xbfb8aa3b, v35
	v_mul_f32_e32 v40, 0xbfb8aa3b, v40
	v_mul_f32_e32 v36, 0xbfb8aa3b, v36
	v_mul_f32_e32 v41, 0xbfb8aa3b, v41
	v_mul_f32_e32 v37, 0xbfb8aa3b, v37
	v_exp_f32_e32 v38, v38
	v_exp_f32_e32 v34, v34
	v_exp_f32_e32 v39, v39
	v_exp_f32_e32 v35, v35
	v_exp_f32_e32 v40, v40
	v_exp_f32_e32 v36, v36
	v_exp_f32_e32 v41, v41
	v_exp_f32_e32 v37, v37
	v_add_f32_e32 v38, 1.0, v38
	v_add_f32_e32 v34, 1.0, v34
	v_add_f32_e32 v39, 1.0, v39
	v_add_f32_e32 v35, 1.0, v35
	v_add_f32_e32 v40, 1.0, v40
	v_add_f32_e32 v36, 1.0, v36
	v_add_f32_e32 v41, 1.0, v41
	v_add_f32_e32 v37, 1.0, v37
	v_rcp_f32_e32 v38, v38
	v_rcp_f32_e32 v34, v34
	v_rcp_f32_e32 v39, v39
	v_rcp_f32_e32 v35, v35
	v_rcp_f32_e32 v40, v40
	v_rcp_f32_e32 v36, v36
	v_rcp_f32_e32 v41, v41
	v_rcp_f32_e32 v37, v37
.LBB0_445:
	s_and_b64 vcc, exec, s[40:41]
	v_cvt_pk_bf16_f32 v38, v38, v39
	v_cvt_pk_bf16_f32 v39, v40, v41
	v_cvt_pk_bf16_f32 v40, v34, v35
	v_cvt_pk_bf16_f32 v41, v36, v37
	flat_store_dwordx4 v[50:51], v[38:41] offset:256 sc1
	s_cbranch_vccnz .LBB0_447
	v_mul_f32_e32 v30, 0xbfb8aa3b, v30
	v_mul_f32_e32 v26, 0xbfb8aa3b, v26
	v_mul_f32_e32 v31, 0xbfb8aa3b, v31
	v_mul_f32_e32 v27, 0xbfb8aa3b, v27
	v_mul_f32_e32 v32, 0xbfb8aa3b, v32
	v_mul_f32_e32 v28, 0xbfb8aa3b, v28
	v_mul_f32_e32 v33, 0xbfb8aa3b, v33
	v_mul_f32_e32 v29, 0xbfb8aa3b, v29
	v_exp_f32_e32 v30, v30
	v_exp_f32_e32 v26, v26
	v_exp_f32_e32 v31, v31
	v_exp_f32_e32 v27, v27
	v_exp_f32_e32 v32, v32
	v_exp_f32_e32 v28, v28
	v_exp_f32_e32 v33, v33
	v_exp_f32_e32 v29, v29
	v_add_f32_e32 v30, 1.0, v30
	v_add_f32_e32 v26, 1.0, v26
	v_add_f32_e32 v31, 1.0, v31
	v_add_f32_e32 v27, 1.0, v27
	v_add_f32_e32 v32, 1.0, v32
	v_add_f32_e32 v28, 1.0, v28
	v_add_f32_e32 v33, 1.0, v33
	v_add_f32_e32 v29, 1.0, v29
	v_rcp_f32_e32 v30, v30
	v_rcp_f32_e32 v26, v26
	v_rcp_f32_e32 v31, v31
	v_rcp_f32_e32 v27, v27
	v_rcp_f32_e32 v32, v32
	v_rcp_f32_e32 v28, v28
	v_rcp_f32_e32 v33, v33
	v_rcp_f32_e32 v29, v29
; __device__ __forceinline__ unsigned cvt_pk_bf16(float lo, float hi) { unsigned r; asm volatile("v_cvt_pk_bf16_f32 %0, %1, %2" : "=v"(r) : "v"(lo), "v"(hi)); return r; }
; __device__ __forceinline__ float fsig(float x) { return __builtin_amdgcn_rcpf(1.0f + __expf(-x)); }
; #define PG8_BAR __builtin_amdgcn_s_barrier()
;     __device__ __forceinline__ void operator()(const f32x4 (&acc)[2][2][4][2], const Unit& u, int wr, int wc, int fr, int fq) const {
;     ...
;             for (int m = 0; m < 4; ++m) { bf16_t* rowp = O + (size_t)(row0 + ai * HALF + m * 16) * LDP + col0;
; #pragma unroll
;                 for (int bj = 0; bj < 2; ++bj) { f32x4 v0 = acc[ai][bj][m][0], v1 = acc[ai][bj][m][1];
;                     if (act == 1) {
; #pragma unroll
;                         for (int j = 0; j < 4; ++j) { v0[j] = v0[j] * fsig(v0[j]); v1[j] = v1[j] * fsig(v1[j]); } }
;                     else if (act == 2) {
; #pragma unroll
;                         for (int j = 0; j < 4; ++j) { v0[j] = fsig(v0[j]); v1[j] = fsig(v1[j]); } }
;                     u32x4 w; w.x = cvt_pk_bf16(v0[0], v0[1]); w.y = cvt_pk_bf16(v0[2], v0[3]); w.z = cvt_pk_bf16(v1[0], v1[1]); w.w = cvt_pk_bf16(v1[2], v1[3]);
;                     *(u32x4*)(rowp + bj * HALF) = w; } }
; template <class Epi, class Sched, bool ALIGN_EPI = false, bool SP2 = false>
; __device__ __forceinline__ void gemm_phase(PG8_LAS unsigned char* lds, const Gemm g, const Sched& S, const Epi& E) {
;     ...
;         if (!has_next) break;
; #pragma unroll
;         for (int a = 0; a < 2; ++a)
; #pragma unroll
;             for (int b = 0; b < 2; ++b)
; #pragma unroll
;                 for (int m = 0; m < 4; ++m)
; #pragma unroll
;                     for (int n = 0; n < 2; ++n) acc[a][b][m][n] = (f32x4){0.f, 0.f, 0.f, 0.f};
;         cur = nxt; cA = nA; cB = nB; ++ui;
;         if constexpr (ALIGN_EPI) { if (wr == 1) PG8_BAR; }
.LBB0_447:
	v_add_u32_e32 v36, 0xa0, v159
	v_mov_b64_e32 v[34:35], s[42:43]
	v_mad_i64_i32 v[34:35], s[2:3], v36, s7, v[34:35]
	v_lshl_add_u64 v[34:35], v[152:153], 1, v[34:35]
	s_and_b64 vcc, exec, s[40:41]
	v_cvt_pk_bf16_f32 v30, v30, v31
	v_cvt_pk_bf16_f32 v31, v32, v33
	v_cvt_pk_bf16_f32 v32, v26, v27
	v_cvt_pk_bf16_f32 v33, v28, v29
	flat_store_dwordx4 v[34:35], v[30:33] sc1
	s_cbranch_vccnz .LBB0_449
	v_mul_f32_e32 v22, 0xbfb8aa3b, v22
	v_mul_f32_e32 v18, 0xbfb8aa3b, v18
	v_mul_f32_e32 v23, 0xbfb8aa3b, v23
	v_mul_f32_e32 v19, 0xbfb8aa3b, v19
	v_mul_f32_e32 v24, 0xbfb8aa3b, v24
	v_mul_f32_e32 v20, 0xbfb8aa3b, v20
	v_mul_f32_e32 v25, 0xbfb8aa3b, v25
	v_mul_f32_e32 v21, 0xbfb8aa3b, v21
	v_exp_f32_e32 v22, v22
	v_exp_f32_e32 v18, v18
	v_exp_f32_e32 v23, v23
	v_exp_f32_e32 v19, v19
	v_exp_f32_e32 v24, v24
	v_exp_f32_e32 v20, v20
	v_exp_f32_e32 v25, v25
	v_exp_f32_e32 v21, v21
	v_add_f32_e32 v22, 1.0, v22
	v_add_f32_e32 v18, 1.0, v18
	v_add_f32_e32 v23, 1.0, v23
	v_add_f32_e32 v19, 1.0, v19
	v_add_f32_e32 v24, 1.0, v24
	v_add_f32_e32 v20, 1.0, v20
	v_add_f32_e32 v25, 1.0, v25
	v_add_f32_e32 v21, 1.0, v21
	v_rcp_f32_e32 v22, v22
	v_rcp_f32_e32 v18, v18
	v_rcp_f32_e32 v23, v23
	v_rcp_f32_e32 v19, v19
	v_rcp_f32_e32 v24, v24
	v_rcp_f32_e32 v20, v20
	v_rcp_f32_e32 v25, v25
	v_rcp_f32_e32 v21, v21
.LBB0_449:
	s_and_b64 vcc, exec, s[40:41]
	v_cvt_pk_bf16_f32 v22, v22, v23
	v_cvt_pk_bf16_f32 v23, v24, v25
	v_cvt_pk_bf16_f32 v24, v18, v19
	v_cvt_pk_bf16_f32 v25, v20, v21
	flat_store_dwordx4 v[34:35], v[22:25] offset:256 sc1
	s_cbranch_vccnz .LBB0_451
	v_mul_f32_e32 v14, 0xbfb8aa3b, v14
	v_mul_f32_e32 v10, 0xbfb8aa3b, v10
	v_mul_f32_e32 v15, 0xbfb8aa3b, v15
	v_mul_f32_e32 v11, 0xbfb8aa3b, v11
	v_mul_f32_e32 v16, 0xbfb8aa3b, v16
	v_mul_f32_e32 v12, 0xbfb8aa3b, v12
	v_mul_f32_e32 v17, 0xbfb8aa3b, v17
	v_mul_f32_e32 v13, 0xbfb8aa3b, v13
	v_exp_f32_e32 v14, v14
	v_exp_f32_e32 v10, v10
	v_exp_f32_e32 v15, v15
	v_exp_f32_e32 v11, v11
	v_exp_f32_e32 v16, v16
	v_exp_f32_e32 v12, v12
	v_exp_f32_e32 v17, v17
	v_exp_f32_e32 v13, v13
	v_add_f32_e32 v14, 1.0, v14
	v_add_f32_e32 v10, 1.0, v10
	v_add_f32_e32 v15, 1.0, v15
	v_add_f32_e32 v11, 1.0, v11
	v_add_f32_e32 v16, 1.0, v16
	v_add_f32_e32 v12, 1.0, v12
	v_add_f32_e32 v17, 1.0, v17
	v_add_f32_e32 v13, 1.0, v13
	v_rcp_f32_e32 v14, v14
	v_rcp_f32_e32 v10, v10
	v_rcp_f32_e32 v15, v15
	v_rcp_f32_e32 v11, v11
	v_rcp_f32_e32 v16, v16
	v_rcp_f32_e32 v12, v12
	v_rcp_f32_e32 v17, v17
	v_rcp_f32_e32 v13, v13
.LBB0_451:
	v_add_u32_e32 v20, 0xb0, v159
	v_mov_b64_e32 v[18:19], s[42:43]
	v_mad_i64_i32 v[18:19], s[2:3], v20, s7, v[18:19]
	v_lshl_add_u64 v[18:19], v[152:153], 1, v[18:19]
	s_and_b64 vcc, exec, s[40:41]
	v_cvt_pk_bf16_f32 v14, v14, v15
	v_cvt_pk_bf16_f32 v15, v16, v17
	v_cvt_pk_bf16_f32 v16, v10, v11
	v_cvt_pk_bf16_f32 v17, v12, v13
	flat_store_dwordx4 v[18:19], v[14:17] sc1
	s_cbranch_vccnz .LBB0_453
	v_mul_f32_e32 v6, 0xbfb8aa3b, v6
	v_mul_f32_e32 v2, 0xbfb8aa3b, v2
	v_mul_f32_e32 v7, 0xbfb8aa3b, v7
	v_mul_f32_e32 v3, 0xbfb8aa3b, v3
	v_mul_f32_e32 v8, 0xbfb8aa3b, v8
	v_mul_f32_e32 v4, 0xbfb8aa3b, v4
	v_mul_f32_e32 v9, 0xbfb8aa3b, v9
	v_mul_f32_e32 v5, 0xbfb8aa3b, v5
	v_exp_f32_e32 v6, v6
	v_exp_f32_e32 v2, v2
	v_exp_f32_e32 v7, v7
	v_exp_f32_e32 v3, v3
	v_exp_f32_e32 v8, v8
	v_exp_f32_e32 v4, v4
	v_exp_f32_e32 v9, v9
	v_exp_f32_e32 v5, v5
	v_add_f32_e32 v6, 1.0, v6
	v_add_f32_e32 v2, 1.0, v2
	v_add_f32_e32 v7, 1.0, v7
	v_add_f32_e32 v3, 1.0, v3
	v_add_f32_e32 v8, 1.0, v8
	v_add_f32_e32 v4, 1.0, v4
	v_add_f32_e32 v9, 1.0, v9
	v_add_f32_e32 v5, 1.0, v5
	v_rcp_f32_e32 v6, v6
	v_rcp_f32_e32 v2, v2
	v_rcp_f32_e32 v7, v7
	v_rcp_f32_e32 v3, v3
	v_rcp_f32_e32 v8, v8
	v_rcp_f32_e32 v4, v4
	v_rcp_f32_e32 v9, v9
	v_rcp_f32_e32 v5, v5
.LBB0_453:
	s_andn2_b64 vcc, exec, s[38:39]
	s_mov_b64 s[2:3], -1
	v_cvt_pk_bf16_f32 v6, v6, v7
	v_cvt_pk_bf16_f32 v7, v8, v9
	v_cvt_pk_bf16_f32 v8, v2, v3
	v_cvt_pk_bf16_f32 v9, v4, v5
	flat_store_dwordx4 v[18:19], v[6:9] offset:256 sc1
	s_cbranch_vccnz .LBB0_414
	s_andn2_b64 vcc, exec, s[0:1]
	s_cbranch_vccnz .LBB0_413
	s_barrier
	s_branch .LBB0_413

; __device__ __forceinline__ unsigned cvt_pk_bf16(float lo, float hi) { unsigned r; asm volatile("v_cvt_pk_bf16_f32 %0, %1, %2" : "=v"(r) : "v"(lo), "v"(hi)); return r; }
; #define LAS __attribute__((address_space(3)))
; #define LDS_WAIT() asm volatile("s_waitcnt lgkmcnt(0)" ::: "memory")
;     ...
;     for (int i = 0; i < 32; ++i) { const int kk = 2 * i + (lane >> 5); scr[kk * 33 + (lane & 31)] = W[(size_t)(k0 + kk) * N + n0 + (lane & 31)]; }
;     LDS_WAIT(); asm volatile("" ::: "memory");
;     const int c = lane & 7;
; #pragma unroll
;     for (int j = 0; j < 4; ++j) { const int n = (lane >> 3) + 8 * j; const LAS float* s = scr + (8 * c) * 33 + n;
;         u32x4 o; o.x = cvt_pk_bf16(s[0 * 33], s[1 * 33]); o.y = cvt_pk_bf16(s[2 * 33], s[3 * 33]); o.z = cvt_pk_bf16(s[4 * 33], s[5 * 33]); o.w = cvt_pk_bf16(s[6 * 33], s[7 * 33]);
;         *(u32x4*)(WT + (size_t)(dn0 + n) * ldo + koff + k0 + 8 * c) = o; }
;     LDS_WAIT(); asm volatile("" ::: "memory");
; __device__ __forceinline__ void phase_convert(const Args& a, LAS unsigned char* lds) {
;     ...
;         if (r < 32) { transpose_item(a.in[I_W2] + (size_t)l * 64 * DA, 64, DA, (bf16*)(ws + WS_W2T) + (size_t)l * DA * 64, 1 << 30, scr, r, lane); continue; } r -= 32;
.LBB0_475:
	s_lshl_b32 s45, s3, 1
	s_lshl_b32 s46, s43, 1
	v_or_b32_e32 v0, s46, v2
	s_add_i32 s48, s45, 4
	s_add_i32 s49, s46, 4
	v_mov_b32_e32 v23, v1
	s_add_i32 s50, s45, 8
	s_add_i32 s51, s46, 8
	s_add_i32 s53, s46, 12
	s_add_i32 s55, s46, 16
	s_add_i32 s56, s45, 20
	s_add_i32 s57, s46, 20
	s_add_i32 s58, s45, 24
	s_add_i32 s59, s46, 24
	s_add_i32 s60, s46, 28
	v_lshlrev_b64 v[40:41], 12, v[0:1]
	v_mad_u64_u32 v[42:43], s[46:47], v0, s85, v[6:7]
	v_or_b32_e32 v22, s48, v3
	v_or_b32_e32 v0, s49, v2
	v_mov_b32_e32 v17, v1
	v_mov_b32_e32 v25, v1
	v_mov_b32_e32 v31, v1
	v_mov_b32_e32 v33, v1
	v_or_b32_e32 v16, s45, v3
	s_add_i32 s52, s45, 12
	s_add_i32 s54, s45, 16
	s_add_i32 s45, s45, 28
	v_or_b32_e32 v24, s50, v3
	v_or_b32_e32 v30, s56, v3
	v_or_b32_e32 v32, s58, v3
	v_lshlrev_b64 v[44:45], 12, v[22:23]
	v_lshlrev_b64 v[46:47], 12, v[0:1]
	v_mad_u64_u32 v[48:49], s[46:47], v0, s85, v[6:7]
	v_or_b32_e32 v0, s51, v2
	v_mov_b32_e32 v27, v1
	v_mov_b32_e32 v29, v1
	v_mov_b32_e32 v35, v1
	v_lshlrev_b64 v[36:37], 12, v[16:17]
	v_or_b32_e32 v26, s52, v3
	v_or_b32_e32 v28, s54, v3
	v_or_b32_e32 v34, s45, v3
	v_lshl_add_u64 v[40:41], v[14:15], 0, v[40:41]
	v_lshlrev_b64 v[50:51], 12, v[24:25]
	v_lshlrev_b64 v[56:57], 12, v[30:31]
	v_lshlrev_b64 v[58:59], 12, v[32:33]
	v_lshl_add_u64 v[44:45], v[14:15], 0, v[44:45]
	v_lshlrev_b64 v[62:63], 12, v[0:1]
	v_mad_u64_u32 v[64:65], s[46:47], v0, s85, v[6:7]
	v_or_b32_e32 v0, s53, v2
	v_lshl_add_u64 v[36:37], v[14:15], 0, v[36:37]
	v_lshlrev_b64 v[52:53], 12, v[26:27]
	v_lshlrev_b64 v[54:55], 12, v[28:29]
	v_lshlrev_b64 v[60:61], 12, v[34:35]
	v_lshl_add_u64 v[46:47], v[14:15], 0, v[46:47]
	v_lshl_add_u64 v[50:51], v[14:15], 0, v[50:51]
	v_lshl_add_u64 v[56:57], v[14:15], 0, v[56:57]
	v_lshl_add_u64 v[58:59], v[14:15], 0, v[58:59]
	global_load_dword v5, v[40:41], off
	global_load_dword v21, v[36:37], off
	global_load_dword v39, v[46:47], off
	global_load_dword v43, v[44:45], off
	v_lshlrev_b64 v[40:41], 12, v[0:1]
	v_mad_u64_u32 v[44:45], s[46:47], v0, s85, v[6:7]
	v_or_b32_e32 v0, s55, v2
	v_lshl_add_u64 v[52:53], v[14:15], 0, v[52:53]
	v_lshl_add_u64 v[54:55], v[14:15], 0, v[54:55]
	v_lshl_add_u64 v[60:61], v[14:15], 0, v[60:61]
	v_lshl_add_u64 v[36:37], v[14:15], 0, v[62:63]
	global_load_dword v45, v[50:51], off
	global_load_dword v49, v[52:53], off
	global_load_dword v62, v[54:55], off
	s_nop 0
	global_load_dword v56, v[56:57], off
	s_nop 0
	global_load_dword v57, v[58:59], off
	s_nop 0
	global_load_dword v58, v[60:61], off
	v_lshl_add_u64 v[40:41], v[14:15], 0, v[40:41]
	v_lshlrev_b64 v[46:47], 12, v[0:1]
	v_mad_u64_u32 v[50:51], s[46:47], v0, s85, v[6:7]
	v_or_b32_e32 v0, s57, v2
	global_load_dword v51, v[36:37], off
	global_load_dword v59, v[40:41], off
	v_lshl_add_u64 v[36:37], v[14:15], 0, v[46:47]
	v_lshlrev_b64 v[40:41], 12, v[0:1]
	v_mad_u64_u32 v[46:47], s[46:47], v0, s85, v[6:7]
	v_or_b32_e32 v0, s59, v2
	v_mad_u64_u32 v[54:55], s[46:47], v0, s85, v[6:7]
	v_lshl_add_u64 v[40:41], v[14:15], 0, v[40:41]
	global_load_dword v47, v[36:37], off
	global_load_dword v55, v[40:41], off
	v_lshlrev_b64 v[52:53], 12, v[0:1]
	v_or_b32_e32 v0, s60, v2
	v_lshl_add_u64 v[36:37], v[14:15], 0, v[52:53]
	v_lshlrev_b64 v[40:41], 12, v[0:1]
	global_load_dword v52, v[36:37], off
	v_lshl_add_u64 v[36:37], v[14:15], 0, v[40:41]
	global_load_dword v40, v[36:37], off
	s_add_i32 s43, s43, 16
	s_add_i32 s3, s3, 16
	s_add_i32 s44, s44, -16
	s_cmp_lg_u32 s44, 0
	v_mad_u64_u32 v[16:17], s[46:47], v16, s85, v[6:7]
	v_mad_u64_u32 v[22:23], s[46:47], v22, s85, v[6:7]
	v_mad_u64_u32 v[24:25], s[46:47], v24, s85, v[6:7]
	v_mad_u64_u32 v[26:27], s[46:47], v26, s85, v[6:7]
	v_mad_u64_u32 v[28:29], s[46:47], v28, s85, v[6:7]
	v_mad_u64_u32 v[30:31], s[46:47], v30, s85, v[6:7]
	v_mad_u64_u32 v[32:33], s[46:47], v32, s85, v[6:7]
	v_mad_u64_u32 v[34:35], s[46:47], v34, s85, v[6:7]
	v_mad_u64_u32 v[36:37], s[46:47], v0, s85, v[6:7]
	s_waitcnt vmcnt(15)
	ds_write_b32 v42, v5
	s_waitcnt vmcnt(14)
	ds_write_b32 v16, v21
	s_waitcnt vmcnt(13)
	ds_write_b32 v48, v39
	s_waitcnt vmcnt(12)
	ds_write_b32 v22, v43
	s_waitcnt vmcnt(5)
	ds_write_b32 v64, v51
	ds_write_b32 v24, v45
	s_waitcnt vmcnt(4)
	ds_write_b32 v44, v59
	ds_write_b32 v26, v49
	s_waitcnt vmcnt(3)
	ds_write_b32 v50, v47
	ds_write_b32 v28, v62
	s_waitcnt vmcnt(2)
	ds_write_b32 v46, v55
	ds_write_b32 v30, v56
	s_waitcnt vmcnt(1)
	ds_write_b32 v54, v52
	ds_write_b32 v32, v57
	s_waitcnt vmcnt(0)
	ds_write_b32 v36, v40
	ds_write_b32 v34, v58
	s_cbranch_scc1 .LBB0_475
	s_waitcnt lgkmcnt(0)
	ds_read2_b32 v[14:15], v9 offset1:33
	s_waitcnt lgkmcnt(0)
	v_cvt_pk_bf16_f32 v14, v14, v15
	ds_read2_b32 v[16:17], v9 offset0:66 offset1:99
	s_lshl_b64 s[44:45], s[0:1], 17
	v_or_b32_e32 v0, s2, v7
	s_waitcnt lgkmcnt(0)
	v_cvt_pk_bf16_f32 v15, v16, v17
	ds_read2_b32 v[16:17], v9 offset0:132 offset1:165
	v_lshl_add_u64 v[24:25], v[10:11], 0, s[44:45]
	v_lshlrev_b32_e32 v0, 7, v0
	s_waitcnt lgkmcnt(0)
	v_cvt_pk_bf16_f32 v16, v16, v17
	ds_read2_b32 v[22:23], v9 offset0:198 offset1:231
	s_waitcnt lgkmcnt(0)
	v_cvt_pk_bf16_f32 v17, v22, v23
	v_lshl_add_u64 v[26:27], v[24:25], 0, v[0:1]
	ds_read2_b32 v[22:23], v9 offset0:8 offset1:41
	global_store_dwordx4 v[26:27], v[14:17], off sc1
	v_or_b32_e32 v0, s2, v18
	v_lshlrev_b32_e32 v0, 7, v0
	s_waitcnt lgkmcnt(0)
	v_cvt_pk_bf16_f32 v14, v22, v23
	ds_read2_b32 v[16:17], v9 offset0:74 offset1:107
	s_waitcnt lgkmcnt(0)
	v_cvt_pk_bf16_f32 v15, v16, v17
	ds_read2_b32 v[16:17], v9 offset0:140 offset1:173
	s_waitcnt lgkmcnt(0)
	v_cvt_pk_bf16_f32 v16, v16, v17
	ds_read2_b32 v[22:23], v9 offset0:206 offset1:239
	s_waitcnt lgkmcnt(0)
	v_cvt_pk_bf16_f32 v17, v22, v23
	v_lshl_add_u64 v[26:27], v[24:25], 0, v[0:1]
	ds_read2_b32 v[22:23], v9 offset0:16 offset1:49
	global_store_dwordx4 v[26:27], v[14:17], off sc1
	v_or_b32_e32 v0, s2, v19
	v_lshlrev_b32_e32 v0, 7, v0
	s_waitcnt lgkmcnt(0)
	v_cvt_pk_bf16_f32 v14, v22, v23
	ds_read2_b32 v[16:17], v9 offset0:82 offset1:115
	s_waitcnt lgkmcnt(0)
	v_cvt_pk_bf16_f32 v15, v16, v17
	ds_read2_b32 v[16:17], v9 offset0:148 offset1:181
	s_waitcnt lgkmcnt(0)
	v_cvt_pk_bf16_f32 v16, v16, v17
	ds_read2_b32 v[22:23], v9 offset0:214 offset1:247
	s_waitcnt lgkmcnt(0)
	v_cvt_pk_bf16_f32 v17, v22, v23
	v_lshl_add_u64 v[26:27], v[24:25], 0, v[0:1]
	ds_read2_b32 v[22:23], v9 offset0:24 offset1:57
	global_store_dwordx4 v[26:27], v[14:17], off sc1
	v_or_b32_e32 v0, s2, v20
	v_lshlrev_b32_e32 v0, 7, v0
	s_waitcnt lgkmcnt(0)
	v_cvt_pk_bf16_f32 v14, v22, v23
	ds_read2_b32 v[16:17], v9 offset0:90 offset1:123
	s_waitcnt lgkmcnt(0)
	v_cvt_pk_bf16_f32 v15, v16, v17
	ds_read2_b32 v[16:17], v9 offset0:156 offset1:189
	s_waitcnt lgkmcnt(0)
	v_cvt_pk_bf16_f32 v16, v16, v17
	ds_read2_b32 v[22:23], v9 offset0:222 offset1:255
	s_waitcnt lgkmcnt(0)
	v_cvt_pk_bf16_f32 v17, v22, v23
	v_lshl_add_u64 v[22:23], v[24:25], 0, v[0:1]
	global_store_dwordx4 v[22:23], v[14:17], off sc1
	s_waitcnt lgkmcnt(0)
	v_readlane_b32 s70, v253, 44
	s_mov_b64 s[2:3], 0
	v_readlane_b32 s71, v253, 45
	s_mov_b32 s48, 0x3a000000

; __device__ __forceinline__ unsigned cvt_pk_bf16(float lo, float hi) { unsigned r; asm volatile("v_cvt_pk_bf16_f32 %0, %1, %2" : "=v"(r) : "v"(lo), "v"(hi)); return r; }
; #define LAS __attribute__((address_space(3)))
; #define LDS_WAIT() asm volatile("s_waitcnt lgkmcnt(0)" ::: "memory")
;     ...
;     for (int i = 0; i < 32; ++i) { const int kk = 2 * i + (lane >> 5); scr[kk * 33 + (lane & 31)] = W[(size_t)(k0 + kk) * N + n0 + (lane & 31)]; }
;     LDS_WAIT(); asm volatile("" ::: "memory");
;     const int c = lane & 7;
; #pragma unroll
;     for (int j = 0; j < 4; ++j) { const int n = (lane >> 3) + 8 * j; const LAS float* s = scr + (8 * c) * 33 + n;
;         u32x4 o; o.x = cvt_pk_bf16(s[0 * 33], s[1 * 33]); o.y = cvt_pk_bf16(s[2 * 33], s[3 * 33]); o.z = cvt_pk_bf16(s[4 * 33], s[5 * 33]); o.w = cvt_pk_bf16(s[6 * 33], s[7 * 33]);
;         *(u32x4*)(WT + (size_t)(dn0 + n) * ldo + koff + k0 + 8 * c) = o; }
;     LDS_WAIT(); asm volatile("" ::: "memory");
; __device__ __forceinline__ void phase_convert(const Args& a, LAS unsigned char* lds) {
;     ...
;         transpose_item(a.in[I_A2] + (size_t)l * 64 * DA, 64, DA, (bf16*)(ws + WS_A2T) + (size_t)l * DA * 64, 1 << 30, scr, r, lane);
.LBB0_479:
	s_lshl_b32 s41, s3, 1
	s_lshl_b32 s43, s38, 1
	v_or_b32_e32 v0, s43, v2
	s_add_i32 s46, s41, 4
	s_add_i32 s47, s43, 4
	v_mov_b32_e32 v23, v1
	s_add_i32 s48, s41, 8
	s_add_i32 s49, s43, 8
	s_add_i32 s54, s41, 20
	s_add_i32 s56, s41, 24
	v_lshlrev_b64 v[40:41], 12, v[0:1]
	v_mad_u64_u32 v[42:43], s[44:45], v0, s85, v[6:7]
	v_or_b32_e32 v22, s46, v3
	v_or_b32_e32 v0, s47, v2
	v_mov_b32_e32 v17, v1
	v_mov_b32_e32 v25, v1
	v_mov_b32_e32 v31, v1
	v_mov_b32_e32 v33, v1
	v_or_b32_e32 v16, s41, v3
	s_add_i32 s50, s41, 12
	s_add_i32 s51, s43, 12
	s_add_i32 s52, s41, 16
	s_add_i32 s41, s41, 28
	v_or_b32_e32 v24, s48, v3
	v_or_b32_e32 v30, s54, v3
	v_or_b32_e32 v32, s56, v3
	v_lshlrev_b64 v[44:45], 12, v[22:23]
	v_lshlrev_b64 v[46:47], 12, v[0:1]
	v_mad_u64_u32 v[48:49], s[44:45], v0, s85, v[6:7]
	v_or_b32_e32 v0, s49, v2
	v_mov_b32_e32 v27, v1
	v_mov_b32_e32 v29, v1
	v_mov_b32_e32 v35, v1
	s_add_i32 s53, s43, 16
	v_lshlrev_b64 v[36:37], 12, v[16:17]
	v_or_b32_e32 v26, s50, v3
	v_or_b32_e32 v28, s52, v3
	v_or_b32_e32 v34, s41, v3
	v_lshl_add_u64 v[40:41], v[14:15], 0, v[40:41]
	v_lshlrev_b64 v[50:51], 12, v[24:25]
	v_lshlrev_b64 v[56:57], 12, v[30:31]
	v_lshlrev_b64 v[58:59], 12, v[32:33]
	v_lshl_add_u64 v[44:45], v[14:15], 0, v[44:45]
	v_lshlrev_b64 v[62:63], 12, v[0:1]
	v_mad_u64_u32 v[64:65], s[44:45], v0, s85, v[6:7]
	v_or_b32_e32 v0, s51, v2
	s_add_i32 s55, s43, 20
	v_lshl_add_u64 v[36:37], v[14:15], 0, v[36:37]
	v_lshlrev_b64 v[52:53], 12, v[26:27]
	v_lshlrev_b64 v[54:55], 12, v[28:29]
	v_lshlrev_b64 v[60:61], 12, v[34:35]
	v_lshl_add_u64 v[46:47], v[14:15], 0, v[46:47]
	v_lshl_add_u64 v[50:51], v[14:15], 0, v[50:51]
	v_lshl_add_u64 v[56:57], v[14:15], 0, v[56:57]
	v_lshl_add_u64 v[58:59], v[14:15], 0, v[58:59]
	global_load_dword v5, v[40:41], off
	global_load_dword v21, v[36:37], off
	global_load_dword v39, v[46:47], off
	global_load_dword v43, v[44:45], off
	v_lshlrev_b64 v[40:41], 12, v[0:1]
	v_mad_u64_u32 v[44:45], s[44:45], v0, s85, v[6:7]
	v_or_b32_e32 v0, s53, v2
	s_add_i32 s57, s43, 24
	v_lshl_add_u64 v[52:53], v[14:15], 0, v[52:53]
	v_lshl_add_u64 v[54:55], v[14:15], 0, v[54:55]
	v_lshl_add_u64 v[60:61], v[14:15], 0, v[60:61]
	v_lshl_add_u64 v[36:37], v[14:15], 0, v[62:63]
	global_load_dword v45, v[50:51], off
	global_load_dword v49, v[52:53], off
	global_load_dword v62, v[54:55], off
	s_nop 0
	global_load_dword v56, v[56:57], off
	s_nop 0
	global_load_dword v57, v[58:59], off
	s_nop 0
	global_load_dword v58, v[60:61], off
	v_lshl_add_u64 v[40:41], v[14:15], 0, v[40:41]
	v_lshlrev_b64 v[46:47], 12, v[0:1]
	v_mad_u64_u32 v[50:51], s[44:45], v0, s85, v[6:7]
	v_or_b32_e32 v0, s55, v2
	global_load_dword v51, v[36:37], off
	global_load_dword v59, v[40:41], off
	v_lshl_add_u64 v[36:37], v[14:15], 0, v[46:47]
	v_lshlrev_b64 v[40:41], 12, v[0:1]
	v_mad_u64_u32 v[46:47], s[44:45], v0, s85, v[6:7]
	v_or_b32_e32 v0, s57, v2
	v_mad_u64_u32 v[54:55], s[44:45], v0, s85, v[6:7]
	v_lshl_add_u64 v[40:41], v[14:15], 0, v[40:41]
	global_load_dword v47, v[36:37], off
	global_load_dword v55, v[40:41], off
	s_add_i32 s43, s43, 28
	v_lshlrev_b64 v[52:53], 12, v[0:1]
	v_or_b32_e32 v0, s43, v2
	v_lshl_add_u64 v[36:37], v[14:15], 0, v[52:53]
	v_lshlrev_b64 v[40:41], 12, v[0:1]
	global_load_dword v52, v[36:37], off
	v_lshl_add_u64 v[36:37], v[14:15], 0, v[40:41]
	global_load_dword v40, v[36:37], off
	s_add_i32 s38, s38, 16
	s_add_i32 s3, s3, 16
	s_add_i32 s39, s39, -16
	s_cmp_lg_u32 s39, 0
	v_mad_u64_u32 v[16:17], s[44:45], v16, s85, v[6:7]
	v_mad_u64_u32 v[22:23], s[44:45], v22, s85, v[6:7]
	v_mad_u64_u32 v[24:25], s[44:45], v24, s85, v[6:7]
	v_mad_u64_u32 v[26:27], s[44:45], v26, s85, v[6:7]
	v_mad_u64_u32 v[28:29], s[44:45], v28, s85, v[6:7]
	v_mad_u64_u32 v[30:31], s[44:45], v30, s85, v[6:7]
	v_mad_u64_u32 v[32:33], s[44:45], v32, s85, v[6:7]
	v_mad_u64_u32 v[34:35], s[44:45], v34, s85, v[6:7]
	v_mad_u64_u32 v[36:37], s[44:45], v0, s85, v[6:7]
	s_waitcnt vmcnt(15)
	ds_write_b32 v42, v5
	s_waitcnt vmcnt(14)
	ds_write_b32 v16, v21
	s_waitcnt vmcnt(13)
	ds_write_b32 v48, v39
	s_waitcnt vmcnt(12)
	ds_write_b32 v22, v43
	s_waitcnt vmcnt(5)
	ds_write_b32 v64, v51
	ds_write_b32 v24, v45
	s_waitcnt vmcnt(4)
	ds_write_b32 v44, v59
	ds_write_b32 v26, v49
	s_waitcnt vmcnt(3)
	ds_write_b32 v50, v47
	ds_write_b32 v28, v62
	s_waitcnt vmcnt(2)
	ds_write_b32 v46, v55
	ds_write_b32 v30, v56
	s_waitcnt vmcnt(1)
	ds_write_b32 v54, v52
	ds_write_b32 v32, v57
	s_waitcnt vmcnt(0)
	ds_write_b32 v36, v40
	ds_write_b32 v34, v58
	s_cbranch_scc1 .LBB0_479
	s_waitcnt lgkmcnt(0)
	ds_read2_b32 v[14:15], v9 offset1:33
	s_waitcnt lgkmcnt(0)
	v_cvt_pk_bf16_f32 v14, v14, v15
	ds_read2_b32 v[16:17], v9 offset0:66 offset1:99
	s_lshl_b64 s[38:39], s[0:1], 17
	v_or_b32_e32 v0, s2, v7
	s_waitcnt lgkmcnt(0)
	v_cvt_pk_bf16_f32 v15, v16, v17
	ds_read2_b32 v[16:17], v9 offset0:132 offset1:165
	v_lshl_add_u64 v[24:25], v[12:13], 0, s[38:39]
	v_lshlrev_b32_e32 v0, 7, v0
	s_waitcnt lgkmcnt(0)
	v_cvt_pk_bf16_f32 v16, v16, v17
	ds_read2_b32 v[22:23], v9 offset0:198 offset1:231
	s_waitcnt lgkmcnt(0)
	v_cvt_pk_bf16_f32 v17, v22, v23
	v_lshl_add_u64 v[26:27], v[24:25], 0, v[0:1]
	ds_read2_b32 v[22:23], v9 offset0:8 offset1:41
	global_store_dwordx4 v[26:27], v[14:17], off sc1
	v_or_b32_e32 v0, s2, v18
	v_lshlrev_b32_e32 v0, 7, v0
	s_waitcnt lgkmcnt(0)
	v_cvt_pk_bf16_f32 v14, v22, v23
	ds_read2_b32 v[16:17], v9 offset0:74 offset1:107
	s_waitcnt lgkmcnt(0)
	v_cvt_pk_bf16_f32 v15, v16, v17
	ds_read2_b32 v[16:17], v9 offset0:140 offset1:173
	s_waitcnt lgkmcnt(0)
	v_cvt_pk_bf16_f32 v16, v16, v17
	ds_read2_b32 v[22:23], v9 offset0:206 offset1:239
	s_waitcnt lgkmcnt(0)
	v_cvt_pk_bf16_f32 v17, v22, v23
	v_lshl_add_u64 v[26:27], v[24:25], 0, v[0:1]
	ds_read2_b32 v[22:23], v9 offset0:16 offset1:49
	global_store_dwordx4 v[26:27], v[14:17], off sc1
	v_or_b32_e32 v0, s2, v19
	v_lshlrev_b32_e32 v0, 7, v0
	s_waitcnt lgkmcnt(0)
	v_cvt_pk_bf16_f32 v14, v22, v23
	ds_read2_b32 v[16:17], v9 offset0:82 offset1:115
	s_waitcnt lgkmcnt(0)
	v_cvt_pk_bf16_f32 v15, v16, v17
	ds_read2_b32 v[16:17], v9 offset0:148 offset1:181
	s_waitcnt lgkmcnt(0)
	v_cvt_pk_bf16_f32 v16, v16, v17
	ds_read2_b32 v[22:23], v9 offset0:214 offset1:247
	s_waitcnt lgkmcnt(0)
	v_cvt_pk_bf16_f32 v17, v22, v23
	v_lshl_add_u64 v[26:27], v[24:25], 0, v[0:1]
	ds_read2_b32 v[22:23], v9 offset0:24 offset1:57
	global_store_dwordx4 v[26:27], v[14:17], off sc1
	v_or_b32_e32 v0, s2, v20
	v_lshlrev_b32_e32 v0, 7, v0
	s_waitcnt lgkmcnt(0)
	v_cvt_pk_bf16_f32 v14, v22, v23
	ds_read2_b32 v[16:17], v9 offset0:90 offset1:123
	s_waitcnt lgkmcnt(0)
	v_cvt_pk_bf16_f32 v15, v16, v17
	ds_read2_b32 v[16:17], v9 offset0:156 offset1:189
	s_waitcnt lgkmcnt(0)
	v_cvt_pk_bf16_f32 v16, v16, v17
	ds_read2_b32 v[22:23], v9 offset0:222 offset1:255
	s_waitcnt lgkmcnt(0)
	v_cvt_pk_bf16_f32 v17, v22, v23
	v_lshl_add_u64 v[22:23], v[24:25], 0, v[0:1]
	global_store_dwordx4 v[22:23], v[14:17], off sc1
	s_waitcnt lgkmcnt(0)
	s_mov_b32 s48, 0x3a000000

;     ...
; #pragma unroll 8
;     for (int i = 0; i < 32; ++i) { const int kk = 2 * i + (lane >> 5); scr[kk * 33 + (lane & 31)] = W[(size_t)(k0 + kk) * N + n0 + (lane & 31)]; }
.LBB0_484:
	s_lshl_b32 s46, s43, 1
	s_lshl_b32 s45, s41, 1
	v_or_b32_e32 v0, s46, v16
	s_add_i32 s49, s46, 4
	s_add_i32 s48, s45, 4
	s_add_i32 s50, s45, 8
	s_add_i32 s51, s46, 8
	v_lshlrev_b64 v[40:41], 13, v[0:1]
	v_or_b32_e32 v0, s49, v16
	v_mov_b32_e32 v23, v1
	v_mov_b32_e32 v25, v1
	v_mov_b32_e32 v27, v1
	v_or_b32_e32 v22, s45, v5
	s_add_i32 s52, s45, 12
	s_add_i32 s53, s46, 12
	s_add_i32 s54, s45, 16
	s_add_i32 s56, s45, 20
	s_add_i32 s58, s45, 24
	s_add_i32 s60, s45, 28
	v_or_b32_e32 v24, s48, v5
	v_or_b32_e32 v26, s50, v5
	v_lshlrev_b64 v[42:43], 13, v[0:1]
	v_or_b32_e32 v0, s51, v16
	v_mov_b32_e32 v29, v1
	v_mov_b32_e32 v31, v1
	v_mov_b32_e32 v33, v1
	v_mov_b32_e32 v35, v1
	v_mov_b32_e32 v37, v1
	s_add_i32 s55, s46, 16
	v_lshlrev_b64 v[22:23], 13, v[22:23]
	v_or_b32_e32 v28, s52, v5
	v_or_b32_e32 v30, s54, v5
	v_or_b32_e32 v32, s56, v5
	v_or_b32_e32 v34, s58, v5
	v_or_b32_e32 v36, s60, v5
	v_lshl_add_u64 v[40:41], v[14:15], 0, v[40:41]
	v_lshlrev_b64 v[24:25], 13, v[24:25]
	v_lshlrev_b64 v[26:27], 13, v[26:27]
	v_lshlrev_b64 v[44:45], 13, v[0:1]
	v_or_b32_e32 v0, s53, v16
	s_add_i32 s57, s46, 20
	v_lshl_add_u64 v[22:23], v[14:15], 0, v[22:23]
	v_lshlrev_b64 v[28:29], 13, v[28:29]
	v_lshlrev_b64 v[30:31], 13, v[30:31]
	v_lshlrev_b64 v[32:33], 13, v[32:33]
	v_lshlrev_b64 v[34:35], 13, v[34:35]
	v_lshlrev_b64 v[36:37], 13, v[36:37]
	v_lshl_add_u64 v[42:43], v[14:15], 0, v[42:43]
	v_lshl_add_u64 v[24:25], v[14:15], 0, v[24:25]
	v_lshl_add_u64 v[26:27], v[14:15], 0, v[26:27]
	global_load_dword v17, v[40:41], off
	global_load_dword v21, v[22:23], off
	v_lshlrev_b64 v[40:41], 13, v[0:1]
	v_or_b32_e32 v0, s55, v16
	s_add_i32 s59, s46, 24
	v_lshl_add_u64 v[28:29], v[14:15], 0, v[28:29]
	v_lshl_add_u64 v[30:31], v[14:15], 0, v[30:31]
	v_lshl_add_u64 v[32:33], v[14:15], 0, v[32:33]
	v_lshl_add_u64 v[34:35], v[14:15], 0, v[34:35]
	v_lshl_add_u64 v[36:37], v[14:15], 0, v[36:37]
	global_load_dword v39, v[42:43], off
	global_load_dword v56, v[24:25], off
	global_load_dword v57, v[26:27], off
	global_load_dword v58, v[28:29], off
	global_load_dword v59, v[30:31], off
	global_load_dword v60, v[32:33], off
	global_load_dword v61, v[34:35], off
	global_load_dword v62, v[36:37], off
	v_lshl_add_u64 v[24:25], v[14:15], 0, v[40:41]
	v_lshlrev_b64 v[26:27], 13, v[0:1]
	v_or_b32_e32 v0, s57, v16
	s_add_i32 s61, s46, 28
	v_lshl_add_u64 v[22:23], v[14:15], 0, v[44:45]
	global_load_dword v63, v[24:25], off
	global_load_dword v64, v[22:23], off
	v_lshlrev_b64 v[24:25], 13, v[0:1]
	v_or_b32_e32 v0, s59, v16
	v_lshl_add_u64 v[22:23], v[14:15], 0, v[26:27]
	v_lshlrev_b64 v[26:27], 13, v[0:1]
	v_or_b32_e32 v0, s61, v16
	v_lshlrev_b64 v[28:29], 13, v[0:1]
	v_lshl_add_u64 v[28:29], v[14:15], 0, v[28:29]
	v_lshl_add_u64 v[24:25], v[14:15], 0, v[24:25]
	v_lshl_add_u64 v[26:27], v[14:15], 0, v[26:27]
	global_load_dword v0, v[28:29], off
	global_load_dword v65, v[26:27], off
	global_load_dword v66, v[24:25], off
	global_load_dword v67, v[22:23], off
	v_or_b32_e32 v24, s45, v3
	v_or_b32_e32 v22, s46, v2
	s_add_i32 s43, s43, 16
	s_add_i32 s41, s41, 16
	s_add_i32 s44, s44, -16
	v_mad_u64_u32 v[22:23], s[46:47], v22, s85, v[6:7]
	v_mad_u64_u32 v[24:25], s[46:47], v24, s85, v[6:7]
	v_or_b32_e32 v23, s48, v3
	v_or_b32_e32 v25, s49, v2
	v_or_b32_e32 v32, s50, v3
	v_or_b32_e32 v30, s51, v2
	v_or_b32_e32 v36, s52, v3
	v_or_b32_e32 v34, s53, v2
	v_or_b32_e32 v42, s54, v3
	v_or_b32_e32 v40, s55, v2
	v_or_b32_e32 v46, s56, v3
	v_or_b32_e32 v44, s57, v2
	v_or_b32_e32 v50, s58, v3
	v_or_b32_e32 v48, s59, v2
	v_or_b32_e32 v54, s60, v3
	v_or_b32_e32 v52, s61, v2
	s_cmp_lg_u32 s44, 0
	v_mad_u64_u32 v[26:27], s[46:47], v25, s85, v[6:7]
	v_mad_u64_u32 v[28:29], s[46:47], v23, s85, v[6:7]
	v_mad_u64_u32 v[30:31], s[46:47], v30, s85, v[6:7]
	v_mad_u64_u32 v[32:33], s[46:47], v32, s85, v[6:7]
	v_mad_u64_u32 v[34:35], s[46:47], v34, s85, v[6:7]
	v_mad_u64_u32 v[36:37], s[46:47], v36, s85, v[6:7]
	v_mad_u64_u32 v[40:41], s[46:47], v40, s85, v[6:7]
	v_mad_u64_u32 v[42:43], s[46:47], v42, s85, v[6:7]
	v_mad_u64_u32 v[44:45], s[46:47], v44, s85, v[6:7]
	v_mad_u64_u32 v[46:47], s[46:47], v46, s85, v[6:7]
	v_mad_u64_u32 v[48:49], s[46:47], v48, s85, v[6:7]
	v_mad_u64_u32 v[50:51], s[46:47], v50, s85, v[6:7]
	v_mad_u64_u32 v[52:53], s[46:47], v52, s85, v[6:7]
	v_mad_u64_u32 v[54:55], s[46:47], v54, s85, v[6:7]
	s_waitcnt vmcnt(15)
	ds_write_b32 v22, v17
	s_waitcnt vmcnt(14)
	ds_write_b32 v24, v21
	s_waitcnt vmcnt(13)
	ds_write_b32 v26, v39
	s_waitcnt vmcnt(12)
	ds_write_b32 v28, v56
	s_waitcnt vmcnt(4)
	ds_write_b32 v30, v64
	ds_write_b32 v32, v57
	ds_write_b32 v34, v63
	ds_write_b32 v36, v58
	s_waitcnt vmcnt(0)
	ds_write_b32 v40, v67
	ds_write_b32 v42, v59
	ds_write_b32 v44, v66
	ds_write_b32 v46, v60
	ds_write_b32 v48, v65
	ds_write_b32 v50, v61
	ds_write_b32 v52, v0
	ds_write_b32 v54, v62
	s_cbranch_scc1 .LBB0_484
; __device__ __forceinline__ unsigned cvt_pk_bf16(float lo, float hi) { unsigned r; asm volatile("v_cvt_pk_bf16_f32 %0, %1, %2" : "=v"(r) : "v"(lo), "v"(hi)); return r; }
; #define LAS __attribute__((address_space(3)))
; #define LDS_WAIT() asm volatile("s_waitcnt lgkmcnt(0)" ::: "memory")
;     ...
;     const int c = lane & 7;
; #pragma unroll
;     for (int j = 0; j < 4; ++j) { const int n = (lane >> 3) + 8 * j; const LAS float* s = scr + (8 * c) * 33 + n;
;         u32x4 o; o.x = cvt_pk_bf16(s[0 * 33], s[1 * 33]); o.y = cvt_pk_bf16(s[2 * 33], s[3 * 33]); o.z = cvt_pk_bf16(s[4 * 33], s[5 * 33]); o.w = cvt_pk_bf16(s[6 * 33], s[7 * 33]);
;         *(u32x4*)(WT + (size_t)(dn0 + n) * ldo + koff + k0 + 8 * c) = o; }
;     LDS_WAIT(); asm volatile("" ::: "memory");
	s_lshl_b64 s[38:39], s[38:39], 1
	v_readlane_b32 s41, v251, 18
	s_waitcnt lgkmcnt(0)
	s_add_u32 s38, s41, s38
	v_readlane_b32 s41, v251, 19
	s_addc_u32 s39, s41, s39
	s_lshl_b32 s3, s3, 1
	ds_read2_b32 v[14:15], v9 offset1:33
	s_add_u32 s38, s38, s3
	s_waitcnt lgkmcnt(0)
	v_cvt_pk_bf16_f32 v14, v14, v15
	ds_read2_b32 v[16:17], v9 offset0:66 offset1:99
	v_lshlrev_b32_e32 v0, 1, v8
	v_or_b32_e32 v5, s2, v7
	s_addc_u32 s39, s39, 0
	s_waitcnt lgkmcnt(0)
	v_cvt_pk_bf16_f32 v15, v16, v17
	ds_read2_b32 v[16:17], v9 offset0:132 offset1:165
	v_lshl_add_u64 v[24:25], s[38:39], 0, v[0:1]
	v_lshlrev_b32_e32 v0, 12, v5
	s_waitcnt lgkmcnt(0)
	v_cvt_pk_bf16_f32 v16, v16, v17
	ds_read2_b32 v[22:23], v9 offset0:198 offset1:231
	s_waitcnt lgkmcnt(0)
	v_cvt_pk_bf16_f32 v17, v22, v23
	v_lshl_add_u64 v[26:27], v[24:25], 0, v[0:1]
	ds_read2_b32 v[22:23], v9 offset0:8 offset1:41
	global_store_dwordx4 v[26:27], v[14:17], off sc1
	v_or_b32_e32 v0, s2, v18
	v_lshlrev_b32_e32 v0, 12, v0
	s_waitcnt lgkmcnt(0)
	v_cvt_pk_bf16_f32 v14, v22, v23
	ds_read2_b32 v[16:17], v9 offset0:74 offset1:107
	s_waitcnt lgkmcnt(0)
	v_cvt_pk_bf16_f32 v15, v16, v17
	ds_read2_b32 v[16:17], v9 offset0:140 offset1:173
	s_waitcnt lgkmcnt(0)
	v_cvt_pk_bf16_f32 v16, v16, v17
	ds_read2_b32 v[22:23], v9 offset0:206 offset1:239
	s_waitcnt lgkmcnt(0)
	v_cvt_pk_bf16_f32 v17, v22, v23
	v_lshl_add_u64 v[26:27], v[24:25], 0, v[0:1]
	ds_read2_b32 v[22:23], v9 offset0:16 offset1:49
	global_store_dwordx4 v[26:27], v[14:17], off sc1
	v_or_b32_e32 v0, s2, v19
	v_lshlrev_b32_e32 v0, 12, v0
	s_waitcnt lgkmcnt(0)
	v_cvt_pk_bf16_f32 v14, v22, v23
	ds_read2_b32 v[16:17], v9 offset0:82 offset1:115
	s_waitcnt lgkmcnt(0)
	v_cvt_pk_bf16_f32 v15, v16, v17
	ds_read2_b32 v[16:17], v9 offset0:148 offset1:181
	s_waitcnt lgkmcnt(0)
	v_cvt_pk_bf16_f32 v16, v16, v17
	ds_read2_b32 v[22:23], v9 offset0:214 offset1:247
	s_waitcnt lgkmcnt(0)
	v_cvt_pk_bf16_f32 v17, v22, v23
	v_lshl_add_u64 v[26:27], v[24:25], 0, v[0:1]
	ds_read2_b32 v[22:23], v9 offset0:24 offset1:57
	global_store_dwordx4 v[26:27], v[14:17], off sc1
	v_or_b32_e32 v0, s2, v20
	v_lshlrev_b32_e32 v0, 12, v0
	s_waitcnt lgkmcnt(0)
	v_cvt_pk_bf16_f32 v14, v22, v23
	ds_read2_b32 v[16:17], v9 offset0:90 offset1:123
	s_waitcnt lgkmcnt(0)
	v_cvt_pk_bf16_f32 v15, v16, v17
	ds_read2_b32 v[16:17], v9 offset0:156 offset1:189
	s_waitcnt lgkmcnt(0)
	v_cvt_pk_bf16_f32 v16, v16, v17
	ds_read2_b32 v[22:23], v9 offset0:222 offset1:255
	s_waitcnt lgkmcnt(0)
	v_cvt_pk_bf16_f32 v17, v22, v23
	v_lshl_add_u64 v[22:23], v[24:25], 0, v[0:1]
	global_store_dwordx4 v[22:23], v[14:17], off sc1
	s_waitcnt lgkmcnt(0)
	v_readlane_b32 s70, v253, 44
	v_readlane_b32 s71, v253, 45
	s_mov_b32 s48, 0x3a000000

;     ...
;     const int nblk = N / 32, kb = item / nblk, nb = item % nblk, k0 = 64 * kb, n0 = 32 * nb;
;     const int dn0 = n0 + (n0 >= shift_from ? 128 : 0);
; #pragma unroll 8
;     for (int i = 0; i < 32; ++i) { const int kk = 2 * i + (lane >> 5); scr[kk * 33 + (lane & 31)] = W[(size_t)(k0 + kk) * N + n0 + (lane & 31)]; }
.LBB0_489:
	s_lshl_b32 s46, s43, 1
	s_lshl_b32 s45, s41, 1
	v_or_b32_e32 v0, s46, v16
	s_add_i32 s49, s46, 4
	s_add_i32 s48, s45, 4
	s_add_i32 s50, s45, 8
	s_add_i32 s51, s46, 8
	v_lshlrev_b64 v[40:41], 13, v[0:1]
	v_or_b32_e32 v0, s49, v16
	v_mov_b32_e32 v23, v1
	v_mov_b32_e32 v25, v1
	v_mov_b32_e32 v27, v1
	v_or_b32_e32 v22, s45, v5
	s_add_i32 s52, s45, 12
	s_add_i32 s53, s46, 12
	s_add_i32 s54, s45, 16
	s_add_i32 s56, s45, 20
	s_add_i32 s58, s45, 24
	s_add_i32 s60, s45, 28
	v_or_b32_e32 v24, s48, v5
	v_or_b32_e32 v26, s50, v5
	v_lshlrev_b64 v[42:43], 13, v[0:1]
	v_or_b32_e32 v0, s51, v16
	v_mov_b32_e32 v29, v1
	v_mov_b32_e32 v31, v1
	v_mov_b32_e32 v33, v1
	v_mov_b32_e32 v35, v1
	v_mov_b32_e32 v37, v1
	s_add_i32 s55, s46, 16
	v_lshlrev_b64 v[22:23], 13, v[22:23]
	v_or_b32_e32 v28, s52, v5
	v_or_b32_e32 v30, s54, v5
	v_or_b32_e32 v32, s56, v5
	v_or_b32_e32 v34, s58, v5
	v_or_b32_e32 v36, s60, v5
	v_lshl_add_u64 v[40:41], v[14:15], 0, v[40:41]
	v_lshlrev_b64 v[24:25], 13, v[24:25]
	v_lshlrev_b64 v[26:27], 13, v[26:27]
	v_lshlrev_b64 v[44:45], 13, v[0:1]
	v_or_b32_e32 v0, s53, v16
	s_add_i32 s57, s46, 20
	v_lshl_add_u64 v[22:23], v[14:15], 0, v[22:23]
	v_lshlrev_b64 v[28:29], 13, v[28:29]
	v_lshlrev_b64 v[30:31], 13, v[30:31]
	v_lshlrev_b64 v[32:33], 13, v[32:33]
	v_lshlrev_b64 v[34:35], 13, v[34:35]
	v_lshlrev_b64 v[36:37], 13, v[36:37]
	v_lshl_add_u64 v[42:43], v[14:15], 0, v[42:43]
	v_lshl_add_u64 v[24:25], v[14:15], 0, v[24:25]
	v_lshl_add_u64 v[26:27], v[14:15], 0, v[26:27]
	global_load_dword v17, v[40:41], off
	global_load_dword v21, v[22:23], off
	v_lshlrev_b64 v[40:41], 13, v[0:1]
	v_or_b32_e32 v0, s55, v16
	s_add_i32 s59, s46, 24
	v_lshl_add_u64 v[28:29], v[14:15], 0, v[28:29]
	v_lshl_add_u64 v[30:31], v[14:15], 0, v[30:31]
	v_lshl_add_u64 v[32:33], v[14:15], 0, v[32:33]
	v_lshl_add_u64 v[34:35], v[14:15], 0, v[34:35]
	v_lshl_add_u64 v[36:37], v[14:15], 0, v[36:37]
	global_load_dword v39, v[42:43], off
	global_load_dword v56, v[24:25], off
	global_load_dword v57, v[26:27], off
	global_load_dword v58, v[28:29], off
	global_load_dword v59, v[30:31], off
	global_load_dword v60, v[32:33], off
	global_load_dword v61, v[34:35], off
	global_load_dword v62, v[36:37], off
	v_lshl_add_u64 v[24:25], v[14:15], 0, v[40:41]
	v_lshlrev_b64 v[26:27], 13, v[0:1]
	v_or_b32_e32 v0, s57, v16
	s_add_i32 s61, s46, 28
	v_lshl_add_u64 v[22:23], v[14:15], 0, v[44:45]
	global_load_dword v63, v[24:25], off
	global_load_dword v64, v[22:23], off
	v_lshlrev_b64 v[24:25], 13, v[0:1]
	v_or_b32_e32 v0, s59, v16
	v_lshl_add_u64 v[22:23], v[14:15], 0, v[26:27]
	v_lshlrev_b64 v[26:27], 13, v[0:1]
	v_or_b32_e32 v0, s61, v16
	v_lshlrev_b64 v[28:29], 13, v[0:1]
	v_lshl_add_u64 v[28:29], v[14:15], 0, v[28:29]
	v_lshl_add_u64 v[24:25], v[14:15], 0, v[24:25]
	v_lshl_add_u64 v[26:27], v[14:15], 0, v[26:27]
	global_load_dword v0, v[28:29], off
	global_load_dword v65, v[26:27], off
	global_load_dword v66, v[24:25], off
	global_load_dword v67, v[22:23], off
	v_or_b32_e32 v24, s45, v3
	v_or_b32_e32 v22, s46, v2
	s_add_i32 s43, s43, 16
	s_add_i32 s41, s41, 16
	s_add_i32 s44, s44, -16
	v_mad_u64_u32 v[22:23], s[46:47], v22, s85, v[6:7]
	v_mad_u64_u32 v[24:25], s[46:47], v24, s85, v[6:7]
	v_or_b32_e32 v23, s48, v3
	v_or_b32_e32 v25, s49, v2
	v_or_b32_e32 v32, s50, v3
	v_or_b32_e32 v30, s51, v2
	v_or_b32_e32 v36, s52, v3
	v_or_b32_e32 v34, s53, v2
	v_or_b32_e32 v42, s54, v3
	v_or_b32_e32 v40, s55, v2
	v_or_b32_e32 v46, s56, v3
	v_or_b32_e32 v44, s57, v2
	v_or_b32_e32 v50, s58, v3
	v_or_b32_e32 v48, s59, v2
	v_or_b32_e32 v54, s60, v3
	v_or_b32_e32 v52, s61, v2
	s_cmp_lg_u32 s44, 0
	v_mad_u64_u32 v[26:27], s[46:47], v25, s85, v[6:7]
	v_mad_u64_u32 v[28:29], s[46:47], v23, s85, v[6:7]
	v_mad_u64_u32 v[30:31], s[46:47], v30, s85, v[6:7]
	v_mad_u64_u32 v[32:33], s[46:47], v32, s85, v[6:7]
	v_mad_u64_u32 v[34:35], s[46:47], v34, s85, v[6:7]
	v_mad_u64_u32 v[36:37], s[46:47], v36, s85, v[6:7]
	v_mad_u64_u32 v[40:41], s[46:47], v40, s85, v[6:7]
	v_mad_u64_u32 v[42:43], s[46:47], v42, s85, v[6:7]
	v_mad_u64_u32 v[44:45], s[46:47], v44, s85, v[6:7]
	v_mad_u64_u32 v[46:47], s[46:47], v46, s85, v[6:7]
	v_mad_u64_u32 v[48:49], s[46:47], v48, s85, v[6:7]
	v_mad_u64_u32 v[50:51], s[46:47], v50, s85, v[6:7]
	v_mad_u64_u32 v[52:53], s[46:47], v52, s85, v[6:7]
	v_mad_u64_u32 v[54:55], s[46:47], v54, s85, v[6:7]
	s_waitcnt vmcnt(15)
	ds_write_b32 v22, v17
	s_waitcnt vmcnt(14)
	ds_write_b32 v24, v21
	s_waitcnt vmcnt(13)
	ds_write_b32 v26, v39
	s_waitcnt vmcnt(12)
	ds_write_b32 v28, v56
	s_waitcnt vmcnt(4)
	ds_write_b32 v30, v64
	ds_write_b32 v32, v57
	ds_write_b32 v34, v63
	ds_write_b32 v36, v58
	s_waitcnt vmcnt(0)
	ds_write_b32 v40, v67
	ds_write_b32 v42, v59
	ds_write_b32 v44, v66
	ds_write_b32 v46, v60
	ds_write_b32 v48, v65
	ds_write_b32 v50, v61
	ds_write_b32 v52, v0
	ds_write_b32 v54, v62
	s_cbranch_scc1 .LBB0_489
; __device__ __forceinline__ unsigned cvt_pk_bf16(float lo, float hi) { unsigned r; asm volatile("v_cvt_pk_bf16_f32 %0, %1, %2" : "=v"(r) : "v"(lo), "v"(hi)); return r; }
; #define LAS __attribute__((address_space(3)))
; #define LDS_WAIT() asm volatile("s_waitcnt lgkmcnt(0)" ::: "memory")
;     ...
;     const int c = lane & 7;
; #pragma unroll
;     for (int j = 0; j < 4; ++j) { const int n = (lane >> 3) + 8 * j; const LAS float* s = scr + (8 * c) * 33 + n;
;         u32x4 o; o.x = cvt_pk_bf16(s[0 * 33], s[1 * 33]); o.y = cvt_pk_bf16(s[2 * 33], s[3 * 33]); o.z = cvt_pk_bf16(s[4 * 33], s[5 * 33]); o.w = cvt_pk_bf16(s[6 * 33], s[7 * 33]);
;         *(u32x4*)(WT + (size_t)(dn0 + n) * ldo + koff + k0 + 8 * c) = o; }
;     LDS_WAIT(); asm volatile("" ::: "memory");
	s_add_u32 s38, s28, s38
	s_waitcnt lgkmcnt(0)
	s_addc_u32 s39, s29, s39
	s_lshl_b32 s3, s3, 1
	s_add_u32 s38, s38, s3
	ds_read2_b32 v[14:15], v9 offset1:33
	v_lshlrev_b32_e32 v0, 1, v8
	s_addc_u32 s39, s39, 0
	s_waitcnt lgkmcnt(0)
	v_cvt_pk_bf16_f32 v14, v14, v15
	ds_read2_b32 v[16:17], v9 offset0:66 offset1:99
	v_or_b32_e32 v5, s2, v7
	v_lshl_add_u64 v[24:25], s[38:39], 0, v[0:1]
	s_mov_b64 s[38:39], 0xd400800
	s_waitcnt lgkmcnt(0)
	v_cvt_pk_bf16_f32 v15, v16, v17
	ds_read2_b32 v[16:17], v9 offset0:132 offset1:165
	v_lshlrev_b32_e32 v0, 12, v5
	v_lshl_add_u64 v[24:25], v[24:25], 0, s[38:39]
	s_waitcnt lgkmcnt(0)
	v_cvt_pk_bf16_f32 v16, v16, v17
	ds_read2_b32 v[22:23], v9 offset0:198 offset1:231
	s_waitcnt lgkmcnt(0)
	v_cvt_pk_bf16_f32 v17, v22, v23
	v_lshl_add_u64 v[26:27], v[24:25], 0, v[0:1]
	ds_read2_b32 v[22:23], v9 offset0:8 offset1:41
	global_store_dwordx4 v[26:27], v[14:17], off sc1
	v_or_b32_e32 v0, s2, v18
	v_lshlrev_b32_e32 v0, 12, v0
	s_waitcnt lgkmcnt(0)
	v_cvt_pk_bf16_f32 v14, v22, v23
	ds_read2_b32 v[16:17], v9 offset0:74 offset1:107
	s_waitcnt lgkmcnt(0)
	v_cvt_pk_bf16_f32 v15, v16, v17
	ds_read2_b32 v[16:17], v9 offset0:140 offset1:173
	s_waitcnt lgkmcnt(0)
	v_cvt_pk_bf16_f32 v16, v16, v17
	ds_read2_b32 v[22:23], v9 offset0:206 offset1:239
	s_waitcnt lgkmcnt(0)
	v_cvt_pk_bf16_f32 v17, v22, v23
	v_lshl_add_u64 v[26:27], v[24:25], 0, v[0:1]
	ds_read2_b32 v[22:23], v9 offset0:16 offset1:49
	global_store_dwordx4 v[26:27], v[14:17], off sc1
	v_or_b32_e32 v0, s2, v19
	v_lshlrev_b32_e32 v0, 12, v0
	s_waitcnt lgkmcnt(0)
	v_cvt_pk_bf16_f32 v14, v22, v23
	ds_read2_b32 v[16:17], v9 offset0:82 offset1:115
	s_waitcnt lgkmcnt(0)
	v_cvt_pk_bf16_f32 v15, v16, v17
	ds_read2_b32 v[16:17], v9 offset0:148 offset1:181
	s_waitcnt lgkmcnt(0)
	v_cvt_pk_bf16_f32 v16, v16, v17
	ds_read2_b32 v[22:23], v9 offset0:214 offset1:247
	s_waitcnt lgkmcnt(0)
	v_cvt_pk_bf16_f32 v17, v22, v23
	v_lshl_add_u64 v[26:27], v[24:25], 0, v[0:1]
	ds_read2_b32 v[22:23], v9 offset0:24 offset1:57
	global_store_dwordx4 v[26:27], v[14:17], off sc1
	v_or_b32_e32 v0, s2, v20
	v_lshlrev_b32_e32 v0, 12, v0
	s_waitcnt lgkmcnt(0)
	v_cvt_pk_bf16_f32 v14, v22, v23
	ds_read2_b32 v[16:17], v9 offset0:90 offset1:123
	s_waitcnt lgkmcnt(0)
	v_cvt_pk_bf16_f32 v15, v16, v17
	ds_read2_b32 v[16:17], v9 offset0:156 offset1:189
	s_waitcnt lgkmcnt(0)
	v_cvt_pk_bf16_f32 v16, v16, v17
	ds_read2_b32 v[22:23], v9 offset0:222 offset1:255
	s_waitcnt lgkmcnt(0)
	v_cvt_pk_bf16_f32 v17, v22, v23
	v_lshl_add_u64 v[22:23], v[24:25], 0, v[0:1]
	global_store_dwordx4 v[22:23], v[14:17], off sc1
	s_waitcnt lgkmcnt(0)
	v_readlane_b32 s70, v253, 44
	v_readlane_b32 s71, v253, 45
	s_mov_b32 s48, 0x3a000000

;     ...
;     const int nblk = N / 32, kb = item / nblk, nb = item % nblk, k0 = 64 * kb, n0 = 32 * nb;
;     const int dn0 = n0 + (n0 >= shift_from ? 128 : 0);
; #pragma unroll 8
;     for (int i = 0; i < 32; ++i) { const int kk = 2 * i + (lane >> 5); scr[kk * 33 + (lane & 31)] = W[(size_t)(k0 + kk) * N + n0 + (lane & 31)]; }
.LBB0_494:
	s_lshl_b32 s45, s41, 1
	s_lshl_b32 s44, s3, 1
	v_or_b32_e32 v0, s45, v16
	s_add_i32 s47, s45, 4
	s_add_i32 s46, s44, 4
	s_add_i32 s48, s44, 8
	s_add_i32 s49, s45, 8
	v_lshlrev_b64 v[40:41], 13, v[0:1]
	v_or_b32_e32 v0, s47, v16
	v_mov_b32_e32 v23, v1
	v_mov_b32_e32 v25, v1
	v_mov_b32_e32 v27, v1
	v_or_b32_e32 v22, s44, v5
	s_add_i32 s50, s44, 12
	s_add_i32 s51, s45, 12
	s_add_i32 s52, s44, 16
	s_add_i32 s54, s44, 20
	s_add_i32 s56, s44, 24
	s_add_i32 s58, s44, 28
	v_or_b32_e32 v24, s46, v5
	v_or_b32_e32 v26, s48, v5
	v_lshlrev_b64 v[42:43], 13, v[0:1]
	v_or_b32_e32 v0, s49, v16
	v_mov_b32_e32 v29, v1
	v_mov_b32_e32 v31, v1
	v_mov_b32_e32 v33, v1
	v_mov_b32_e32 v35, v1
	v_mov_b32_e32 v37, v1
	s_add_i32 s53, s45, 16
	v_lshlrev_b64 v[22:23], 13, v[22:23]
	v_or_b32_e32 v28, s50, v5
	v_or_b32_e32 v30, s52, v5
	v_or_b32_e32 v32, s54, v5
	v_or_b32_e32 v34, s56, v5
	v_or_b32_e32 v36, s58, v5
	v_lshl_add_u64 v[40:41], v[14:15], 0, v[40:41]
	v_lshlrev_b64 v[24:25], 13, v[24:25]
	v_lshlrev_b64 v[26:27], 13, v[26:27]
	v_lshlrev_b64 v[44:45], 13, v[0:1]
	v_or_b32_e32 v0, s51, v16
	s_add_i32 s55, s45, 20
	v_lshl_add_u64 v[22:23], v[14:15], 0, v[22:23]
	v_lshlrev_b64 v[28:29], 13, v[28:29]
	v_lshlrev_b64 v[30:31], 13, v[30:31]
	v_lshlrev_b64 v[32:33], 13, v[32:33]
	v_lshlrev_b64 v[34:35], 13, v[34:35]
	v_lshlrev_b64 v[36:37], 13, v[36:37]
	v_lshl_add_u64 v[42:43], v[14:15], 0, v[42:43]
	v_lshl_add_u64 v[24:25], v[14:15], 0, v[24:25]
	v_lshl_add_u64 v[26:27], v[14:15], 0, v[26:27]
	global_load_dword v17, v[40:41], off
	global_load_dword v21, v[22:23], off
	v_lshlrev_b64 v[40:41], 13, v[0:1]
	v_or_b32_e32 v0, s53, v16
	s_add_i32 s57, s45, 24
	v_lshl_add_u64 v[28:29], v[14:15], 0, v[28:29]
	v_lshl_add_u64 v[30:31], v[14:15], 0, v[30:31]
	v_lshl_add_u64 v[32:33], v[14:15], 0, v[32:33]
	v_lshl_add_u64 v[34:35], v[14:15], 0, v[34:35]
	v_lshl_add_u64 v[36:37], v[14:15], 0, v[36:37]
	global_load_dword v39, v[42:43], off
	global_load_dword v56, v[24:25], off
	global_load_dword v57, v[26:27], off
	global_load_dword v58, v[28:29], off
	global_load_dword v59, v[30:31], off
	global_load_dword v60, v[32:33], off
	global_load_dword v61, v[34:35], off
	global_load_dword v62, v[36:37], off
	v_lshl_add_u64 v[24:25], v[14:15], 0, v[40:41]
	v_lshlrev_b64 v[26:27], 13, v[0:1]
	v_or_b32_e32 v0, s55, v16
	s_add_i32 s59, s45, 28
	v_lshl_add_u64 v[22:23], v[14:15], 0, v[44:45]
	global_load_dword v63, v[24:25], off
	global_load_dword v64, v[22:23], off
	v_lshlrev_b64 v[24:25], 13, v[0:1]
	v_or_b32_e32 v0, s57, v16
	v_lshl_add_u64 v[22:23], v[14:15], 0, v[26:27]
	v_lshlrev_b64 v[26:27], 13, v[0:1]
	v_or_b32_e32 v0, s59, v16
	v_lshlrev_b64 v[28:29], 13, v[0:1]
	v_lshl_add_u64 v[28:29], v[14:15], 0, v[28:29]
	v_lshl_add_u64 v[24:25], v[14:15], 0, v[24:25]
	v_lshl_add_u64 v[26:27], v[14:15], 0, v[26:27]
	global_load_dword v0, v[28:29], off
	global_load_dword v65, v[26:27], off
	global_load_dword v66, v[24:25], off
	global_load_dword v67, v[22:23], off
	v_or_b32_e32 v24, s44, v3
	v_or_b32_e32 v22, s45, v2
	s_add_i32 s41, s41, 16
	s_add_i32 s3, s3, 16
	s_add_i32 s43, s43, -16
	v_mad_u64_u32 v[22:23], s[44:45], v22, s85, v[6:7]
	v_mad_u64_u32 v[24:25], s[44:45], v24, s85, v[6:7]
	v_or_b32_e32 v23, s46, v3
	v_or_b32_e32 v25, s47, v2
	v_or_b32_e32 v32, s48, v3
	v_or_b32_e32 v30, s49, v2
	v_or_b32_e32 v36, s50, v3
	v_or_b32_e32 v34, s51, v2
	v_or_b32_e32 v42, s52, v3
	v_or_b32_e32 v40, s53, v2
	v_or_b32_e32 v46, s54, v3
	v_or_b32_e32 v44, s55, v2
	v_or_b32_e32 v50, s56, v3
	v_or_b32_e32 v48, s57, v2
	v_or_b32_e32 v54, s58, v3
	v_or_b32_e32 v52, s59, v2
	s_cmp_lg_u32 s43, 0
	v_mad_u64_u32 v[26:27], s[44:45], v25, s85, v[6:7]
	v_mad_u64_u32 v[28:29], s[44:45], v23, s85, v[6:7]
	v_mad_u64_u32 v[30:31], s[44:45], v30, s85, v[6:7]
	v_mad_u64_u32 v[32:33], s[44:45], v32, s85, v[6:7]
	v_mad_u64_u32 v[34:35], s[44:45], v34, s85, v[6:7]
	v_mad_u64_u32 v[36:37], s[44:45], v36, s85, v[6:7]
	v_mad_u64_u32 v[40:41], s[44:45], v40, s85, v[6:7]
	v_mad_u64_u32 v[42:43], s[44:45], v42, s85, v[6:7]
	v_mad_u64_u32 v[44:45], s[44:45], v44, s85, v[6:7]
	v_mad_u64_u32 v[46:47], s[44:45], v46, s85, v[6:7]
	v_mad_u64_u32 v[48:49], s[44:45], v48, s85, v[6:7]
	v_mad_u64_u32 v[50:51], s[44:45], v50, s85, v[6:7]
	v_mad_u64_u32 v[52:53], s[44:45], v52, s85, v[6:7]
	v_mad_u64_u32 v[54:55], s[44:45], v54, s85, v[6:7]
	s_waitcnt vmcnt(15)
	ds_write_b32 v22, v17
	s_waitcnt vmcnt(14)
	ds_write_b32 v24, v21
	s_waitcnt vmcnt(13)
	ds_write_b32 v26, v39
	s_waitcnt vmcnt(12)
	ds_write_b32 v28, v56
	s_waitcnt vmcnt(4)
	ds_write_b32 v30, v64
	ds_write_b32 v32, v57
	ds_write_b32 v34, v63
	ds_write_b32 v36, v58
	s_waitcnt vmcnt(0)
	ds_write_b32 v40, v67
	ds_write_b32 v42, v59
	ds_write_b32 v44, v66
	ds_write_b32 v46, v60
	ds_write_b32 v48, v65
	ds_write_b32 v50, v61
	ds_write_b32 v52, v0
	ds_write_b32 v54, v62
	s_cbranch_scc1 .LBB0_494
; __device__ __forceinline__ unsigned cvt_pk_bf16(float lo, float hi) { unsigned r; asm volatile("v_cvt_pk_bf16_f32 %0, %1, %2" : "=v"(r) : "v"(lo), "v"(hi)); return r; }
; #define LAS __attribute__((address_space(3)))
; #define LDS_WAIT() asm volatile("s_waitcnt lgkmcnt(0)" ::: "memory")
;     ...
;     const int c = lane & 7;
; #pragma unroll
;     for (int j = 0; j < 4; ++j) { const int n = (lane >> 3) + 8 * j; const LAS float* s = scr + (8 * c) * 33 + n;
;         u32x4 o; o.x = cvt_pk_bf16(s[0 * 33], s[1 * 33]); o.y = cvt_pk_bf16(s[2 * 33], s[3 * 33]); o.z = cvt_pk_bf16(s[4 * 33], s[5 * 33]); o.w = cvt_pk_bf16(s[6 * 33], s[7 * 33]);
;         *(u32x4*)(WT + (size_t)(dn0 + n) * ldo + koff + k0 + 8 * c) = o; }
;     LDS_WAIT(); asm volatile("" ::: "memory");
	v_readlane_b32 s3, v251, 20
	s_waitcnt lgkmcnt(0)
	s_add_u32 s3, s3, s38
	v_readlane_b32 s38, v251, 21
	s_addc_u32 s38, s38, s39
	s_lshl_b32 s2, s2, 1
	ds_read2_b32 v[14:15], v9 offset1:33
	s_add_u32 s2, s3, s2
	s_waitcnt lgkmcnt(0)
	v_cvt_pk_bf16_f32 v14, v14, v15
	ds_read2_b32 v[16:17], v9 offset0:66 offset1:99
	v_lshlrev_b32_e32 v0, 1, v8
	v_or_b32_e32 v5, s1, v7
	s_addc_u32 s3, s38, 0
	s_waitcnt lgkmcnt(0)
	v_cvt_pk_bf16_f32 v15, v16, v17
	ds_read2_b32 v[16:17], v9 offset0:132 offset1:165
	v_lshl_add_u64 v[24:25], s[2:3], 0, v[0:1]
	v_lshlrev_b32_e32 v0, 12, v5
	s_waitcnt lgkmcnt(0)
	v_cvt_pk_bf16_f32 v16, v16, v17
	ds_read2_b32 v[22:23], v9 offset0:198 offset1:231
	s_waitcnt lgkmcnt(0)
	v_cvt_pk_bf16_f32 v17, v22, v23
	v_lshl_add_u64 v[26:27], v[24:25], 0, v[0:1]
	ds_read2_b32 v[22:23], v9 offset0:8 offset1:41
	global_store_dwordx4 v[26:27], v[14:17], off sc1
	v_or_b32_e32 v0, s1, v18
	v_lshlrev_b32_e32 v0, 12, v0
	s_waitcnt lgkmcnt(0)
	v_cvt_pk_bf16_f32 v14, v22, v23
	ds_read2_b32 v[16:17], v9 offset0:74 offset1:107
	s_waitcnt lgkmcnt(0)
	v_cvt_pk_bf16_f32 v15, v16, v17
	ds_read2_b32 v[16:17], v9 offset0:140 offset1:173
	s_waitcnt lgkmcnt(0)
	v_cvt_pk_bf16_f32 v16, v16, v17
	ds_read2_b32 v[22:23], v9 offset0:206 offset1:239
	s_waitcnt lgkmcnt(0)
	v_cvt_pk_bf16_f32 v17, v22, v23
	v_lshl_add_u64 v[26:27], v[24:25], 0, v[0:1]
	ds_read2_b32 v[22:23], v9 offset0:16 offset1:49
	global_store_dwordx4 v[26:27], v[14:17], off sc1
	v_or_b32_e32 v0, s1, v19
	v_lshlrev_b32_e32 v0, 12, v0
	s_waitcnt lgkmcnt(0)
	v_cvt_pk_bf16_f32 v14, v22, v23
	ds_read2_b32 v[16:17], v9 offset0:82 offset1:115
	s_waitcnt lgkmcnt(0)
	v_cvt_pk_bf16_f32 v15, v16, v17
	ds_read2_b32 v[16:17], v9 offset0:148 offset1:181
	s_waitcnt lgkmcnt(0)
	v_cvt_pk_bf16_f32 v16, v16, v17
	ds_read2_b32 v[22:23], v9 offset0:214 offset1:247
	s_waitcnt lgkmcnt(0)
	v_cvt_pk_bf16_f32 v17, v22, v23
	v_lshl_add_u64 v[26:27], v[24:25], 0, v[0:1]
	ds_read2_b32 v[22:23], v9 offset0:24 offset1:57
	global_store_dwordx4 v[26:27], v[14:17], off sc1
	v_or_b32_e32 v0, s1, v20
	v_lshlrev_b32_e32 v0, 12, v0
	s_waitcnt lgkmcnt(0)
	v_cvt_pk_bf16_f32 v14, v22, v23
	ds_read2_b32 v[16:17], v9 offset0:90 offset1:123
	s_waitcnt lgkmcnt(0)
	v_cvt_pk_bf16_f32 v15, v16, v17
	ds_read2_b32 v[16:17], v9 offset0:156 offset1:189
	s_waitcnt lgkmcnt(0)
	v_cvt_pk_bf16_f32 v16, v16, v17
	ds_read2_b32 v[22:23], v9 offset0:222 offset1:255
	s_waitcnt lgkmcnt(0)
	v_cvt_pk_bf16_f32 v17, v22, v23
	v_lshl_add_u64 v[22:23], v[24:25], 0, v[0:1]
	global_store_dwordx4 v[22:23], v[14:17], off sc1
	s_waitcnt lgkmcnt(0)
	s_mov_b32 s48, 0x3a000000

;     ...
;     const int nblk = N / 32, kb = item / nblk, nb = item % nblk, k0 = 64 * kb, n0 = 32 * nb;
;     const int dn0 = n0 + (n0 >= shift_from ? 128 : 0);
; #pragma unroll 8
;     for (int i = 0; i < 32; ++i) { const int kk = 2 * i + (lane >> 5); scr[kk * 33 + (lane & 31)] = W[(size_t)(k0 + kk) * N + n0 + (lane & 31)]; }
.LBB0_498:
	s_lshl_b32 s41, s2, 1
	s_lshl_b32 s43, s3, 1
	v_or_b32_e32 v21, s41, v5
	v_or_b32_e32 v16, s43, v0
	s_add_i32 s46, s41, 4
	s_add_i32 s47, s43, 4
	s_add_i32 s48, s41, 8
	s_add_i32 s49, s43, 8
	s_add_i32 s50, s41, 12
	s_add_i32 s51, s43, 12
	s_add_i32 s52, s41, 16
	s_add_i32 s53, s43, 16
	s_add_i32 s54, s41, 20
	s_add_i32 s55, s43, 20
	s_add_i32 s56, s41, 24
	s_add_i32 s57, s43, 24
	s_add_i32 s58, s41, 28
	s_add_i32 s59, s43, 28
	v_mad_i64_i32 v[16:17], s[44:45], v16, s6, v[14:15]
	v_mad_i64_i32 v[22:23], s[44:45], v21, s6, v[14:15]
	v_or_b32_e32 v21, s46, v5
	v_or_b32_e32 v24, s47, v0
	v_or_b32_e32 v30, s48, v5
	v_or_b32_e32 v28, s49, v0
	v_or_b32_e32 v34, s50, v5
	v_or_b32_e32 v32, s51, v0
	v_or_b32_e32 v39, s52, v5
	v_or_b32_e32 v36, s53, v0
	v_or_b32_e32 v44, s54, v5
	v_or_b32_e32 v42, s55, v0
	v_or_b32_e32 v48, s56, v5
	v_or_b32_e32 v46, s57, v0
	v_or_b32_e32 v52, s58, v5
	v_or_b32_e32 v50, s59, v0
	v_mad_i64_i32 v[24:25], s[44:45], v24, s6, v[14:15]
	v_mad_i64_i32 v[26:27], s[44:45], v21, s6, v[14:15]
	v_mad_i64_i32 v[28:29], s[44:45], v28, s6, v[14:15]
	v_mad_i64_i32 v[30:31], s[44:45], v30, s6, v[14:15]
	v_mad_i64_i32 v[32:33], s[44:45], v32, s6, v[14:15]
	v_mad_i64_i32 v[34:35], s[44:45], v34, s6, v[14:15]
	v_mad_i64_i32 v[36:37], s[44:45], v36, s6, v[14:15]
	v_mad_i64_i32 v[40:41], s[44:45], v39, s6, v[14:15]
	v_mad_i64_i32 v[42:43], s[44:45], v42, s6, v[14:15]
	v_mad_i64_i32 v[44:45], s[44:45], v44, s6, v[14:15]
	v_mad_i64_i32 v[46:47], s[44:45], v46, s6, v[14:15]
	v_mad_i64_i32 v[48:49], s[44:45], v48, s6, v[14:15]
	v_mad_i64_i32 v[50:51], s[44:45], v50, s6, v[14:15]
	v_mad_i64_i32 v[52:53], s[44:45], v52, s6, v[14:15]
	global_load_dword v21, v[16:17], off
	global_load_dword v39, v[22:23], off
	global_load_dword v54, v[24:25], off
	global_load_dword v55, v[26:27], off
	global_load_dword v56, v[28:29], off
	global_load_dword v57, v[30:31], off
	global_load_dword v58, v[32:33], off
	global_load_dword v59, v[34:35], off
	global_load_dword v60, v[36:37], off
	global_load_dword v61, v[40:41], off
	global_load_dword v62, v[42:43], off
	global_load_dword v63, v[44:45], off
	global_load_dword v64, v[46:47], off
	global_load_dword v65, v[48:49], off
	global_load_dword v66, v[50:51], off
	global_load_dword v67, v[52:53], off
	v_or_b32_e32 v22, s41, v3
	v_or_b32_e32 v16, s43, v2
	s_add_i32 s3, s3, 16
	s_add_i32 s2, s2, 16
	s_add_i32 s39, s39, -16
	v_mad_u64_u32 v[16:17], s[44:45], v16, s85, v[6:7]
	v_mad_u64_u32 v[22:23], s[44:45], v22, s85, v[6:7]
	v_or_b32_e32 v17, s46, v3
	v_or_b32_e32 v23, s47, v2
	v_or_b32_e32 v30, s48, v3
	v_or_b32_e32 v28, s49, v2
	v_or_b32_e32 v34, s50, v3
	v_or_b32_e32 v32, s51, v2
	v_or_b32_e32 v40, s52, v3
	v_or_b32_e32 v36, s53, v2
	v_or_b32_e32 v44, s54, v3
	v_or_b32_e32 v42, s55, v2
	v_or_b32_e32 v48, s56, v3
	v_or_b32_e32 v46, s57, v2
	v_or_b32_e32 v52, s58, v3
	v_or_b32_e32 v50, s59, v2
	s_cmp_lg_u32 s39, 0
	v_mad_u64_u32 v[24:25], s[44:45], v23, s85, v[6:7]
	v_mad_u64_u32 v[26:27], s[44:45], v17, s85, v[6:7]
	v_mad_u64_u32 v[28:29], s[44:45], v28, s85, v[6:7]
	v_mad_u64_u32 v[30:31], s[44:45], v30, s85, v[6:7]
	v_mad_u64_u32 v[32:33], s[44:45], v32, s85, v[6:7]
	v_mad_u64_u32 v[34:35], s[44:45], v34, s85, v[6:7]
	v_mad_u64_u32 v[36:37], s[44:45], v36, s85, v[6:7]
	v_mad_u64_u32 v[40:41], s[44:45], v40, s85, v[6:7]
	v_mad_u64_u32 v[42:43], s[44:45], v42, s85, v[6:7]
	v_mad_u64_u32 v[44:45], s[44:45], v44, s85, v[6:7]
	v_mad_u64_u32 v[46:47], s[44:45], v46, s85, v[6:7]
	v_mad_u64_u32 v[48:49], s[44:45], v48, s85, v[6:7]
	v_mad_u64_u32 v[50:51], s[44:45], v50, s85, v[6:7]
	v_mad_u64_u32 v[52:53], s[44:45], v52, s85, v[6:7]
	s_waitcnt vmcnt(15)
	ds_write_b32 v16, v21
	s_waitcnt vmcnt(14)
	ds_write_b32 v22, v39
	s_waitcnt vmcnt(13)
	ds_write_b32 v24, v54
	s_waitcnt vmcnt(12)
	ds_write_b32 v26, v55
	s_waitcnt vmcnt(11)
	ds_write_b32 v28, v56
	s_waitcnt vmcnt(10)
	ds_write_b32 v30, v57
	s_waitcnt vmcnt(9)
	ds_write_b32 v32, v58
	s_waitcnt vmcnt(8)
	ds_write_b32 v34, v59
	s_waitcnt vmcnt(7)
	ds_write_b32 v36, v60
	s_waitcnt vmcnt(6)
	ds_write_b32 v40, v61
	s_waitcnt vmcnt(5)
	ds_write_b32 v42, v62
	s_waitcnt vmcnt(4)
	ds_write_b32 v44, v63
	s_waitcnt vmcnt(3)
	ds_write_b32 v46, v64
	s_waitcnt vmcnt(2)
	ds_write_b32 v48, v65
	s_waitcnt vmcnt(1)
	ds_write_b32 v50, v66
	s_waitcnt vmcnt(0)
	ds_write_b32 v52, v67
	s_cbranch_scc1 .LBB0_498
; __device__ __forceinline__ unsigned cvt_pk_bf16(float lo, float hi) { unsigned r; asm volatile("v_cvt_pk_bf16_f32 %0, %1, %2" : "=v"(r) : "v"(lo), "v"(hi)); return r; }
; #define LAS __attribute__((address_space(3)))
; #define LDS_WAIT() asm volatile("s_waitcnt lgkmcnt(0)" ::: "memory")
;     ...
;     const int dn0 = n0 + (n0 >= shift_from ? 128 : 0);
; #pragma unroll 8
;     for (int i = 0; i < 32; ++i) { const int kk = 2 * i + (lane >> 5); scr[kk * 33 + (lane & 31)] = W[(size_t)(k0 + kk) * N + n0 + (lane & 31)]; }
;     LDS_WAIT(); asm volatile("" ::: "memory");
;     const int c = lane & 7;
; #pragma unroll
;     for (int j = 0; j < 4; ++j) { const int n = (lane >> 3) + 8 * j; const LAS float* s = scr + (8 * c) * 33 + n;
;         u32x4 o; o.x = cvt_pk_bf16(s[0 * 33], s[1 * 33]); o.y = cvt_pk_bf16(s[2 * 33], s[3 * 33]); o.z = cvt_pk_bf16(s[4 * 33], s[5 * 33]); o.w = cvt_pk_bf16(s[6 * 33], s[7 * 33]);
;         *(u32x4*)(WT + (size_t)(dn0 + n) * ldo + koff + k0 + 8 * c) = o; }
;     LDS_WAIT(); asm volatile("" ::: "memory");
	s_waitcnt lgkmcnt(0)
	s_mul_hi_i32 s2, s0, 0x3100000
	s_mul_i32 s0, s0, 0x3100000
	s_add_u32 s3, s91, s0
	ds_read2_b32 v[14:15], v9 offset1:33
	s_addc_u32 s2, s93, s2
	s_waitcnt lgkmcnt(0)
	v_cvt_pk_bf16_f32 v14, v14, v15
	ds_read2_b32 v[16:17], v9 offset0:66 offset1:99
	s_cmpk_lt_i32 s1, 0x64
	s_waitcnt lgkmcnt(0)
	v_cvt_pk_bf16_f32 v15, v16, v17
	ds_read2_b32 v[16:17], v9 offset0:132 offset1:165
	s_cselect_b32 s0, 0, 0x80
	s_ashr_i32 s39, s38, 31
	s_add_i32 s40, s0, s40
	s_waitcnt lgkmcnt(0)
	v_cvt_pk_bf16_f32 v16, v16, v17
	ds_read2_b32 v[22:23], v9 offset0:198 offset1:231
	s_lshl_b64 s[0:1], s[38:39], 1
	s_add_u32 s0, s3, s0
	s_waitcnt lgkmcnt(0)
	v_cvt_pk_bf16_f32 v17, v22, v23
	v_or_b32_e32 v22, s40, v7
	v_lshlrev_b32_e32 v0, 1, v8
	s_addc_u32 s1, s2, s1
	v_ashrrev_i32_e32 v23, 31, v22
	v_lshl_add_u64 v[24:25], s[0:1], 0, v[0:1]
	v_lshlrev_b64 v[22:23], 12, v[22:23]
	ds_read2_b32 v[26:27], v9 offset0:8 offset1:41
	v_lshl_add_u64 v[22:23], v[24:25], 0, v[22:23]
	global_store_dwordx4 v[22:23], v[14:17], off sc1
	s_mov_b32 s48, 0x3a000000
	s_waitcnt lgkmcnt(0)
	v_cvt_pk_bf16_f32 v14, v26, v27
	v_or_b32_e32 v26, s40, v18
	v_ashrrev_i32_e32 v27, 31, v26
	ds_read2_b32 v[16:17], v9 offset0:74 offset1:107
	v_lshlrev_b64 v[26:27], 12, v[26:27]
	s_waitcnt lgkmcnt(0)
	v_cvt_pk_bf16_f32 v15, v16, v17
	ds_read2_b32 v[16:17], v9 offset0:140 offset1:173
	v_lshl_add_u64 v[26:27], v[24:25], 0, v[26:27]
	s_waitcnt lgkmcnt(0)
	v_cvt_pk_bf16_f32 v16, v16, v17
	ds_read2_b32 v[22:23], v9 offset0:206 offset1:239
	s_waitcnt lgkmcnt(0)
	v_cvt_pk_bf16_f32 v17, v22, v23
	global_store_dwordx4 v[26:27], v[14:17], off sc1
	v_or_b32_e32 v26, s40, v19
	ds_read2_b32 v[22:23], v9 offset0:16 offset1:49
	s_waitcnt lgkmcnt(0)
	v_cvt_pk_bf16_f32 v14, v22, v23
	ds_read2_b32 v[16:17], v9 offset0:82 offset1:115
	v_ashrrev_i32_e32 v27, 31, v26
	s_waitcnt lgkmcnt(0)
	v_cvt_pk_bf16_f32 v15, v16, v17
	ds_read2_b32 v[16:17], v9 offset0:148 offset1:181
	v_lshlrev_b64 v[26:27], 12, v[26:27]
	s_waitcnt lgkmcnt(0)
	v_cvt_pk_bf16_f32 v16, v16, v17
	ds_read2_b32 v[22:23], v9 offset0:214 offset1:247
	s_waitcnt lgkmcnt(0)
	v_cvt_pk_bf16_f32 v17, v22, v23
	v_lshl_add_u64 v[26:27], v[24:25], 0, v[26:27]
	ds_read2_b32 v[22:23], v9 offset0:24 offset1:57
	global_store_dwordx4 v[26:27], v[14:17], off sc1
	v_or_b32_e32 v26, s40, v20
	v_ashrrev_i32_e32 v27, 31, v26
	s_waitcnt lgkmcnt(0)
	v_cvt_pk_bf16_f32 v14, v22, v23
	ds_read2_b32 v[16:17], v9 offset0:90 offset1:123
	s_waitcnt lgkmcnt(0)
	v_cvt_pk_bf16_f32 v15, v16, v17
	ds_read2_b32 v[16:17], v9 offset0:156 offset1:189
	s_waitcnt lgkmcnt(0)
	v_cvt_pk_bf16_f32 v16, v16, v17
	ds_read2_b32 v[22:23], v9 offset0:222 offset1:255
	v_lshlrev_b64 v[26:27], 12, v[26:27]
	s_waitcnt lgkmcnt(0)
	v_cvt_pk_bf16_f32 v17, v22, v23
	v_lshl_add_u64 v[22:23], v[24:25], 0, v[26:27]
	global_store_dwordx4 v[22:23], v[14:17], off sc1
	s_waitcnt lgkmcnt(0)
	s_branch .LBB0_467

; __device__ __forceinline__ void phase_convert(const Args& a, LAS unsigned char* lds) {
;     ...
;     for (int i = blockIdx.x * NTHR + tid; i < LDP * 2 / 16; i += gridDim.x * NTHR) ((u32x4*)(ws + WS_ZROW))[i] = (u32x4){0u, 0u, 0u, 0u};
.LBB0_502:
	v_ashrrev_i32_e32 v3, 31, v2
	s_waitcnt lgkmcnt(0)
	v_lshl_add_u64 v[6:7], v[2:3], 4, s[70:71]
	v_add_u32_e32 v2, s88, v2
	s_movk_i32 s38, 0x61f
	v_cmp_lt_i32_e32 vcc, s38, v2
	s_or_b64 s[2:3], vcc, s[2:3]
	global_store_dwordx4 v[6:7], v[210:213], off sc1
	s_andn2_b64 exec, exec, s[2:3]
	s_cbranch_execnz .LBB0_502

; __device__ __forceinline__ void phase_convert(const Args& a, LAS unsigned char* lds) {
;     ...
;     for (int i = blockIdx.x * NTHR + tid; i < DEPTH * 32768; i += gridDim.x * NTHR) {
;         const int l = i >> 15, r = i & 32767;
;         ((u32x4*)(ws + WS_WIN + l * SZ_WIN + (size_t)3200 * D * 2))[r] = (u32x4){0u, 0u, 0u, 0u};
;     }
.LBB0_505:
	v_ashrrev_i32_e32 v0, 15, v4
	v_and_b32_e32 v5, 0x7fff, v4
	v_mov_b64_e32 v[2:3], s[28:29]
	s_mov_b32 s2, 0x3100000
	v_add_u32_e32 v4, s88, v4
	v_mad_i64_i32 v[2:3], s[2:3], v0, s2, v[2:3]
	v_lshlrev_b32_e32 v0, 4, v5
	v_cmp_lt_i32_e32 vcc, s76, v4
	v_lshl_add_u64 v[2:3], v[2:3], 0, v[0:1]
	s_or_b64 s[38:39], vcc, s[38:39]
	v_add_co_u32_e32 v2, vcc, 0x1c80000, v2
	s_nop 1
	v_addc_co_u32_e32 v3, vcc, 0, v3, vcc
	global_store_dwordx4 v[2:3], v[210:213], off sc1
	s_andn2_b64 exec, exec, s[38:39]
	s_cbranch_execnz .LBB0_505
